# v19 + non-temporal hint on the once-read f32 weight and ada_w loads of the prologue phase
# speedup vs baseline: 1.0035x; 1.0035x over previous
.LBB0_16:
	v_add_co_u32_e32 v20, vcc, 0x18000, v8
	global_load_dwordx2 v[18:19], v[8:9], off nt
	s_nop 0
	v_addc_co_u32_e32 v21, vcc, 0, v9, vcc
	v_add_co_u32_e32 v88, vcc, 0x30000, v8
	v_mov_b32_e32 v7, s17
	s_nop 0
	v_addc_co_u32_e32 v89, vcc, 0, v9, vcc
	v_add_co_u32_e32 v90, vcc, 0x48000, v8
	ds_read_b128 v[24:27], v7
	ds_read_b128 v[28:31], v7 offset:16
	ds_read_b128 v[32:35], v7 offset:16384
	ds_read_b128 v[36:39], v7 offset:16400
	ds_read_b128 v[40:43], v7 offset:32768
	ds_read_b128 v[44:47], v7 offset:32784
	ds_read_b128 v[48:51], v7 offset:49152
	ds_read_b128 v[52:55], v7 offset:49168
	ds_read_b128 v[56:59], v7 offset:32
	ds_read_b128 v[60:63], v7 offset:48
	ds_read_b128 v[64:67], v7 offset:16416
	ds_read_b128 v[68:71], v7 offset:16432
	ds_read_b128 v[72:75], v7 offset:32800
	ds_read_b128 v[76:79], v7 offset:32816
	ds_read_b128 v[80:83], v7 offset:49184
	ds_read_b128 v[84:87], v7 offset:49200
	v_addc_co_u32_e32 v91, vcc, 0, v9, vcc
	v_add_co_u32_e32 v92, vcc, 0x60000, v8
	global_load_dwordx2 v[20:21], v[20:21], off nt
	s_nop 0
	global_load_dwordx2 v[88:89], v[88:89], off nt
	v_addc_co_u32_e32 v93, vcc, 0, v9, vcc
	v_add_co_u32_e32 v94, vcc, 0x78000, v8
	global_load_dwordx2 v[90:91], v[90:91], off nt
	s_nop 0
	global_load_dwordx2 v[92:93], v[92:93], off nt
	v_addc_co_u32_e32 v95, vcc, 0, v9, vcc
	v_add_co_u32_e32 v96, vcc, 0x90000, v8
	s_waitcnt lgkmcnt(14)
	v_mov_b32_e32 v100, v27
	v_addc_co_u32_e32 v97, vcc, 0, v9, vcc
	v_add_co_u32_e32 v98, vcc, 0xa8000, v8
	global_load_dwordx2 v[94:95], v[94:95], off nt
	s_nop 0
	global_load_dwordx2 v[96:97], v[96:97], off nt
	v_addc_co_u32_e32 v99, vcc, 0, v9, vcc
	v_add_co_u32_e32 v102, vcc, 0xc0000, v8
	s_waitcnt lgkmcnt(13)
	v_mov_b32_e32 v118, v35
	v_addc_co_u32_e32 v103, vcc, 0, v9, vcc
	v_add_co_u32_e32 v104, vcc, 0xd8000, v8
	global_load_dwordx2 v[98:99], v[98:99], off nt
	s_nop 0
	global_load_dwordx2 v[102:103], v[102:103], off nt
	v_addc_co_u32_e32 v105, vcc, 0, v9, vcc
	v_add_co_u32_e32 v106, vcc, 0xf0000, v8
	s_waitcnt lgkmcnt(11)
	v_mov_b32_e32 v120, v43
	v_addc_co_u32_e32 v107, vcc, 0, v9, vcc
	v_add_co_u32_e32 v108, vcc, 0x108000, v8
	global_load_dwordx2 v[104:105], v[104:105], off nt
	s_nop 0
	global_load_dwordx2 v[106:107], v[106:107], off nt
	v_addc_co_u32_e32 v109, vcc, 0, v9, vcc
	v_add_co_u32_e32 v110, vcc, 0x120000, v8
	s_waitcnt lgkmcnt(9)
	v_mov_b32_e32 v122, v51
	v_addc_co_u32_e32 v111, vcc, 0, v9, vcc
	v_add_co_u32_e32 v112, vcc, 0x138000, v8
	global_load_dwordx2 v[108:109], v[108:109], off nt
	s_nop 0
	global_load_dwordx2 v[110:111], v[110:111], off nt
	v_addc_co_u32_e32 v113, vcc, 0, v9, vcc
	v_add_co_u32_e32 v114, vcc, 0x150000, v8
	global_load_dwordx2 v[112:113], v[112:113], off nt
	s_nop 0
	v_addc_co_u32_e32 v115, vcc, 0, v9, vcc
	v_add_co_u32_e32 v116, vcc, 0x168000, v8
	global_load_dwordx2 v[114:115], v[114:115], off nt
	s_nop 0
	v_addc_co_u32_e32 v117, vcc, 0, v9, vcc
	global_load_dwordx2 v[116:117], v[116:117], off nt
	v_mov_b32_e32 v124, v31
	v_mov_b32_e32 v126, v39
	v_mov_b32_e32 v128, v47
	s_waitcnt lgkmcnt(8)
	v_mov_b32_e32 v130, v55
	s_waitcnt lgkmcnt(7)
	v_mov_b32_e32 v132, v59
	s_waitcnt lgkmcnt(5)
	v_mov_b32_e32 v136, v67
	s_waitcnt vmcnt(15)
	v_pk_fma_f32 v[12:13], v[18:19], v[24:25], v[12:13] op_sel_hi:[1,0,1]
	v_pk_fma_f32 v[14:15], v[18:19], v[32:33], v[14:15] op_sel_hi:[1,0,1]
	v_pk_fma_f32 v[16:17], v[18:19], v[40:41], v[16:17] op_sel_hi:[1,0,1]
	v_pk_fma_f32 v[10:11], v[18:19], v[48:49], v[10:11] op_sel_hi:[1,0,1]
	s_waitcnt lgkmcnt(3)
	v_mov_b32_e32 v140, v75
	s_waitcnt lgkmcnt(1)
	v_mov_b32_e32 v144, v83
	s_add_i32 s16, s16, 16
	s_add_i32 s17, s17, 64
	v_mov_b32_e32 v134, v63
	v_mov_b32_e32 v138, v71
	v_mov_b32_e32 v142, v79
	s_waitcnt lgkmcnt(0)
	v_mov_b32_e32 v146, v87
	s_cmpk_gt_u32 s16, 0x1ef
	v_lshl_add_u64 v[8:9], v[8:9], 0, s[10:11]
	s_waitcnt vmcnt(14)
	v_pk_fma_f32 v[12:13], v[20:21], v[24:25], v[12:13] op_sel:[0,1,0]
	v_pk_fma_f32 v[14:15], v[20:21], v[32:33], v[14:15] op_sel:[0,1,0]
	v_pk_fma_f32 v[16:17], v[20:21], v[40:41], v[16:17] op_sel:[0,1,0]
	v_pk_fma_f32 v[10:11], v[20:21], v[48:49], v[10:11] op_sel:[0,1,0]
	s_waitcnt vmcnt(13)
	v_pk_fma_f32 v[12:13], v[88:89], v[26:27], v[12:13] op_sel_hi:[1,0,1]
	v_pk_fma_f32 v[14:15], v[88:89], v[34:35], v[14:15] op_sel_hi:[1,0,1]
	v_pk_fma_f32 v[16:17], v[88:89], v[42:43], v[16:17] op_sel_hi:[1,0,1]
	v_pk_fma_f32 v[10:11], v[88:89], v[50:51], v[10:11] op_sel_hi:[1,0,1]
	s_waitcnt vmcnt(12)
	v_pk_fma_f32 v[12:13], v[90:91], v[100:101], v[12:13] op_sel_hi:[1,0,1]
	v_pk_fma_f32 v[14:15], v[90:91], v[118:119], v[14:15] op_sel_hi:[1,0,1]
	v_pk_fma_f32 v[16:17], v[90:91], v[120:121], v[16:17] op_sel_hi:[1,0,1]
	v_pk_fma_f32 v[10:11], v[90:91], v[122:123], v[10:11] op_sel_hi:[1,0,1]
	s_waitcnt vmcnt(11)
	v_pk_fma_f32 v[12:13], v[92:93], v[28:29], v[12:13] op_sel_hi:[1,0,1]
	v_pk_fma_f32 v[14:15], v[92:93], v[36:37], v[14:15] op_sel_hi:[1,0,1]
	v_pk_fma_f32 v[16:17], v[92:93], v[44:45], v[16:17] op_sel_hi:[1,0,1]
	v_pk_fma_f32 v[10:11], v[92:93], v[52:53], v[10:11] op_sel_hi:[1,0,1]
	s_waitcnt vmcnt(10)
	v_pk_fma_f32 v[12:13], v[94:95], v[28:29], v[12:13] op_sel:[0,1,0]
	v_pk_fma_f32 v[14:15], v[94:95], v[36:37], v[14:15] op_sel:[0,1,0]
	v_pk_fma_f32 v[16:17], v[94:95], v[44:45], v[16:17] op_sel:[0,1,0]
	v_pk_fma_f32 v[10:11], v[94:95], v[52:53], v[10:11] op_sel:[0,1,0]
	s_waitcnt vmcnt(9)
	v_pk_fma_f32 v[12:13], v[96:97], v[30:31], v[12:13] op_sel_hi:[1,0,1]
	v_pk_fma_f32 v[14:15], v[96:97], v[38:39], v[14:15] op_sel_hi:[1,0,1]
	v_pk_fma_f32 v[16:17], v[96:97], v[46:47], v[16:17] op_sel_hi:[1,0,1]
	v_pk_fma_f32 v[10:11], v[96:97], v[54:55], v[10:11] op_sel_hi:[1,0,1]
	s_waitcnt vmcnt(8)
	v_pk_fma_f32 v[12:13], v[98:99], v[124:125], v[12:13] op_sel_hi:[1,0,1]
	v_pk_fma_f32 v[14:15], v[98:99], v[126:127], v[14:15] op_sel_hi:[1,0,1]
	v_pk_fma_f32 v[16:17], v[98:99], v[128:129], v[16:17] op_sel_hi:[1,0,1]
	v_pk_fma_f32 v[10:11], v[98:99], v[130:131], v[10:11] op_sel_hi:[1,0,1]
	s_waitcnt vmcnt(7)
	v_pk_fma_f32 v[12:13], v[102:103], v[56:57], v[12:13] op_sel_hi:[1,0,1]
	v_pk_fma_f32 v[14:15], v[102:103], v[64:65], v[14:15] op_sel_hi:[1,0,1]
	v_pk_fma_f32 v[16:17], v[102:103], v[72:73], v[16:17] op_sel_hi:[1,0,1]
	v_pk_fma_f32 v[10:11], v[102:103], v[80:81], v[10:11] op_sel_hi:[1,0,1]
	s_waitcnt vmcnt(6)
	v_pk_fma_f32 v[12:13], v[104:105], v[56:57], v[12:13] op_sel:[0,1,0]
	v_pk_fma_f32 v[14:15], v[104:105], v[64:65], v[14:15] op_sel:[0,1,0]
	v_pk_fma_f32 v[16:17], v[104:105], v[72:73], v[16:17] op_sel:[0,1,0]
	v_pk_fma_f32 v[10:11], v[104:105], v[80:81], v[10:11] op_sel:[0,1,0]
	s_waitcnt vmcnt(5)
	v_pk_fma_f32 v[12:13], v[106:107], v[58:59], v[12:13] op_sel_hi:[1,0,1]
	v_pk_fma_f32 v[14:15], v[106:107], v[66:67], v[14:15] op_sel_hi:[1,0,1]
	v_pk_fma_f32 v[16:17], v[106:107], v[74:75], v[16:17] op_sel_hi:[1,0,1]
	v_pk_fma_f32 v[10:11], v[106:107], v[82:83], v[10:11] op_sel_hi:[1,0,1]
	s_waitcnt vmcnt(4)
	v_pk_fma_f32 v[12:13], v[108:109], v[132:133], v[12:13] op_sel_hi:[1,0,1]
	v_pk_fma_f32 v[14:15], v[108:109], v[136:137], v[14:15] op_sel_hi:[1,0,1]
	v_pk_fma_f32 v[16:17], v[108:109], v[140:141], v[16:17] op_sel_hi:[1,0,1]
	v_pk_fma_f32 v[10:11], v[108:109], v[144:145], v[10:11] op_sel_hi:[1,0,1]
	s_waitcnt vmcnt(3)
	v_pk_fma_f32 v[12:13], v[110:111], v[60:61], v[12:13] op_sel_hi:[1,0,1]
	v_pk_fma_f32 v[14:15], v[110:111], v[68:69], v[14:15] op_sel_hi:[1,0,1]
	v_pk_fma_f32 v[16:17], v[110:111], v[76:77], v[16:17] op_sel_hi:[1,0,1]
	v_pk_fma_f32 v[10:11], v[110:111], v[84:85], v[10:11] op_sel_hi:[1,0,1]
	s_waitcnt vmcnt(2)
	v_pk_fma_f32 v[12:13], v[112:113], v[60:61], v[12:13] op_sel:[0,1,0]
	v_pk_fma_f32 v[14:15], v[112:113], v[68:69], v[14:15] op_sel:[0,1,0]
	v_pk_fma_f32 v[16:17], v[112:113], v[76:77], v[16:17] op_sel:[0,1,0]
	v_pk_fma_f32 v[10:11], v[112:113], v[84:85], v[10:11] op_sel:[0,1,0]
	s_waitcnt vmcnt(1)
	v_pk_fma_f32 v[12:13], v[114:115], v[62:63], v[12:13] op_sel_hi:[1,0,1]
	v_pk_fma_f32 v[14:15], v[114:115], v[70:71], v[14:15] op_sel_hi:[1,0,1]
	v_pk_fma_f32 v[16:17], v[114:115], v[78:79], v[16:17] op_sel_hi:[1,0,1]
	v_pk_fma_f32 v[10:11], v[114:115], v[86:87], v[10:11] op_sel_hi:[1,0,1]
	s_waitcnt vmcnt(0)
	v_pk_fma_f32 v[12:13], v[116:117], v[134:135], v[12:13] op_sel_hi:[1,0,1]
	v_pk_fma_f32 v[14:15], v[116:117], v[138:139], v[14:15] op_sel_hi:[1,0,1]
	v_pk_fma_f32 v[16:17], v[116:117], v[142:143], v[16:17] op_sel_hi:[1,0,1]
	v_pk_fma_f32 v[10:11], v[116:117], v[146:147], v[10:11] op_sel_hi:[1,0,1]
	s_cbranch_scc0 .LBB0_16
	s_and_saveexec_b64 s[16:17], s[2:3]
	s_cbranch_execz .LBB0_19
	ds_write2_b64 v2, v[12:13], v[14:15] offset1:48
	ds_write2_b64 v2, v[16:17], v[10:11] offset0:96 offset1:144

.LBB0_25:
	s_cmpk_gt_i32 s67, 0x2df
	s_mov_b64 s[28:29], -1
	s_cbranch_scc0 .LBB0_78
	s_cmpk_gt_u32 s67, 0x35f
	s_cbranch_scc0 .LBB0_65
	s_lshl_b32 s4, s42, 10
	s_cmpk_gt_u32 s67, 0x55f
	s_cbranch_scc0 .LBB0_52
	s_cmpk_gt_u32 s67, 0x5df
	s_cbranch_scc0 .LBB0_40
	v_add_u32_e32 v34, s43, v45
	v_add_u32_e32 v2, 0xfffd1000, v34
	buffer_load_dword v4, v2, s[16:19], 0 offen nt
	v_add_u32_e32 v2, 0xfffd9000, v34
	buffer_load_dword v5, v2, s[16:19], 0 offen nt
	v_add_u32_e32 v2, 0x8000, v2
	buffer_load_dword v6, v2, s[16:19], 0 offen nt
	v_add_u32_e32 v2, 0x8000, v2
	buffer_load_dword v7, v2, s[16:19], 0 offen nt
	v_add_u32_e32 v2, 0x8000, v2
	buffer_load_dword v8, v2, s[16:19], 0 offen nt
	v_add_u32_e32 v2, 0x8000, v2
	buffer_load_dword v9, v2, s[16:19], 0 offen nt
	v_add_u32_e32 v2, 0x8000, v2
	buffer_load_dword v10, v2, s[16:19], 0 offen nt
	v_add_u32_e32 v2, 0x8000, v2
	buffer_load_dword v11, v2, s[16:19], 0 offen nt
	v_add_u32_e32 v2, 0x8000, v2
	buffer_load_dword v12, v2, s[16:19], 0 offen nt
	v_add_u32_e32 v2, 0x8000, v2
	buffer_load_dword v13, v2, s[16:19], 0 offen nt
	v_add_u32_e32 v2, 0x8000, v2
	buffer_load_dword v14, v2, s[16:19], 0 offen nt
	v_add_u32_e32 v2, 0x8000, v2
	buffer_load_dword v15, v2, s[16:19], 0 offen nt
	v_add_u32_e32 v2, 0x8000, v2
	buffer_load_dword v16, v2, s[16:19], 0 offen nt
	v_add_u32_e32 v2, 0x8000, v2
	buffer_load_dword v17, v2, s[16:19], 0 offen nt
	v_add_u32_e32 v2, 0x8000, v2
	buffer_load_dword v18, v2, s[16:19], 0 offen nt
	v_add_u32_e32 v2, 0x8000, v2
	buffer_load_dword v19, v2, s[16:19], 0 offen nt
	v_add_u32_e32 v2, 0x8000, v2
	buffer_load_dword v20, v2, s[16:19], 0 offen nt
	v_add_u32_e32 v2, 0x8000, v2
	buffer_load_dword v21, v2, s[16:19], 0 offen nt
	v_add_u32_e32 v2, 0x8000, v2
	buffer_load_dword v22, v2, s[16:19], 0 offen nt
	v_add_u32_e32 v2, 0x8000, v2
	buffer_load_dword v23, v2, s[16:19], 0 offen nt
	v_add_u32_e32 v2, 0x8000, v2
	buffer_load_dword v24, v2, s[16:19], 0 offen nt
	v_add_u32_e32 v2, 0x8000, v2
	buffer_load_dword v25, v2, s[16:19], 0 offen nt
	v_add_u32_e32 v2, 0x8000, v2
	buffer_load_dword v26, v2, s[16:19], 0 offen nt
	v_add_u32_e32 v2, 0x8000, v2
	buffer_load_dword v27, v2, s[16:19], 0 offen nt
	v_add_u32_e32 v2, 0x8000, v2
	buffer_load_dword v28, v2, s[16:19], 0 offen nt
	v_add_u32_e32 v2, 0x8000, v2
	buffer_load_dword v29, v2, s[16:19], 0 offen nt
	v_add_u32_e32 v2, 0x8000, v2
	buffer_load_dword v30, v2, s[16:19], 0 offen nt
	v_add_u32_e32 v2, 0x8000, v2
	buffer_load_dword v31, v2, s[16:19], 0 offen nt
	v_add_u32_e32 v2, 0x8000, v2
	buffer_load_dword v32, v2, s[16:19], 0 offen nt
	v_add_u32_e32 v2, 0x8000, v2
	buffer_load_dword v33, v2, s[16:19], 0 offen nt
	v_add_u32_e32 v2, 0x8000, v2
	buffer_load_dword v88, v2, s[16:19], 0 offen nt
	v_add_u32_e32 v2, 0x8000, v2
	buffer_load_dword v89, v2, s[16:19], 0 offen nt
	v_add_u32_e32 v2, 0x8000, v2
	s_waitcnt vmcnt(30)
	v_max_f32_e64 v35, |v5|, |v5|
	v_max_f32_e64 v2, |v4|, |v4|
	v_max_f32_e32 v2, v2, v35
	s_waitcnt vmcnt(29)
	v_max_f32_e64 v35, |v6|, |v6|
	s_waitcnt vmcnt(28)
	v_max_f32_e64 v36, |v7|, |v7|
	v_max_f32_e32 v35, v35, v36
	v_max3_f32 v2, v2, 0, v35
	s_waitcnt vmcnt(27)
	v_max_f32_e64 v35, |v8|, |v8|
	s_waitcnt vmcnt(26)
	v_max_f32_e64 v36, |v9|, |v9|
	v_max_f32_e32 v35, v35, v36
	s_waitcnt vmcnt(25)
	v_max_f32_e64 v36, |v10|, |v10|
	s_waitcnt vmcnt(24)
	v_max_f32_e64 v37, |v11|, |v11|
	v_max_f32_e32 v36, v36, v37
	v_max3_f32 v2, v2, v35, v36
	s_waitcnt vmcnt(23)
	v_max_f32_e64 v35, |v12|, |v12|
	s_waitcnt vmcnt(22)
	v_max_f32_e64 v36, |v13|, |v13|
	v_max_f32_e32 v35, v35, v36
	s_waitcnt vmcnt(21)
	v_max_f32_e64 v36, |v14|, |v14|
	s_waitcnt vmcnt(20)
	v_max_f32_e64 v37, |v15|, |v15|
	v_max_f32_e32 v36, v36, v37
	v_max3_f32 v2, v2, v35, v36
	s_waitcnt vmcnt(19)
	v_max_f32_e64 v35, |v16|, |v16|
	s_waitcnt vmcnt(18)
	v_max_f32_e64 v36, |v17|, |v17|
	v_max_f32_e32 v35, v35, v36
	v_cmp_lt_i32_e32 vcc, v54, v55
	s_waitcnt vmcnt(17)
	v_max_f32_e64 v36, |v18|, |v18|
	s_add_i32 s12, s4, 0
	s_add_i32 s12, s12, 0x20800
	s_waitcnt vmcnt(16)
	v_max_f32_e64 v37, |v19|, |v19|
	v_max_f32_e32 v36, v36, v37
	v_max3_f32 v35, v2, v35, v36
	s_waitcnt vmcnt(15)
	v_max_f32_e64 v2, |v20|, |v20|
	s_waitcnt vmcnt(14)
	v_max_f32_e64 v36, |v21|, |v21|
	v_max_f32_e32 v36, v2, v36
	v_add_u32_e32 v2, 0x7d1000, v34
	v_add_u32_e32 v34, 0x7d9000, v34
	buffer_load_dword v2, v2, s[16:19], 0 offen nt
	buffer_load_dword v57, v34, s[16:19], 0 offen nt
	v_add_u32_e32 v34, 0x8000, v34
	buffer_load_dword v58, v34, s[16:19], 0 offen nt
	v_add_u32_e32 v34, 0x8000, v34
	buffer_load_dword v59, v34, s[16:19], 0 offen nt
	v_add_u32_e32 v34, 0x8000, v34
	buffer_load_dword v60, v34, s[16:19], 0 offen nt
	v_add_u32_e32 v34, 0x8000, v34
	buffer_load_dword v61, v34, s[16:19], 0 offen nt
	v_add_u32_e32 v34, 0x8000, v34
	buffer_load_dword v62, v34, s[16:19], 0 offen nt
	v_add_u32_e32 v34, 0x8000, v34
	buffer_load_dword v63, v34, s[16:19], 0 offen nt
	v_add_u32_e32 v34, 0x8000, v34
	buffer_load_dword v64, v34, s[16:19], 0 offen nt
	v_add_u32_e32 v34, 0x8000, v34
	buffer_load_dword v65, v34, s[16:19], 0 offen nt
	v_add_u32_e32 v34, 0x8000, v34
	buffer_load_dword v66, v34, s[16:19], 0 offen nt
	v_add_u32_e32 v34, 0x8000, v34
	buffer_load_dword v67, v34, s[16:19], 0 offen nt
	v_add_u32_e32 v34, 0x8000, v34
	buffer_load_dword v68, v34, s[16:19], 0 offen nt
	v_add_u32_e32 v34, 0x8000, v34
	buffer_load_dword v69, v34, s[16:19], 0 offen nt
	v_add_u32_e32 v34, 0x8000, v34
	buffer_load_dword v70, v34, s[16:19], 0 offen nt
	v_add_u32_e32 v34, 0x8000, v34
	buffer_load_dword v71, v34, s[16:19], 0 offen nt
	v_add_u32_e32 v34, 0x8000, v34
	buffer_load_dword v72, v34, s[16:19], 0 offen nt
	v_add_u32_e32 v34, 0x8000, v34
	buffer_load_dword v73, v34, s[16:19], 0 offen nt
	v_add_u32_e32 v34, 0x8000, v34
	buffer_load_dword v74, v34, s[16:19], 0 offen nt
	v_add_u32_e32 v34, 0x8000, v34
	buffer_load_dword v75, v34, s[16:19], 0 offen nt
	v_add_u32_e32 v34, 0x8000, v34
	buffer_load_dword v76, v34, s[16:19], 0 offen nt
	v_add_u32_e32 v34, 0x8000, v34
	buffer_load_dword v77, v34, s[16:19], 0 offen nt
	v_add_u32_e32 v34, 0x8000, v34
	buffer_load_dword v78, v34, s[16:19], 0 offen nt
	v_add_u32_e32 v34, 0x8000, v34
	buffer_load_dword v79, v34, s[16:19], 0 offen nt
	v_add_u32_e32 v34, 0x8000, v34
	buffer_load_dword v80, v34, s[16:19], 0 offen nt
	v_add_u32_e32 v34, 0x8000, v34
	buffer_load_dword v81, v34, s[16:19], 0 offen nt
	v_add_u32_e32 v34, 0x8000, v34
	buffer_load_dword v82, v34, s[16:19], 0 offen nt
	v_add_u32_e32 v34, 0x8000, v34
	buffer_load_dword v83, v34, s[16:19], 0 offen nt
	v_add_u32_e32 v34, 0x8000, v34
	buffer_load_dword v84, v34, s[16:19], 0 offen nt
	v_add_u32_e32 v34, 0x8000, v34
	buffer_load_dword v85, v34, s[16:19], 0 offen nt
	v_add_u32_e32 v34, 0x8000, v34
	buffer_load_dword v86, v34, s[16:19], 0 offen nt
	v_add_u32_e32 v34, 0x8000, v34
	buffer_load_dword v87, v34, s[16:19], 0 offen nt
	s_waitcnt vmcnt(45)
	v_max_f32_e64 v37, |v22|, |v22|
	s_waitcnt vmcnt(44)
	v_max_f32_e64 v90, |v23|, |v23|
	v_max_f32_e32 v37, v37, v90
	v_max3_f32 v35, v35, v36, v37
	s_waitcnt vmcnt(43)
	v_max_f32_e64 v36, |v24|, |v24|
	s_waitcnt vmcnt(42)
	v_max_f32_e64 v37, |v25|, |v25|
	v_max_f32_e32 v36, v36, v37
	s_waitcnt vmcnt(41)
	v_max_f32_e64 v37, |v26|, |v26|
	s_waitcnt vmcnt(40)
	v_max_f32_e64 v90, |v27|, |v27|
	v_max_f32_e32 v37, v37, v90
	v_max3_f32 v35, v35, v36, v37
	s_waitcnt vmcnt(39)
	v_max_f32_e64 v36, |v28|, |v28|
	s_waitcnt vmcnt(38)
	v_max_f32_e64 v37, |v29|, |v29|
	v_max_f32_e32 v36, v36, v37
	s_waitcnt vmcnt(37)
	v_max_f32_e64 v37, |v30|, |v30|
	s_waitcnt vmcnt(36)
	v_max_f32_e64 v90, |v31|, |v31|
	v_max_f32_e32 v37, v37, v90
	v_max3_f32 v35, v35, v36, v37
	s_waitcnt vmcnt(35)
	v_max_f32_e64 v36, |v32|, |v32|
	s_waitcnt vmcnt(34)
	v_max_f32_e64 v37, |v33|, |v33|
	v_max_f32_e32 v36, v36, v37
	s_waitcnt vmcnt(33)
	v_max_f32_e64 v37, |v88|, |v88|
	s_waitcnt vmcnt(32)
	v_max_f32_e64 v90, |v89|, |v89|
	v_add_u32_e32 v34, 0x8000, v34
	v_max_f32_e32 v37, v37, v90
	v_max3_f32 v35, v35, v36, v37
	s_waitcnt vmcnt(31)
	v_max_f32_e64 v34, |v2|, |v2|
	s_waitcnt vmcnt(30)
	v_max_f32_e64 v36, |v57|, |v57|
	v_max_f32_e32 v34, v34, v36
	s_waitcnt vmcnt(29)
	v_max_f32_e64 v36, |v58|, |v58|
	s_waitcnt vmcnt(28)
	v_max_f32_e64 v37, |v59|, |v59|
	v_max_f32_e32 v36, v36, v37
	v_max3_f32 v34, v35, v34, v36
	s_waitcnt vmcnt(27)
	v_max_f32_e64 v35, |v60|, |v60|
	s_waitcnt vmcnt(26)
	v_max_f32_e64 v36, |v61|, |v61|
	v_max_f32_e32 v35, v35, v36
	s_waitcnt vmcnt(25)
	v_max_f32_e64 v36, |v62|, |v62|
	s_waitcnt vmcnt(24)
	v_max_f32_e64 v37, |v63|, |v63|
	v_max_f32_e32 v36, v36, v37
	v_max3_f32 v34, v34, v35, v36
	s_waitcnt vmcnt(23)
	v_max_f32_e64 v35, |v64|, |v64|
	s_waitcnt vmcnt(22)
	v_max_f32_e64 v36, |v65|, |v65|
	v_max_f32_e32 v35, v35, v36
	s_waitcnt vmcnt(21)
	v_max_f32_e64 v36, |v66|, |v66|
	s_waitcnt vmcnt(20)
	v_max_f32_e64 v37, |v67|, |v67|
	v_max_f32_e32 v36, v36, v37
	v_max3_f32 v34, v34, v35, v36
	s_waitcnt vmcnt(19)
	v_max_f32_e64 v35, |v68|, |v68|
	s_waitcnt vmcnt(18)
	v_max_f32_e64 v36, |v69|, |v69|
	v_max_f32_e32 v35, v35, v36
	s_waitcnt vmcnt(17)
	v_max_f32_e64 v36, |v70|, |v70|
	s_waitcnt vmcnt(16)
	v_max_f32_e64 v37, |v71|, |v71|
	v_max_f32_e32 v36, v36, v37
	v_max3_f32 v34, v34, v35, v36
	s_waitcnt vmcnt(15)
	v_max_f32_e64 v35, |v72|, |v72|
	s_waitcnt vmcnt(14)
	v_max_f32_e64 v36, |v73|, |v73|
	v_max_f32_e32 v35, v35, v36
	s_waitcnt vmcnt(13)
	v_max_f32_e64 v36, |v74|, |v74|
	s_waitcnt vmcnt(12)
	v_max_f32_e64 v37, |v75|, |v75|
	v_max_f32_e32 v36, v36, v37
	v_max3_f32 v34, v34, v35, v36
	s_waitcnt vmcnt(11)
	v_max_f32_e64 v35, |v76|, |v76|
	s_waitcnt vmcnt(10)
	v_max_f32_e64 v36, |v77|, |v77|
	v_max_f32_e32 v35, v35, v36
	s_waitcnt vmcnt(9)
	v_max_f32_e64 v36, |v78|, |v78|
	s_waitcnt vmcnt(8)
	v_max_f32_e64 v37, |v79|, |v79|
	v_max_f32_e32 v36, v36, v37
	v_max3_f32 v34, v34, v35, v36
	s_waitcnt vmcnt(7)
	v_max_f32_e64 v35, |v80|, |v80|
	s_waitcnt vmcnt(6)
	v_max_f32_e64 v36, |v81|, |v81|
	v_max_f32_e32 v35, v35, v36
	s_waitcnt vmcnt(5)
	v_max_f32_e64 v36, |v82|, |v82|
	s_waitcnt vmcnt(4)
	v_max_f32_e64 v37, |v83|, |v83|
	v_max_f32_e32 v36, v36, v37
	v_max3_f32 v34, v34, v35, v36
	s_waitcnt vmcnt(3)
	v_max_f32_e64 v35, |v84|, |v84|
	s_waitcnt vmcnt(2)
	v_max_f32_e64 v36, |v85|, |v85|
	v_max_f32_e32 v35, v35, v36
	s_waitcnt vmcnt(1)
	v_max_f32_e64 v36, |v86|, |v86|
	s_waitcnt vmcnt(0)
	v_max_f32_e64 v37, |v87|, |v87|
	v_max_f32_e32 v36, v36, v37
	v_max3_f32 v34, v34, v35, v36
	v_cndmask_b32_e32 v35, v53, v54, vcc
	v_lshlrev_b32_e32 v35, 2, v35
	ds_bpermute_b32 v35, v35, v34
	s_and_saveexec_b64 s[28:29], s[2:3]
	s_cbranch_execz .LBB0_31
	s_add_i32 s46, s12, s34
	s_waitcnt lgkmcnt(0)
	v_max_f32_e32 v35, v35, v35
	v_max_f32_e32 v34, v34, v34
	v_lshl_add_u32 v36, v182, 2, s46
	v_max_f32_e32 v34, v34, v35
	ds_write_b32 v36, v34

.LBB0_40:
	s_and_b64 vcc, exec, s[28:29]
	s_cbranch_vccz .LBB0_89
	v_add_u32_e32 v33, s43, v45
	v_add_u32_e32 v2, 0xfffd5000, v33
	v_add_u32_e32 v5, 0xfffdd000, v33
	buffer_load_dword v2, v2, s[20:23], 0 offen nt
	buffer_load_dword v4, v5, s[20:23], 0 offen nt
	v_add_u32_e32 v6, 0x8000, v5
	buffer_load_dword v5, v6, s[20:23], 0 offen nt
	v_add_u32_e32 v7, 0x8000, v6
	buffer_load_dword v6, v7, s[20:23], 0 offen nt
	v_add_u32_e32 v8, 0x8000, v7
	buffer_load_dword v7, v8, s[20:23], 0 offen nt
	v_add_u32_e32 v9, 0x8000, v8
	buffer_load_dword v8, v9, s[20:23], 0 offen nt
	v_add_u32_e32 v10, 0x8000, v9
	buffer_load_dword v9, v10, s[20:23], 0 offen nt
	v_add_u32_e32 v11, 0x8000, v10
	buffer_load_dword v10, v11, s[20:23], 0 offen nt
	v_add_u32_e32 v12, 0x8000, v11
	buffer_load_dword v11, v12, s[20:23], 0 offen nt
	v_add_u32_e32 v13, 0x8000, v12
	buffer_load_dword v12, v13, s[20:23], 0 offen nt
	v_add_u32_e32 v14, 0x8000, v13
	buffer_load_dword v13, v14, s[20:23], 0 offen nt
	v_add_u32_e32 v15, 0x8000, v14
	buffer_load_dword v14, v15, s[20:23], 0 offen nt
	v_add_u32_e32 v16, 0x8000, v15
	buffer_load_dword v15, v16, s[20:23], 0 offen nt
	v_add_u32_e32 v17, 0x8000, v16
	buffer_load_dword v16, v17, s[20:23], 0 offen nt
	v_add_u32_e32 v18, 0x8000, v17
	buffer_load_dword v17, v18, s[20:23], 0 offen nt
	v_add_u32_e32 v19, 0x8000, v18
	buffer_load_dword v18, v19, s[20:23], 0 offen nt
	v_add_u32_e32 v20, 0x8000, v19
	buffer_load_dword v19, v20, s[20:23], 0 offen nt
	v_add_u32_e32 v21, 0x8000, v20
	buffer_load_dword v20, v21, s[20:23], 0 offen nt
	v_add_u32_e32 v22, 0x8000, v21
	buffer_load_dword v21, v22, s[20:23], 0 offen nt
	v_add_u32_e32 v23, 0x8000, v22
	buffer_load_dword v22, v23, s[20:23], 0 offen nt
	v_add_u32_e32 v24, 0x8000, v23
	buffer_load_dword v23, v24, s[20:23], 0 offen nt
	v_add_u32_e32 v25, 0x8000, v24
	buffer_load_dword v24, v25, s[20:23], 0 offen nt
	v_add_u32_e32 v26, 0x8000, v25
	buffer_load_dword v25, v26, s[20:23], 0 offen nt
	v_add_u32_e32 v27, 0x8000, v26
	buffer_load_dword v26, v27, s[20:23], 0 offen nt
	v_add_u32_e32 v28, 0x8000, v27
	buffer_load_dword v27, v28, s[20:23], 0 offen nt
	v_add_u32_e32 v29, 0x8000, v28
	buffer_load_dword v28, v29, s[20:23], 0 offen nt
	v_add_u32_e32 v30, 0x8000, v29
	buffer_load_dword v29, v30, s[20:23], 0 offen nt
	v_add_u32_e32 v31, 0x8000, v30
	buffer_load_dword v30, v31, s[20:23], 0 offen nt
	v_add_u32_e32 v32, 0x8000, v31
	buffer_load_dword v31, v32, s[20:23], 0 offen nt
	v_add_u32_e32 v34, 0x8000, v32
	buffer_load_dword v32, v34, s[20:23], 0 offen nt
	v_add_u32_e32 v34, 0x8000, v34
	buffer_load_dword v121, v34, s[20:23], 0 offen nt
	v_add_u32_e32 v34, 0x8000, v34
	buffer_load_dword v122, v34, s[20:23], 0 offen nt
	v_add_u32_e32 v34, 0x8000, v34
	s_waitcnt vmcnt(30)
	v_max_f32_e64 v35, |v4|, |v4|
	v_max_f32_e64 v34, |v2|, |v2|
	v_max_f32_e32 v34, v34, v35
	s_waitcnt vmcnt(29)
	v_max_f32_e64 v35, |v5|, |v5|
	s_waitcnt vmcnt(28)
	v_max_f32_e64 v36, |v6|, |v6|
	v_max_f32_e32 v35, v35, v36
	v_max3_f32 v34, v34, 0, v35
	s_waitcnt vmcnt(27)
	v_max_f32_e64 v35, |v7|, |v7|
	s_waitcnt vmcnt(26)
	v_max_f32_e64 v36, |v8|, |v8|
	v_max_f32_e32 v35, v35, v36
	s_waitcnt vmcnt(25)
	v_max_f32_e64 v36, |v9|, |v9|
	s_waitcnt vmcnt(24)
	v_max_f32_e64 v37, |v10|, |v10|
	v_max_f32_e32 v36, v36, v37
	v_max3_f32 v34, v34, v35, v36
	s_waitcnt vmcnt(23)
	v_max_f32_e64 v35, |v11|, |v11|
	s_waitcnt vmcnt(22)
	v_max_f32_e64 v36, |v12|, |v12|
	v_max_f32_e32 v35, v35, v36
	s_waitcnt vmcnt(21)
	v_max_f32_e64 v36, |v13|, |v13|
	s_waitcnt vmcnt(20)
	v_max_f32_e64 v37, |v14|, |v14|
	v_max_f32_e32 v36, v36, v37
	v_max3_f32 v34, v34, v35, v36
	s_waitcnt vmcnt(19)
	v_max_f32_e64 v35, |v15|, |v15|
	s_waitcnt vmcnt(18)
	v_max_f32_e64 v36, |v16|, |v16|
	v_max_f32_e32 v35, v35, v36
	v_add_u32_e32 v57, 0x7dd000, v33
	s_waitcnt vmcnt(17)
	v_max_f32_e64 v36, |v17|, |v17|
	v_cmp_lt_i32_e32 vcc, v54, v55
	s_add_i32 s12, s4, 0
	s_waitcnt vmcnt(16)
	v_max_f32_e64 v37, |v18|, |v18|
	v_max_f32_e32 v36, v36, v37
	v_max3_f32 v34, v34, v35, v36
	s_waitcnt vmcnt(15)
	v_max_f32_e64 v35, |v19|, |v19|
	s_add_i32 s12, s12, 0x20800
	s_waitcnt vmcnt(14)
	v_max_f32_e64 v36, |v20|, |v20|
	v_max_f32_e32 v35, v35, v36
	s_waitcnt vmcnt(13)
	v_max_f32_e64 v36, |v21|, |v21|
	s_waitcnt vmcnt(12)
	v_max_f32_e64 v37, |v22|, |v22|
	v_max_f32_e32 v36, v36, v37
	v_max3_f32 v34, v34, v35, v36
	v_add_u32_e32 v36, 0x7d5000, v33
	buffer_load_dword v36, v36, s[20:23], 0 offen nt
	buffer_load_dword v37, v57, s[20:23], 0 offen nt
	v_add_u32_e32 v58, 0x8000, v57
	buffer_load_dword v57, v58, s[20:23], 0 offen nt
	v_add_u32_e32 v59, 0x8000, v58
	buffer_load_dword v58, v59, s[20:23], 0 offen nt
	v_add_u32_e32 v60, 0x8000, v59
	buffer_load_dword v59, v60, s[20:23], 0 offen nt
	v_add_u32_e32 v61, 0x8000, v60
	buffer_load_dword v60, v61, s[20:23], 0 offen nt
	v_add_u32_e32 v62, 0x8000, v61
	buffer_load_dword v61, v62, s[20:23], 0 offen nt
	v_add_u32_e32 v63, 0x8000, v62
	buffer_load_dword v62, v63, s[20:23], 0 offen nt
	v_add_u32_e32 v64, 0x8000, v63
	buffer_load_dword v63, v64, s[20:23], 0 offen nt
	v_add_u32_e32 v65, 0x8000, v64
	buffer_load_dword v64, v65, s[20:23], 0 offen nt
	v_add_u32_e32 v66, 0x8000, v65
	buffer_load_dword v65, v66, s[20:23], 0 offen nt
	v_add_u32_e32 v67, 0x8000, v66
	buffer_load_dword v66, v67, s[20:23], 0 offen nt
	v_add_u32_e32 v68, 0x8000, v67
	buffer_load_dword v67, v68, s[20:23], 0 offen nt
	v_add_u32_e32 v69, 0x8000, v68
	buffer_load_dword v68, v69, s[20:23], 0 offen nt
	v_add_u32_e32 v70, 0x8000, v69
	buffer_load_dword v69, v70, s[20:23], 0 offen nt
	v_add_u32_e32 v71, 0x8000, v70
	buffer_load_dword v70, v71, s[20:23], 0 offen nt
	v_add_u32_e32 v72, 0x8000, v71
	buffer_load_dword v71, v72, s[20:23], 0 offen nt
	v_add_u32_e32 v73, 0x8000, v72
	buffer_load_dword v72, v73, s[20:23], 0 offen nt
	v_add_u32_e32 v74, 0x8000, v73
	buffer_load_dword v73, v74, s[20:23], 0 offen nt
	v_add_u32_e32 v75, 0x8000, v74
	buffer_load_dword v74, v75, s[20:23], 0 offen nt
	v_add_u32_e32 v76, 0x8000, v75
	buffer_load_dword v75, v76, s[20:23], 0 offen nt
	v_add_u32_e32 v77, 0x8000, v76
	buffer_load_dword v76, v77, s[20:23], 0 offen nt
	v_add_u32_e32 v78, 0x8000, v77
	buffer_load_dword v77, v78, s[20:23], 0 offen nt
	v_add_u32_e32 v79, 0x8000, v78
	buffer_load_dword v78, v79, s[20:23], 0 offen nt
	v_add_u32_e32 v80, 0x8000, v79
	buffer_load_dword v79, v80, s[20:23], 0 offen nt
	v_add_u32_e32 v81, 0x8000, v80
	buffer_load_dword v80, v81, s[20:23], 0 offen nt
	v_add_u32_e32 v82, 0x8000, v81
	buffer_load_dword v81, v82, s[20:23], 0 offen nt
	v_add_u32_e32 v84, 0x8000, v82
	buffer_load_dword v82, v84, s[20:23], 0 offen nt
	s_waitcnt vmcnt(39)
	v_max_f32_e64 v35, |v23|, |v23|
	s_waitcnt vmcnt(38)
	v_max_f32_e64 v83, |v24|, |v24|
	v_max_f32_e32 v35, v35, v83
	s_waitcnt vmcnt(37)
	v_max_f32_e64 v83, |v25|, |v25|
	s_waitcnt vmcnt(36)
	v_max_f32_e64 v85, |v26|, |v26|
	v_max_f32_e32 v83, v83, v85
	v_max3_f32 v34, v34, v35, v83
	s_waitcnt vmcnt(35)
	v_max_f32_e64 v35, |v27|, |v27|
	s_waitcnt vmcnt(34)
	v_max_f32_e64 v83, |v28|, |v28|
	v_max_f32_e32 v35, v35, v83
	s_waitcnt vmcnt(33)
	v_max_f32_e64 v83, |v29|, |v29|
	s_waitcnt vmcnt(32)
	v_max_f32_e64 v85, |v30|, |v30|
	v_max_f32_e32 v83, v83, v85
	v_max3_f32 v34, v34, v35, v83
	s_waitcnt vmcnt(31)
	v_max_f32_e64 v35, |v31|, |v31|
	s_waitcnt vmcnt(30)
	v_max_f32_e64 v83, |v32|, |v32|
	v_max_f32_e32 v35, v35, v83
	s_waitcnt vmcnt(29)
	v_max_f32_e64 v83, |v121|, |v121|
	s_waitcnt vmcnt(28)
	v_max_f32_e64 v85, |v122|, |v122|
	v_max_f32_e32 v83, v83, v85
	v_max3_f32 v34, v34, v35, v83
	v_add_u32_e32 v35, 0x8000, v84
	buffer_load_dword v83, v35, s[20:23], 0 offen nt
	v_add_u32_e32 v35, 0x8000, v35
	buffer_load_dword v84, v35, s[20:23], 0 offen nt
	v_add_u32_e32 v35, 0x8000, v35
	buffer_load_dword v85, v35, s[20:23], 0 offen nt
	v_add_u32_e32 v35, 0x8000, v35
	buffer_load_dword v86, v35, s[20:23], 0 offen nt
	v_add_u32_e32 v35, 0x8000, v35
	s_waitcnt vmcnt(30)
	v_max_f32_e64 v87, |v37|, |v37|
	v_max_f32_e64 v35, |v36|, |v36|
	v_max_f32_e32 v35, v35, v87
	s_waitcnt vmcnt(29)
	v_max_f32_e64 v87, |v57|, |v57|
	s_waitcnt vmcnt(28)
	v_max_f32_e64 v88, |v58|, |v58|
	v_max_f32_e32 v87, v87, v88
	v_max3_f32 v34, v34, v35, v87
	s_waitcnt vmcnt(27)
	v_max_f32_e64 v35, |v59|, |v59|
	s_waitcnt vmcnt(26)
	v_max_f32_e64 v87, |v60|, |v60|
	v_max_f32_e32 v35, v35, v87
	s_waitcnt vmcnt(25)
	v_max_f32_e64 v87, |v61|, |v61|
	s_waitcnt vmcnt(24)
	v_max_f32_e64 v88, |v62|, |v62|
	v_max_f32_e32 v87, v87, v88
	v_max3_f32 v34, v34, v35, v87
	s_waitcnt vmcnt(23)
	v_max_f32_e64 v35, |v63|, |v63|
	s_waitcnt vmcnt(22)
	v_max_f32_e64 v87, |v64|, |v64|
	v_max_f32_e32 v35, v35, v87
	s_waitcnt vmcnt(21)
	v_max_f32_e64 v87, |v65|, |v65|
	s_waitcnt vmcnt(20)
	v_max_f32_e64 v88, |v66|, |v66|
	v_max_f32_e32 v87, v87, v88
	v_max3_f32 v34, v34, v35, v87
	s_waitcnt vmcnt(19)
	v_max_f32_e64 v35, |v67|, |v67|
	s_waitcnt vmcnt(18)
	v_max_f32_e64 v87, |v68|, |v68|
	v_max_f32_e32 v35, v35, v87
	s_waitcnt vmcnt(17)
	v_max_f32_e64 v87, |v69|, |v69|
	s_waitcnt vmcnt(16)
	v_max_f32_e64 v88, |v70|, |v70|
	v_max_f32_e32 v87, v87, v88
	v_max3_f32 v34, v34, v35, v87
	s_waitcnt vmcnt(15)
	v_max_f32_e64 v35, |v71|, |v71|
	s_waitcnt vmcnt(14)
	v_max_f32_e64 v87, |v72|, |v72|
	v_max_f32_e32 v35, v35, v87
	s_waitcnt vmcnt(13)
	v_max_f32_e64 v87, |v73|, |v73|
	s_waitcnt vmcnt(12)
	v_max_f32_e64 v88, |v74|, |v74|
	v_max_f32_e32 v87, v87, v88
	v_max3_f32 v34, v34, v35, v87
	s_waitcnt vmcnt(11)
	v_max_f32_e64 v35, |v75|, |v75|
	s_waitcnt vmcnt(10)
	v_max_f32_e64 v87, |v76|, |v76|
	v_max_f32_e32 v35, v35, v87
	s_waitcnt vmcnt(9)
	v_max_f32_e64 v87, |v77|, |v77|
	s_waitcnt vmcnt(8)
	v_max_f32_e64 v88, |v78|, |v78|
	v_max_f32_e32 v87, v87, v88
	v_max3_f32 v34, v34, v35, v87
	s_waitcnt vmcnt(7)
	v_max_f32_e64 v35, |v79|, |v79|
	s_waitcnt vmcnt(6)
	v_max_f32_e64 v87, |v80|, |v80|
	v_max_f32_e32 v35, v35, v87
	s_waitcnt vmcnt(5)
	v_max_f32_e64 v87, |v81|, |v81|
	s_waitcnt vmcnt(4)
	v_max_f32_e64 v88, |v82|, |v82|
	v_max_f32_e32 v87, v87, v88
	v_max3_f32 v34, v34, v35, v87
	v_add_u32_e32 v35, 0xfd5000, v33
	buffer_load_dword v87, v35, s[20:23], 0 offen nt
	v_add_u32_e32 v35, 0xfdd000, v33
	buffer_load_dword v88, v35, s[20:23], 0 offen nt
	v_add_u32_e32 v35, 0x8000, v35
	buffer_load_dword v89, v35, s[20:23], 0 offen nt
	v_add_u32_e32 v35, 0x8000, v35
	buffer_load_dword v90, v35, s[20:23], 0 offen nt
	v_add_u32_e32 v35, 0x8000, v35
	buffer_load_dword v91, v35, s[20:23], 0 offen nt
	v_add_u32_e32 v35, 0x8000, v35
	buffer_load_dword v92, v35, s[20:23], 0 offen nt
	v_add_u32_e32 v35, 0x8000, v35
	buffer_load_dword v93, v35, s[20:23], 0 offen nt
	v_add_u32_e32 v35, 0x8000, v35
	buffer_load_dword v94, v35, s[20:23], 0 offen nt
	v_add_u32_e32 v35, 0x8000, v35
	buffer_load_dword v95, v35, s[20:23], 0 offen nt
	v_add_u32_e32 v35, 0x8000, v35
	buffer_load_dword v96, v35, s[20:23], 0 offen nt
	v_add_u32_e32 v35, 0x8000, v35
	buffer_load_dword v97, v35, s[20:23], 0 offen nt
	v_add_u32_e32 v35, 0x8000, v35
	buffer_load_dword v98, v35, s[20:23], 0 offen nt
	v_add_u32_e32 v35, 0x8000, v35
	buffer_load_dword v99, v35, s[20:23], 0 offen nt
	v_add_u32_e32 v35, 0x8000, v35
	buffer_load_dword v100, v35, s[20:23], 0 offen nt
	v_add_u32_e32 v35, 0x8000, v35
	buffer_load_dword v101, v35, s[20:23], 0 offen nt
	v_add_u32_e32 v35, 0x8000, v35
	buffer_load_dword v102, v35, s[20:23], 0 offen nt
	v_add_u32_e32 v35, 0x8000, v35
	buffer_load_dword v103, v35, s[20:23], 0 offen nt
	v_add_u32_e32 v35, 0x8000, v35
	buffer_load_dword v104, v35, s[20:23], 0 offen nt
	v_add_u32_e32 v35, 0x8000, v35
	buffer_load_dword v105, v35, s[20:23], 0 offen nt
	s_waitcnt vmcnt(22)
	v_max_f32_e64 v106, |v83|, |v83|
	s_waitcnt vmcnt(21)
	v_max_f32_e64 v107, |v84|, |v84|
	v_add_u32_e32 v35, 0x8000, v35
	v_max_f32_e32 v106, v106, v107
	s_waitcnt vmcnt(20)
	v_max_f32_e64 v107, |v85|, |v85|
	s_waitcnt vmcnt(19)
	v_max_f32_e64 v108, |v86|, |v86|
	v_max_f32_e32 v107, v107, v108
	buffer_load_dword v108, v35, s[20:23], 0 offen nt
	v_add_u32_e32 v35, 0x8000, v35
	buffer_load_dword v109, v35, s[20:23], 0 offen nt
	v_add_u32_e32 v35, 0x8000, v35
	buffer_load_dword v110, v35, s[20:23], 0 offen nt
	v_add_u32_e32 v35, 0x8000, v35
	buffer_load_dword v111, v35, s[20:23], 0 offen nt
	v_add_u32_e32 v35, 0x8000, v35
	buffer_load_dword v112, v35, s[20:23], 0 offen nt
	v_add_u32_e32 v35, 0x8000, v35
	buffer_load_dword v113, v35, s[20:23], 0 offen nt
	v_add_u32_e32 v35, 0x8000, v35
	buffer_load_dword v114, v35, s[20:23], 0 offen nt
	v_add_u32_e32 v35, 0x8000, v35
	buffer_load_dword v115, v35, s[20:23], 0 offen nt
	v_add_u32_e32 v35, 0x8000, v35
	buffer_load_dword v116, v35, s[20:23], 0 offen nt
	v_add_u32_e32 v35, 0x8000, v35
	buffer_load_dword v117, v35, s[20:23], 0 offen nt
	v_add_u32_e32 v35, 0x8000, v35
	buffer_load_dword v118, v35, s[20:23], 0 offen nt
	v_add_u32_e32 v35, 0x8000, v35
	buffer_load_dword v119, v35, s[20:23], 0 offen nt
	v_add_u32_e32 v35, 0x8000, v35
	buffer_load_dword v120, v35, s[20:23], 0 offen nt
	v_add_u32_e32 v35, 0x8000, v35
	v_max3_f32 v34, v34, v106, v107
	s_waitcnt vmcnt(31)
	v_max_f32_e64 v35, |v87|, |v87|
	s_waitcnt vmcnt(30)
	v_max_f32_e64 v106, |v88|, |v88|
	v_max_f32_e32 v35, v35, v106
	s_waitcnt vmcnt(29)
	v_max_f32_e64 v106, |v89|, |v89|
	s_waitcnt vmcnt(28)
	v_max_f32_e64 v107, |v90|, |v90|
	v_max_f32_e32 v106, v106, v107
	v_max3_f32 v34, v34, v35, v106
	s_waitcnt vmcnt(27)
	v_max_f32_e64 v35, |v91|, |v91|
	s_waitcnt vmcnt(26)
	v_max_f32_e64 v106, |v92|, |v92|
	v_max_f32_e32 v35, v35, v106
	s_waitcnt vmcnt(25)
	v_max_f32_e64 v106, |v93|, |v93|
	s_waitcnt vmcnt(24)
	v_max_f32_e64 v107, |v94|, |v94|
	v_max_f32_e32 v106, v106, v107
	v_max3_f32 v34, v34, v35, v106
	s_waitcnt vmcnt(23)
	v_max_f32_e64 v35, |v95|, |v95|
	s_waitcnt vmcnt(22)
	v_max_f32_e64 v106, |v96|, |v96|
	v_max_f32_e32 v35, v35, v106
	s_waitcnt vmcnt(21)
	v_max_f32_e64 v106, |v97|, |v97|
	s_waitcnt vmcnt(20)
	v_max_f32_e64 v107, |v98|, |v98|
	v_max_f32_e32 v106, v106, v107
	v_max3_f32 v34, v34, v35, v106
	s_waitcnt vmcnt(19)
	v_max_f32_e64 v35, |v99|, |v99|
	s_waitcnt vmcnt(18)
	v_max_f32_e64 v106, |v100|, |v100|
	v_max_f32_e32 v35, v35, v106
	s_waitcnt vmcnt(17)
	v_max_f32_e64 v106, |v101|, |v101|
	s_waitcnt vmcnt(16)
	v_max_f32_e64 v107, |v102|, |v102|
	v_max_f32_e32 v106, v106, v107
	v_max3_f32 v34, v34, v35, v106
	s_waitcnt vmcnt(15)
	v_max_f32_e64 v35, |v103|, |v103|
	s_waitcnt vmcnt(14)
	v_max_f32_e64 v106, |v104|, |v104|
	v_max_f32_e32 v35, v35, v106
	v_add_u32_e32 v106, 0x17d5000, v33
	v_add_u32_e32 v33, 0x17dd000, v33
	buffer_load_dword v123, v106, s[20:23], 0 offen nt
	buffer_load_dword v124, v33, s[20:23], 0 offen nt
	v_add_u32_e32 v33, 0x8000, v33
	buffer_load_dword v125, v33, s[20:23], 0 offen nt
	v_add_u32_e32 v33, 0x8000, v33
	buffer_load_dword v126, v33, s[20:23], 0 offen nt
	v_add_u32_e32 v33, 0x8000, v33
	buffer_load_dword v127, v33, s[20:23], 0 offen nt
	v_add_u32_e32 v33, 0x8000, v33
	buffer_load_dword v128, v33, s[20:23], 0 offen nt
	v_add_u32_e32 v33, 0x8000, v33
	buffer_load_dword v129, v33, s[20:23], 0 offen nt
	v_add_u32_e32 v33, 0x8000, v33
	buffer_load_dword v130, v33, s[20:23], 0 offen nt
	v_add_u32_e32 v33, 0x8000, v33
	buffer_load_dword v131, v33, s[20:23], 0 offen nt
	v_add_u32_e32 v33, 0x8000, v33
	buffer_load_dword v132, v33, s[20:23], 0 offen nt
	v_add_u32_e32 v33, 0x8000, v33
	buffer_load_dword v133, v33, s[20:23], 0 offen nt
	v_add_u32_e32 v33, 0x8000, v33
	buffer_load_dword v134, v33, s[20:23], 0 offen nt
	v_add_u32_e32 v33, 0x8000, v33
	buffer_load_dword v135, v33, s[20:23], 0 offen nt
	v_add_u32_e32 v33, 0x8000, v33
	buffer_load_dword v136, v33, s[20:23], 0 offen nt
	v_add_u32_e32 v33, 0x8000, v33
	buffer_load_dword v137, v33, s[20:23], 0 offen nt
	v_add_u32_e32 v33, 0x8000, v33
	buffer_load_dword v138, v33, s[20:23], 0 offen nt
	v_add_u32_e32 v33, 0x8000, v33
	buffer_load_dword v139, v33, s[20:23], 0 offen nt
	v_add_u32_e32 v33, 0x8000, v33
	buffer_load_dword v140, v33, s[20:23], 0 offen nt
	v_add_u32_e32 v33, 0x8000, v33
	buffer_load_dword v141, v33, s[20:23], 0 offen nt
	v_add_u32_e32 v33, 0x8000, v33
	buffer_load_dword v142, v33, s[20:23], 0 offen nt
	v_add_u32_e32 v33, 0x8000, v33
	buffer_load_dword v143, v33, s[20:23], 0 offen nt
	v_add_u32_e32 v33, 0x8000, v33
	buffer_load_dword v144, v33, s[20:23], 0 offen nt
	v_add_u32_e32 v33, 0x8000, v33
	buffer_load_dword v145, v33, s[20:23], 0 offen nt
	v_add_u32_e32 v33, 0x8000, v33
	buffer_load_dword v146, v33, s[20:23], 0 offen nt
	v_add_u32_e32 v33, 0x8000, v33
	buffer_load_dword v148, v33, s[20:23], 0 offen nt
	v_add_u32_e32 v33, 0x8000, v33
	buffer_load_dword v150, v33, s[20:23], 0 offen nt
	v_add_u32_e32 v33, 0x8000, v33
	buffer_load_dword v151, v33, s[20:23], 0 offen nt
	v_add_u32_e32 v33, 0x8000, v33
	buffer_load_dword v152, v33, s[20:23], 0 offen nt
	v_add_u32_e32 v33, 0x8000, v33
	buffer_load_dword v147, v33, s[20:23], 0 offen nt
	v_add_u32_e32 v33, 0x8000, v33
	buffer_load_dword v149, v33, s[20:23], 0 offen nt
	v_add_u32_e32 v33, 0x8000, v33
	buffer_load_dword v106, v33, s[20:23], 0 offen nt
	v_add_u32_e32 v33, 0x8000, v33
	buffer_load_dword v107, v33, s[20:23], 0 offen nt
	s_waitcnt vmcnt(45)
	v_max_f32_e64 v153, |v105|, |v105|
	s_waitcnt vmcnt(44)
	v_max_f32_e64 v154, |v108|, |v108|
	v_max_f32_e32 v153, v153, v154
	v_max3_f32 v34, v34, v35, v153
	s_waitcnt vmcnt(43)
	v_max_f32_e64 v35, |v109|, |v109|
	s_waitcnt vmcnt(42)
	v_max_f32_e64 v153, |v110|, |v110|
	v_max_f32_e32 v35, v35, v153
	s_waitcnt vmcnt(41)
	v_max_f32_e64 v153, |v111|, |v111|
	s_waitcnt vmcnt(40)
	v_max_f32_e64 v154, |v112|, |v112|
	v_max_f32_e32 v153, v153, v154
	v_max3_f32 v34, v34, v35, v153
	s_waitcnt vmcnt(39)
	v_max_f32_e64 v35, |v113|, |v113|
	s_waitcnt vmcnt(38)
	v_max_f32_e64 v153, |v114|, |v114|
	v_max_f32_e32 v35, v35, v153
	s_waitcnt vmcnt(37)
	v_max_f32_e64 v153, |v115|, |v115|
	s_waitcnt vmcnt(36)
	v_max_f32_e64 v154, |v116|, |v116|
	v_max_f32_e32 v153, v153, v154
	v_max3_f32 v34, v34, v35, v153
	s_waitcnt vmcnt(35)
	v_max_f32_e64 v35, |v117|, |v117|
	s_waitcnt vmcnt(34)
	v_max_f32_e64 v153, |v118|, |v118|
	v_max_f32_e32 v35, v35, v153
	s_waitcnt vmcnt(33)
	v_max_f32_e64 v153, |v119|, |v119|
	s_waitcnt vmcnt(32)
	v_max_f32_e64 v154, |v120|, |v120|
	v_add_u32_e32 v33, 0x8000, v33
	v_max_f32_e32 v153, v153, v154
	v_max3_f32 v34, v34, v35, v153
	s_waitcnt vmcnt(31)
	v_max_f32_e64 v33, |v123|, |v123|
	s_waitcnt vmcnt(30)
	v_max_f32_e64 v35, |v124|, |v124|
	v_max_f32_e32 v33, v33, v35
	s_waitcnt vmcnt(29)
	v_max_f32_e64 v35, |v125|, |v125|
	s_waitcnt vmcnt(28)
	v_max_f32_e64 v153, |v126|, |v126|
	v_max_f32_e32 v35, v35, v153
	v_max3_f32 v33, v34, v33, v35
	s_waitcnt vmcnt(27)
	v_max_f32_e64 v34, |v127|, |v127|
	s_waitcnt vmcnt(26)
	v_max_f32_e64 v35, |v128|, |v128|
	v_max_f32_e32 v34, v34, v35
	s_waitcnt vmcnt(25)
	v_max_f32_e64 v35, |v129|, |v129|
	s_waitcnt vmcnt(24)
	v_max_f32_e64 v153, |v130|, |v130|
	v_max_f32_e32 v35, v35, v153
	v_max3_f32 v33, v33, v34, v35
	s_waitcnt vmcnt(23)
	v_max_f32_e64 v34, |v131|, |v131|
	s_waitcnt vmcnt(22)
	v_max_f32_e64 v35, |v132|, |v132|
	v_max_f32_e32 v34, v34, v35
	s_waitcnt vmcnt(21)
	v_max_f32_e64 v35, |v133|, |v133|
	s_waitcnt vmcnt(20)
	v_max_f32_e64 v153, |v134|, |v134|
	v_max_f32_e32 v35, v35, v153
	v_max3_f32 v33, v33, v34, v35
	s_waitcnt vmcnt(19)
	v_max_f32_e64 v34, |v135|, |v135|
	s_waitcnt vmcnt(18)
	v_max_f32_e64 v35, |v136|, |v136|
	v_max_f32_e32 v34, v34, v35
	s_waitcnt vmcnt(17)
	v_max_f32_e64 v35, |v137|, |v137|
	s_waitcnt vmcnt(16)
	v_max_f32_e64 v153, |v138|, |v138|
	v_max_f32_e32 v35, v35, v153
	v_max3_f32 v33, v33, v34, v35
	s_waitcnt vmcnt(15)
	v_max_f32_e64 v34, |v139|, |v139|
	s_waitcnt vmcnt(14)
	v_max_f32_e64 v35, |v140|, |v140|
	v_max_f32_e32 v34, v34, v35
	s_waitcnt vmcnt(13)
	v_max_f32_e64 v35, |v141|, |v141|
	s_waitcnt vmcnt(12)
	v_max_f32_e64 v153, |v142|, |v142|
	v_max_f32_e32 v35, v35, v153
	v_max3_f32 v33, v33, v34, v35
	s_waitcnt vmcnt(11)
	v_max_f32_e64 v34, |v143|, |v143|
	s_waitcnt vmcnt(10)
	v_max_f32_e64 v35, |v144|, |v144|
	v_max_f32_e32 v34, v34, v35
	s_waitcnt vmcnt(9)
	v_max_f32_e64 v35, |v145|, |v145|
	s_waitcnt vmcnt(8)
	v_max_f32_e64 v153, |v146|, |v146|
	v_max_f32_e32 v35, v35, v153
	v_max3_f32 v33, v33, v34, v35
	s_waitcnt vmcnt(7)
	v_max_f32_e64 v34, |v148|, |v148|
	s_waitcnt vmcnt(6)
	v_max_f32_e64 v35, |v150|, |v150|
	v_max_f32_e32 v34, v34, v35
	s_waitcnt vmcnt(5)
	v_max_f32_e64 v35, |v151|, |v151|
	s_waitcnt vmcnt(4)
	v_max_f32_e64 v153, |v152|, |v152|
	v_max_f32_e32 v35, v35, v153
	v_max3_f32 v33, v33, v34, v35
	s_waitcnt vmcnt(3)
	v_max_f32_e64 v34, |v147|, |v147|
	s_waitcnt vmcnt(2)
	v_max_f32_e64 v35, |v149|, |v149|
	v_max_f32_e32 v34, v34, v35
	s_waitcnt vmcnt(1)
	v_max_f32_e64 v35, |v106|, |v106|
	s_waitcnt vmcnt(0)
	v_max_f32_e64 v153, |v107|, |v107|
	v_max_f32_e32 v35, v35, v153
	v_max3_f32 v33, v33, v34, v35
	v_cndmask_b32_e32 v34, v53, v54, vcc
	v_lshlrev_b32_e32 v34, 2, v34
	ds_bpermute_b32 v34, v34, v33
	s_and_saveexec_b64 s[28:29], s[2:3]
	s_cbranch_execz .LBB0_43
	s_add_i32 s46, s12, s34
	s_waitcnt lgkmcnt(0)
	v_max_f32_e32 v34, v34, v34
	v_max_f32_e32 v33, v33, v33
	v_lshl_add_u32 v35, v182, 2, s46
	v_max_f32_e32 v33, v33, v34
	ds_write_b32 v35, v33

.LBB0_53:
	v_add_u32_e32 v33, s43, v50
	v_add_u32_e32 v2, 0xfffe5000, v33
	s_mov_b32 s12, s54
	v_add_u32_e32 v5, 0x5000, v33
	buffer_load_dword v2, v2, s[12:15], 0 offen nt
	buffer_load_dword v4, v5, s[12:15], 0 offen nt
	v_add_u32_e32 v6, 0x20000, v5
	buffer_load_dword v5, v6, s[12:15], 0 offen nt
	v_add_u32_e32 v7, 0x20000, v6
	buffer_load_dword v6, v7, s[12:15], 0 offen nt
	v_add_u32_e32 v8, 0x20000, v7
	buffer_load_dword v7, v8, s[12:15], 0 offen nt
	v_add_u32_e32 v9, 0x20000, v8
	buffer_load_dword v8, v9, s[12:15], 0 offen nt
	v_add_u32_e32 v10, 0x20000, v9
	buffer_load_dword v9, v10, s[12:15], 0 offen nt
	v_add_u32_e32 v11, 0x20000, v10
	buffer_load_dword v10, v11, s[12:15], 0 offen nt
	v_add_u32_e32 v12, 0x20000, v11
	buffer_load_dword v11, v12, s[12:15], 0 offen nt
	v_add_u32_e32 v13, 0x20000, v12
	buffer_load_dword v12, v13, s[12:15], 0 offen nt
	v_add_u32_e32 v14, 0x20000, v13
	buffer_load_dword v13, v14, s[12:15], 0 offen nt
	v_add_u32_e32 v15, 0x20000, v14
	buffer_load_dword v14, v15, s[12:15], 0 offen nt
	v_add_u32_e32 v16, 0x20000, v15
	buffer_load_dword v15, v16, s[12:15], 0 offen nt
	v_add_u32_e32 v17, 0x20000, v16
	buffer_load_dword v16, v17, s[12:15], 0 offen nt
	v_add_u32_e32 v18, 0x20000, v17
	buffer_load_dword v17, v18, s[12:15], 0 offen nt
	v_add_u32_e32 v19, 0x20000, v18
	buffer_load_dword v18, v19, s[12:15], 0 offen nt
	v_add_u32_e32 v20, 0x20000, v19
	buffer_load_dword v19, v20, s[12:15], 0 offen nt
	v_add_u32_e32 v21, 0x20000, v20
	buffer_load_dword v20, v21, s[12:15], 0 offen nt
	v_add_u32_e32 v22, 0x20000, v21
	buffer_load_dword v21, v22, s[12:15], 0 offen nt
	v_add_u32_e32 v23, 0x20000, v22
	buffer_load_dword v22, v23, s[12:15], 0 offen nt
	v_add_u32_e32 v24, 0x20000, v23
	buffer_load_dword v23, v24, s[12:15], 0 offen nt
	v_add_u32_e32 v25, 0x20000, v24
	buffer_load_dword v24, v25, s[12:15], 0 offen nt
	v_add_u32_e32 v26, 0x20000, v25
	buffer_load_dword v25, v26, s[12:15], 0 offen nt
	v_add_u32_e32 v27, 0x20000, v26
	buffer_load_dword v26, v27, s[12:15], 0 offen nt
	v_add_u32_e32 v28, 0x20000, v27
	buffer_load_dword v27, v28, s[12:15], 0 offen nt
	v_add_u32_e32 v29, 0x20000, v28
	buffer_load_dword v28, v29, s[12:15], 0 offen nt
	v_add_u32_e32 v30, 0x20000, v29
	buffer_load_dword v29, v30, s[12:15], 0 offen nt
	v_add_u32_e32 v31, 0x20000, v30
	buffer_load_dword v30, v31, s[12:15], 0 offen nt
	v_add_u32_e32 v32, 0x20000, v31
	buffer_load_dword v31, v32, s[12:15], 0 offen nt
	v_add_u32_e32 v34, 0x20000, v32
	buffer_load_dword v32, v34, s[12:15], 0 offen nt
	v_add_u32_e32 v34, 0x20000, v34
	buffer_load_dword v121, v34, s[12:15], 0 offen nt
	v_add_u32_e32 v34, 0x20000, v34
	buffer_load_dword v122, v34, s[12:15], 0 offen nt
	v_add_u32_e32 v34, 0x20000, v34
	s_waitcnt vmcnt(30)
	v_max_f32_e64 v35, |v4|, |v4|
	v_max_f32_e64 v34, |v2|, |v2|
	v_max_f32_e32 v34, v34, v35
	s_waitcnt vmcnt(29)
	v_max_f32_e64 v35, |v5|, |v5|
	s_waitcnt vmcnt(28)
	v_max_f32_e64 v36, |v6|, |v6|
	v_max_f32_e32 v35, v35, v36
	v_max3_f32 v34, v34, 0, v35
	s_waitcnt vmcnt(27)
	v_max_f32_e64 v35, |v7|, |v7|
	s_waitcnt vmcnt(26)
	v_max_f32_e64 v36, |v8|, |v8|
	v_max_f32_e32 v35, v35, v36
	s_waitcnt vmcnt(25)
	v_max_f32_e64 v36, |v9|, |v9|
	s_waitcnt vmcnt(24)
	v_max_f32_e64 v37, |v10|, |v10|
	v_max_f32_e32 v36, v36, v37
	v_max3_f32 v34, v34, v35, v36
	s_waitcnt vmcnt(23)
	v_max_f32_e64 v35, |v11|, |v11|
	s_waitcnt vmcnt(22)
	v_max_f32_e64 v36, |v12|, |v12|
	v_max_f32_e32 v35, v35, v36
	s_waitcnt vmcnt(21)
	v_max_f32_e64 v36, |v13|, |v13|
	s_waitcnt vmcnt(20)
	v_max_f32_e64 v37, |v14|, |v14|
	v_max_f32_e32 v36, v36, v37
	v_max3_f32 v34, v34, v35, v36
	s_waitcnt vmcnt(19)
	v_max_f32_e64 v35, |v15|, |v15|
	s_waitcnt vmcnt(18)
	v_max_f32_e64 v36, |v16|, |v16|
	v_max_f32_e32 v35, v35, v36
	v_add_u32_e32 v57, 0x2005000, v33
	s_waitcnt vmcnt(17)
	v_max_f32_e64 v36, |v17|, |v17|
	v_add_u32_e32 v89, 0x4005000, v33
	v_cmp_lt_i32_e32 vcc, v54, v55
	s_waitcnt vmcnt(16)
	v_max_f32_e64 v37, |v18|, |v18|
	v_max_f32_e32 v36, v36, v37
	v_max3_f32 v34, v34, v35, v36
	s_waitcnt vmcnt(15)
	v_max_f32_e64 v35, |v19|, |v19|
	s_add_i32 s4, s4, 0
	s_add_i32 s4, s4, 0x20800
	s_waitcnt vmcnt(14)
	v_max_f32_e64 v36, |v20|, |v20|
	v_max_f32_e32 v35, v35, v36
	s_waitcnt vmcnt(13)
	v_max_f32_e64 v36, |v21|, |v21|
	s_waitcnt vmcnt(12)
	v_max_f32_e64 v37, |v22|, |v22|
	v_max_f32_e32 v36, v36, v37
	v_max3_f32 v34, v34, v35, v36
	s_waitcnt vmcnt(11)
	v_max_f32_e64 v35, |v23|, |v23|
	s_waitcnt vmcnt(10)
	v_max_f32_e64 v36, |v24|, |v24|
	v_max_f32_e32 v35, v35, v36
	v_add_u32_e32 v36, 0x1fe5000, v33
	buffer_load_dword v36, v36, s[12:15], 0 offen nt
	buffer_load_dword v37, v57, s[12:15], 0 offen nt
	v_add_u32_e32 v58, 0x20000, v57
	buffer_load_dword v57, v58, s[12:15], 0 offen nt
	v_add_u32_e32 v59, 0x20000, v58
	buffer_load_dword v58, v59, s[12:15], 0 offen nt
	v_add_u32_e32 v60, 0x20000, v59
	buffer_load_dword v59, v60, s[12:15], 0 offen nt
	v_add_u32_e32 v61, 0x20000, v60
	buffer_load_dword v60, v61, s[12:15], 0 offen nt
	v_add_u32_e32 v62, 0x20000, v61
	buffer_load_dword v61, v62, s[12:15], 0 offen nt
	v_add_u32_e32 v63, 0x20000, v62
	buffer_load_dword v62, v63, s[12:15], 0 offen nt
	v_add_u32_e32 v64, 0x20000, v63
	buffer_load_dword v63, v64, s[12:15], 0 offen nt
	v_add_u32_e32 v65, 0x20000, v64
	buffer_load_dword v64, v65, s[12:15], 0 offen nt
	v_add_u32_e32 v66, 0x20000, v65
	buffer_load_dword v65, v66, s[12:15], 0 offen nt
	v_add_u32_e32 v67, 0x20000, v66
	buffer_load_dword v66, v67, s[12:15], 0 offen nt
	v_add_u32_e32 v68, 0x20000, v67
	buffer_load_dword v67, v68, s[12:15], 0 offen nt
	v_add_u32_e32 v69, 0x20000, v68
	buffer_load_dword v68, v69, s[12:15], 0 offen nt
	v_add_u32_e32 v70, 0x20000, v69
	buffer_load_dword v69, v70, s[12:15], 0 offen nt
	v_add_u32_e32 v71, 0x20000, v70
	buffer_load_dword v70, v71, s[12:15], 0 offen nt
	v_add_u32_e32 v72, 0x20000, v71
	buffer_load_dword v71, v72, s[12:15], 0 offen nt
	v_add_u32_e32 v73, 0x20000, v72
	buffer_load_dword v72, v73, s[12:15], 0 offen nt
	v_add_u32_e32 v74, 0x20000, v73
	buffer_load_dword v73, v74, s[12:15], 0 offen nt
	v_add_u32_e32 v75, 0x20000, v74
	buffer_load_dword v74, v75, s[12:15], 0 offen nt
	v_add_u32_e32 v76, 0x20000, v75
	buffer_load_dword v75, v76, s[12:15], 0 offen nt
	v_add_u32_e32 v77, 0x20000, v76
	buffer_load_dword v76, v77, s[12:15], 0 offen nt
	v_add_u32_e32 v78, 0x20000, v77
	buffer_load_dword v77, v78, s[12:15], 0 offen nt
	v_add_u32_e32 v79, 0x20000, v78
	buffer_load_dword v78, v79, s[12:15], 0 offen nt
	v_add_u32_e32 v80, 0x20000, v79
	buffer_load_dword v79, v80, s[12:15], 0 offen nt
	v_add_u32_e32 v83, 0x20000, v80
	buffer_load_dword v80, v83, s[12:15], 0 offen nt
	s_waitcnt vmcnt(35)
	v_max_f32_e64 v81, |v25|, |v25|
	s_waitcnt vmcnt(34)
	v_max_f32_e64 v82, |v26|, |v26|
	v_max_f32_e32 v81, v81, v82
	v_max3_f32 v34, v34, v35, v81
	s_waitcnt vmcnt(33)
	v_max_f32_e64 v35, |v27|, |v27|
	s_waitcnt vmcnt(32)
	v_max_f32_e64 v81, |v28|, |v28|
	v_max_f32_e32 v35, v35, v81
	s_waitcnt vmcnt(31)
	v_max_f32_e64 v81, |v29|, |v29|
	s_waitcnt vmcnt(30)
	v_max_f32_e64 v82, |v30|, |v30|
	v_max_f32_e32 v81, v81, v82
	v_max3_f32 v34, v34, v35, v81
	s_waitcnt vmcnt(29)
	v_max_f32_e64 v35, |v31|, |v31|
	s_waitcnt vmcnt(28)
	v_max_f32_e64 v81, |v32|, |v32|
	v_max_f32_e32 v35, v35, v81
	s_waitcnt vmcnt(27)
	v_max_f32_e64 v81, |v121|, |v121|
	s_waitcnt vmcnt(26)
	v_max_f32_e64 v82, |v122|, |v122|
	v_max_f32_e32 v81, v81, v82
	v_max3_f32 v34, v34, v35, v81
	v_add_u32_e32 v35, 0x20000, v83
	buffer_load_dword v81, v35, s[12:15], 0 offen nt
	v_add_u32_e32 v35, 0x20000, v35
	buffer_load_dword v82, v35, s[12:15], 0 offen nt
	v_add_u32_e32 v35, 0x20000, v35
	buffer_load_dword v83, v35, s[12:15], 0 offen nt
	v_add_u32_e32 v35, 0x20000, v35
	buffer_load_dword v84, v35, s[12:15], 0 offen nt
	v_add_u32_e32 v35, 0x20000, v35
	buffer_load_dword v85, v35, s[12:15], 0 offen nt
	v_add_u32_e32 v35, 0x20000, v35
	buffer_load_dword v86, v35, s[12:15], 0 offen nt
	v_add_u32_e32 v35, 0x20000, v35
	s_waitcnt vmcnt(30)
	v_max_f32_e64 v87, |v37|, |v37|
	v_max_f32_e64 v35, |v36|, |v36|
	v_max_f32_e32 v35, v35, v87
	s_waitcnt vmcnt(29)
	v_max_f32_e64 v87, |v57|, |v57|
	s_waitcnt vmcnt(28)
	v_max_f32_e64 v88, |v58|, |v58|
	v_max_f32_e32 v87, v87, v88
	v_max3_f32 v34, v34, v35, v87
	s_waitcnt vmcnt(27)
	v_max_f32_e64 v35, |v59|, |v59|
	s_waitcnt vmcnt(26)
	v_max_f32_e64 v87, |v60|, |v60|
	v_max_f32_e32 v35, v35, v87
	s_waitcnt vmcnt(25)
	v_max_f32_e64 v87, |v61|, |v61|
	s_waitcnt vmcnt(24)
	v_max_f32_e64 v88, |v62|, |v62|
	v_max_f32_e32 v87, v87, v88
	v_max3_f32 v34, v34, v35, v87
	s_waitcnt vmcnt(23)
	v_max_f32_e64 v35, |v63|, |v63|
	s_waitcnt vmcnt(22)
	v_max_f32_e64 v87, |v64|, |v64|
	v_max_f32_e32 v35, v35, v87
	s_waitcnt vmcnt(21)
	v_max_f32_e64 v87, |v65|, |v65|
	s_waitcnt vmcnt(20)
	v_max_f32_e64 v88, |v66|, |v66|
	v_max_f32_e32 v87, v87, v88
	v_max3_f32 v34, v34, v35, v87
	s_waitcnt vmcnt(19)
	v_max_f32_e64 v35, |v67|, |v67|
	s_waitcnt vmcnt(18)
	v_max_f32_e64 v87, |v68|, |v68|
	v_max_f32_e32 v35, v35, v87
	s_waitcnt vmcnt(17)
	v_max_f32_e64 v87, |v69|, |v69|
	s_waitcnt vmcnt(16)
	v_max_f32_e64 v88, |v70|, |v70|
	v_max_f32_e32 v87, v87, v88
	v_max3_f32 v34, v34, v35, v87
	s_waitcnt vmcnt(15)
	v_max_f32_e64 v35, |v71|, |v71|
	s_waitcnt vmcnt(14)
	v_max_f32_e64 v87, |v72|, |v72|
	v_max_f32_e32 v35, v35, v87
	s_waitcnt vmcnt(13)
	v_max_f32_e64 v87, |v73|, |v73|
	s_waitcnt vmcnt(12)
	v_max_f32_e64 v88, |v74|, |v74|
	v_max_f32_e32 v87, v87, v88
	v_max3_f32 v34, v34, v35, v87
	s_waitcnt vmcnt(11)
	v_max_f32_e64 v35, |v75|, |v75|
	s_waitcnt vmcnt(10)
	v_max_f32_e64 v87, |v76|, |v76|
	v_max_f32_e32 v35, v35, v87
	s_waitcnt vmcnt(9)
	v_max_f32_e64 v87, |v77|, |v77|
	s_waitcnt vmcnt(8)
	v_max_f32_e64 v88, |v78|, |v78|
	v_max_f32_e32 v87, v87, v88
	v_max3_f32 v34, v34, v35, v87
	s_waitcnt vmcnt(7)
	v_max_f32_e64 v35, |v79|, |v79|
	s_waitcnt vmcnt(6)
	v_max_f32_e64 v87, |v80|, |v80|
	v_max_f32_e32 v35, v35, v87
	v_add_u32_e32 v87, 0x3fe5000, v33
	buffer_load_dword v87, v87, s[12:15], 0 offen nt
	buffer_load_dword v88, v89, s[12:15], 0 offen nt
	v_add_u32_e32 v90, 0x20000, v89
	buffer_load_dword v89, v90, s[12:15], 0 offen nt
	v_add_u32_e32 v91, 0x20000, v90
	buffer_load_dword v90, v91, s[12:15], 0 offen nt
	v_add_u32_e32 v92, 0x20000, v91
	buffer_load_dword v91, v92, s[12:15], 0 offen nt
	v_add_u32_e32 v93, 0x20000, v92
	buffer_load_dword v92, v93, s[12:15], 0 offen nt
	v_add_u32_e32 v94, 0x20000, v93
	buffer_load_dword v93, v94, s[12:15], 0 offen nt
	v_add_u32_e32 v95, 0x20000, v94
	buffer_load_dword v94, v95, s[12:15], 0 offen nt
	v_add_u32_e32 v96, 0x20000, v95
	buffer_load_dword v95, v96, s[12:15], 0 offen nt
	v_add_u32_e32 v97, 0x20000, v96
	buffer_load_dword v96, v97, s[12:15], 0 offen nt
	v_add_u32_e32 v98, 0x20000, v97
	buffer_load_dword v97, v98, s[12:15], 0 offen nt
	v_add_u32_e32 v99, 0x20000, v98
	buffer_load_dword v98, v99, s[12:15], 0 offen nt
	v_add_u32_e32 v100, 0x20000, v99
	buffer_load_dword v99, v100, s[12:15], 0 offen nt
	v_add_u32_e32 v101, 0x20000, v100
	buffer_load_dword v100, v101, s[12:15], 0 offen nt
	v_add_u32_e32 v102, 0x20000, v101
	buffer_load_dword v101, v102, s[12:15], 0 offen nt
	v_add_u32_e32 v102, 0x20000, v102
	buffer_load_dword v103, v102, s[12:15], 0 offen nt
	v_add_u32_e32 v102, 0x20000, v102
	buffer_load_dword v104, v102, s[12:15], 0 offen nt
	v_add_u32_e32 v102, 0x20000, v102
	buffer_load_dword v106, v102, s[12:15], 0 offen nt
	v_add_u32_e32 v102, 0x20000, v102
	buffer_load_dword v107, v102, s[12:15], 0 offen nt
	v_add_u32_e32 v102, 0x20000, v102
	buffer_load_dword v108, v102, s[12:15], 0 offen nt
	s_waitcnt vmcnt(25)
	v_max_f32_e64 v105, |v81|, |v81|
	s_waitcnt vmcnt(24)
	v_max_f32_e64 v111, |v82|, |v82|
	v_max_f32_e32 v105, v105, v111
	v_add_u32_e32 v102, 0x20000, v102
	v_max3_f32 v34, v34, v35, v105
	s_waitcnt vmcnt(23)
	v_max_f32_e64 v35, |v83|, |v83|
	s_waitcnt vmcnt(22)
	v_max_f32_e64 v105, |v84|, |v84|
	v_max_f32_e32 v35, v35, v105
	s_waitcnt vmcnt(21)
	v_max_f32_e64 v105, |v85|, |v85|
	s_waitcnt vmcnt(20)
	v_max_f32_e64 v111, |v86|, |v86|
	buffer_load_dword v109, v102, s[12:15], 0 offen nt
	v_add_u32_e32 v102, 0x20000, v102
	v_max_f32_e32 v105, v105, v111
	v_max3_f32 v34, v34, v35, v105
	v_add_u32_e32 v35, 0x20000, v102
	buffer_load_dword v110, v102, s[12:15], 0 offen nt
	buffer_load_dword v111, v35, s[12:15], 0 offen nt
	v_add_u32_e32 v35, 0x20000, v35
	buffer_load_dword v112, v35, s[12:15], 0 offen nt
	v_add_u32_e32 v35, 0x20000, v35
	buffer_load_dword v113, v35, s[12:15], 0 offen nt
	v_add_u32_e32 v35, 0x20000, v35
	buffer_load_dword v114, v35, s[12:15], 0 offen nt
	v_add_u32_e32 v35, 0x20000, v35
	buffer_load_dword v115, v35, s[12:15], 0 offen nt
	v_add_u32_e32 v35, 0x20000, v35
	buffer_load_dword v116, v35, s[12:15], 0 offen nt
	v_add_u32_e32 v35, 0x20000, v35
	buffer_load_dword v117, v35, s[12:15], 0 offen nt
	v_add_u32_e32 v35, 0x20000, v35
	buffer_load_dword v118, v35, s[12:15], 0 offen nt
	v_add_u32_e32 v35, 0x20000, v35
	buffer_load_dword v119, v35, s[12:15], 0 offen nt
	v_add_u32_e32 v35, 0x20000, v35
	buffer_load_dword v120, v35, s[12:15], 0 offen nt
	v_add_u32_e32 v35, 0x20000, v35
	s_waitcnt vmcnt(30)
	v_max_f32_e64 v102, |v88|, |v88|
	v_max_f32_e64 v35, |v87|, |v87|
	v_max_f32_e32 v35, v35, v102
	s_waitcnt vmcnt(29)
	v_max_f32_e64 v102, |v89|, |v89|
	s_waitcnt vmcnt(28)
	v_max_f32_e64 v105, |v90|, |v90|
	v_max_f32_e32 v102, v102, v105
	v_max3_f32 v34, v34, v35, v102
	s_waitcnt vmcnt(27)
	v_max_f32_e64 v35, |v91|, |v91|
	s_waitcnt vmcnt(26)
	v_max_f32_e64 v102, |v92|, |v92|
	v_max_f32_e32 v35, v35, v102
	s_waitcnt vmcnt(25)
	v_max_f32_e64 v102, |v93|, |v93|
	s_waitcnt vmcnt(24)
	v_max_f32_e64 v105, |v94|, |v94|
	v_max_f32_e32 v102, v102, v105
	v_max3_f32 v34, v34, v35, v102
	s_waitcnt vmcnt(23)
	v_max_f32_e64 v35, |v95|, |v95|
	s_waitcnt vmcnt(22)
	v_max_f32_e64 v102, |v96|, |v96|
	v_max_f32_e32 v35, v35, v102
	s_waitcnt vmcnt(21)
	v_max_f32_e64 v102, |v97|, |v97|
	s_waitcnt vmcnt(20)
	v_max_f32_e64 v105, |v98|, |v98|
	v_max_f32_e32 v102, v102, v105
	v_max3_f32 v34, v34, v35, v102
	s_waitcnt vmcnt(19)
	v_max_f32_e64 v35, |v99|, |v99|
	s_waitcnt vmcnt(18)
	v_max_f32_e64 v102, |v100|, |v100|
	v_max_f32_e32 v35, v35, v102
	s_waitcnt vmcnt(17)
	v_max_f32_e64 v102, |v101|, |v101|
	s_waitcnt vmcnt(16)
	v_max_f32_e64 v105, |v103|, |v103|
	v_max_f32_e32 v102, v102, v105
	v_max3_f32 v34, v34, v35, v102
	s_waitcnt vmcnt(15)
	v_max_f32_e64 v35, |v104|, |v104|
	s_waitcnt vmcnt(14)
	v_max_f32_e64 v102, |v106|, |v106|
	v_max_f32_e32 v35, v35, v102
	s_waitcnt vmcnt(13)
	v_max_f32_e64 v102, |v107|, |v107|
	s_waitcnt vmcnt(12)
	v_max_f32_e64 v105, |v108|, |v108|
	v_max_f32_e32 v102, v102, v105
	v_add_u32_e32 v105, 0x5fe5000, v33
	buffer_load_dword v123, v105, s[12:15], 0 offen nt
	v_add_u32_e32 v105, 0x6005000, v33
	buffer_load_dword v124, v105, s[12:15], 0 offen nt
	v_add_u32_e32 v105, 0x20000, v105
	buffer_load_dword v125, v105, s[12:15], 0 offen nt
	v_add_u32_e32 v105, 0x20000, v105
	buffer_load_dword v126, v105, s[12:15], 0 offen nt
	v_add_u32_e32 v105, 0x20000, v105
	buffer_load_dword v127, v105, s[12:15], 0 offen nt
	v_add_u32_e32 v105, 0x20000, v105
	buffer_load_dword v128, v105, s[12:15], 0 offen nt
	v_add_u32_e32 v105, 0x20000, v105
	buffer_load_dword v129, v105, s[12:15], 0 offen nt
	v_add_u32_e32 v105, 0x20000, v105
	buffer_load_dword v130, v105, s[12:15], 0 offen nt
	v_add_u32_e32 v105, 0x20000, v105
	buffer_load_dword v131, v105, s[12:15], 0 offen nt
	v_add_u32_e32 v105, 0x20000, v105
	buffer_load_dword v132, v105, s[12:15], 0 offen nt
	v_add_u32_e32 v105, 0x20000, v105
	buffer_load_dword v133, v105, s[12:15], 0 offen nt
	v_add_u32_e32 v105, 0x20000, v105
	buffer_load_dword v134, v105, s[12:15], 0 offen nt
	v_add_u32_e32 v105, 0x20000, v105
	buffer_load_dword v135, v105, s[12:15], 0 offen nt
	v_add_u32_e32 v105, 0x20000, v105
	buffer_load_dword v136, v105, s[12:15], 0 offen nt
	v_add_u32_e32 v105, 0x20000, v105
	buffer_load_dword v137, v105, s[12:15], 0 offen nt
	v_add_u32_e32 v105, 0x20000, v105
	buffer_load_dword v138, v105, s[12:15], 0 offen nt
	v_add_u32_e32 v105, 0x20000, v105
	buffer_load_dword v139, v105, s[12:15], 0 offen nt
	v_add_u32_e32 v105, 0x20000, v105
	buffer_load_dword v141, v105, s[12:15], 0 offen nt
	v_add_u32_e32 v105, 0x20000, v105
	buffer_load_dword v143, v105, s[12:15], 0 offen nt
	v_add_u32_e32 v105, 0x20000, v105
	buffer_load_dword v144, v105, s[12:15], 0 offen nt
	v_add_u32_e32 v105, 0x20000, v105
	buffer_load_dword v145, v105, s[12:15], 0 offen nt
	v_add_u32_e32 v105, 0x20000, v105
	buffer_load_dword v146, v105, s[12:15], 0 offen nt
	v_add_u32_e32 v105, 0x20000, v105
	buffer_load_dword v147, v105, s[12:15], 0 offen nt
	v_add_u32_e32 v105, 0x20000, v105
	buffer_load_dword v148, v105, s[12:15], 0 offen nt
	v_add_u32_e32 v105, 0x20000, v105
	buffer_load_dword v149, v105, s[12:15], 0 offen nt
	v_add_u32_e32 v105, 0x20000, v105
	buffer_load_dword v150, v105, s[12:15], 0 offen nt
	v_add_u32_e32 v105, 0x20000, v105
	buffer_load_dword v151, v105, s[12:15], 0 offen nt
	v_add_u32_e32 v105, 0x20000, v105
	buffer_load_dword v152, v105, s[12:15], 0 offen nt
	v_max3_f32 v34, v34, v35, v102
	s_waitcnt vmcnt(39)
	v_max_f32_e64 v35, |v109|, |v109|
	s_waitcnt vmcnt(38)
	v_max_f32_e64 v102, |v110|, |v110|
	v_max_f32_e32 v35, v35, v102
	s_waitcnt vmcnt(37)
	v_max_f32_e64 v102, |v111|, |v111|
	s_waitcnt vmcnt(36)
	v_max_f32_e64 v140, |v112|, |v112|
	v_max_f32_e32 v102, v102, v140
	v_max3_f32 v34, v34, v35, v102
	s_waitcnt vmcnt(35)
	v_max_f32_e64 v35, |v113|, |v113|
	s_waitcnt vmcnt(34)
	v_max_f32_e64 v102, |v114|, |v114|
	v_max_f32_e32 v35, v35, v102
	s_waitcnt vmcnt(33)
	v_max_f32_e64 v102, |v115|, |v115|
	s_waitcnt vmcnt(32)
	v_max_f32_e64 v140, |v116|, |v116|
	v_max_f32_e32 v102, v102, v140
	v_max3_f32 v34, v34, v35, v102
	s_waitcnt vmcnt(31)
	v_max_f32_e64 v35, |v117|, |v117|
	s_waitcnt vmcnt(30)
	v_max_f32_e64 v102, |v118|, |v118|
	v_max_f32_e32 v35, v35, v102
	s_waitcnt vmcnt(29)
	v_max_f32_e64 v102, |v119|, |v119|
	s_waitcnt vmcnt(28)
	v_max_f32_e64 v140, |v120|, |v120|
	v_max_f32_e32 v102, v102, v140
	v_max3_f32 v34, v34, v35, v102
	v_add_u32_e32 v35, 0x20000, v105
	buffer_load_dword v153, v35, s[12:15], 0 offen nt
	v_add_u32_e32 v35, 0x20000, v35
	buffer_load_dword v154, v35, s[12:15], 0 offen nt
	v_add_u32_e32 v35, 0x20000, v35
	buffer_load_dword v155, v35, s[12:15], 0 offen nt
	v_add_u32_e32 v35, 0x20000, v35
	buffer_load_dword v156, v35, s[12:15], 0 offen nt
	v_add_u32_e32 v35, 0x20000, v35
	s_waitcnt vmcnt(30)
	v_max_f32_e64 v102, |v124|, |v124|
	v_max_f32_e64 v35, |v123|, |v123|
	v_max_f32_e32 v35, v35, v102
	s_waitcnt vmcnt(29)
	v_max_f32_e64 v102, |v125|, |v125|
	s_waitcnt vmcnt(28)
	v_max_f32_e64 v105, |v126|, |v126|
	v_max_f32_e32 v102, v102, v105
	v_max3_f32 v34, v34, v35, v102
	s_waitcnt vmcnt(27)
	v_max_f32_e64 v35, |v127|, |v127|
	s_waitcnt vmcnt(26)
	v_max_f32_e64 v102, |v128|, |v128|
	v_max_f32_e32 v35, v35, v102
	s_waitcnt vmcnt(25)
	v_max_f32_e64 v102, |v129|, |v129|
	s_waitcnt vmcnt(24)
	v_max_f32_e64 v105, |v130|, |v130|
	v_max_f32_e32 v102, v102, v105
	v_max3_f32 v34, v34, v35, v102
	s_waitcnt vmcnt(23)
	v_max_f32_e64 v35, |v131|, |v131|
	s_waitcnt vmcnt(22)
	v_max_f32_e64 v102, |v132|, |v132|
	v_max_f32_e32 v35, v35, v102
	s_waitcnt vmcnt(21)
	v_max_f32_e64 v102, |v133|, |v133|
	s_waitcnt vmcnt(20)
	v_max_f32_e64 v105, |v134|, |v134|
	v_max_f32_e32 v102, v102, v105
	v_max3_f32 v34, v34, v35, v102
	s_waitcnt vmcnt(19)
	v_max_f32_e64 v35, |v135|, |v135|
	s_waitcnt vmcnt(18)
	v_max_f32_e64 v102, |v136|, |v136|
	v_max_f32_e32 v35, v35, v102
	s_waitcnt vmcnt(17)
	v_max_f32_e64 v102, |v137|, |v137|
	s_waitcnt vmcnt(16)
	v_max_f32_e64 v105, |v138|, |v138|
	v_max_f32_e32 v102, v102, v105
	v_max3_f32 v34, v34, v35, v102
	s_waitcnt vmcnt(15)
	v_max_f32_e64 v35, |v139|, |v139|
	s_waitcnt vmcnt(14)
	v_max_f32_e64 v102, |v141|, |v141|
	v_max_f32_e32 v35, v35, v102
	s_waitcnt vmcnt(13)
	v_max_f32_e64 v102, |v143|, |v143|
	s_waitcnt vmcnt(12)
	v_max_f32_e64 v105, |v144|, |v144|
	v_max_f32_e32 v102, v102, v105
	v_max3_f32 v34, v34, v35, v102
	s_waitcnt vmcnt(11)
	v_max_f32_e64 v35, |v145|, |v145|
	s_waitcnt vmcnt(10)
	v_max_f32_e64 v102, |v146|, |v146|
	v_max_f32_e32 v35, v35, v102
	s_waitcnt vmcnt(9)
	v_max_f32_e64 v102, |v147|, |v147|
	s_waitcnt vmcnt(8)
	v_max_f32_e64 v105, |v148|, |v148|
	v_max_f32_e32 v102, v102, v105
	v_max3_f32 v34, v34, v35, v102
	s_waitcnt vmcnt(7)
	v_max_f32_e64 v35, |v149|, |v149|
	s_waitcnt vmcnt(6)
	v_max_f32_e64 v102, |v150|, |v150|
	v_max_f32_e32 v35, v35, v102
	s_waitcnt vmcnt(5)
	v_max_f32_e64 v102, |v151|, |v151|
	s_waitcnt vmcnt(4)
	v_max_f32_e64 v105, |v152|, |v152|
	v_max_f32_e32 v102, v102, v105
	v_max3_f32 v34, v34, v35, v102
	v_add_u32_e32 v35, 0x7fe5000, v33
	buffer_load_dword v157, v35, s[12:15], 0 offen nt
	v_add_u32_e32 v35, 0x8005000, v33
	buffer_load_dword v158, v35, s[12:15], 0 offen nt
	v_add_u32_e32 v35, 0x20000, v35
	buffer_load_dword v159, v35, s[12:15], 0 offen nt
	v_add_u32_e32 v35, 0x20000, v35
	buffer_load_dword v160, v35, s[12:15], 0 offen nt
	v_add_u32_e32 v35, 0x20000, v35
	buffer_load_dword v161, v35, s[12:15], 0 offen nt
	v_add_u32_e32 v35, 0x20000, v35
	buffer_load_dword v162, v35, s[12:15], 0 offen nt
	v_add_u32_e32 v35, 0x20000, v35
	buffer_load_dword v163, v35, s[12:15], 0 offen nt
	v_add_u32_e32 v35, 0x20000, v35
	buffer_load_dword v164, v35, s[12:15], 0 offen nt
	v_add_u32_e32 v35, 0x20000, v35
	buffer_load_dword v165, v35, s[12:15], 0 offen nt
	v_add_u32_e32 v35, 0x20000, v35
	buffer_load_dword v166, v35, s[12:15], 0 offen nt
	v_add_u32_e32 v35, 0x20000, v35
	buffer_load_dword v167, v35, s[12:15], 0 offen nt
	v_add_u32_e32 v35, 0x20000, v35
	buffer_load_dword v168, v35, s[12:15], 0 offen nt
	v_add_u32_e32 v35, 0x20000, v35
	buffer_load_dword v169, v35, s[12:15], 0 offen nt
	v_add_u32_e32 v35, 0x20000, v35
	buffer_load_dword v170, v35, s[12:15], 0 offen nt
	v_add_u32_e32 v35, 0x20000, v35
	buffer_load_dword v171, v35, s[12:15], 0 offen nt
	v_add_u32_e32 v35, 0x20000, v35
	buffer_load_dword v172, v35, s[12:15], 0 offen nt
	v_add_u32_e32 v35, 0x20000, v35
	buffer_load_dword v174, v35, s[12:15], 0 offen nt
	v_add_u32_e32 v35, 0x20000, v35
	buffer_load_dword v176, v35, s[12:15], 0 offen nt
	v_add_u32_e32 v35, 0x20000, v35
	buffer_load_dword v177, v35, s[12:15], 0 offen nt
	v_add_u32_e32 v35, 0x20000, v35
	buffer_load_dword v178, v35, s[12:15], 0 offen nt
	v_add_u32_e32 v35, 0x20000, v35
	buffer_load_dword v179, v35, s[12:15], 0 offen nt
	v_add_u32_e32 v35, 0x20000, v35
	buffer_load_dword v180, v35, s[12:15], 0 offen nt
	v_add_u32_e32 v35, 0x20000, v35
	buffer_load_dword v181, v35, s[12:15], 0 offen nt
	v_add_u32_e32 v35, 0x20000, v35
	buffer_load_dword v183, v35, s[12:15], 0 offen nt
	v_add_u32_e32 v35, 0x20000, v35
	buffer_load_dword v184, v35, s[12:15], 0 offen nt
	v_add_u32_e32 v35, 0x20000, v35
	buffer_load_dword v185, v35, s[12:15], 0 offen nt
	v_add_u32_e32 v35, 0x20000, v35
	buffer_load_dword v186, v35, s[12:15], 0 offen nt
	v_add_u32_e32 v35, 0x20000, v35
	buffer_load_dword v187, v35, s[12:15], 0 offen nt
	v_add_u32_e32 v35, 0x20000, v35
	buffer_load_dword v188, v35, s[12:15], 0 offen nt
	v_add_u32_e32 v35, 0x20000, v35
	buffer_load_dword v189, v35, s[12:15], 0 offen nt
	v_add_u32_e32 v35, 0x20000, v35
	buffer_load_dword v190, v35, s[12:15], 0 offen nt
	v_add_u32_e32 v35, 0x20000, v35
	s_waitcnt vmcnt(34)
	v_max_f32_e64 v102, |v153|, |v153|
	s_waitcnt vmcnt(33)
	v_max_f32_e64 v105, |v154|, |v154|
	v_max_f32_e32 v102, v102, v105
	s_waitcnt vmcnt(32)
	v_max_f32_e64 v105, |v155|, |v155|
	s_waitcnt vmcnt(31)
	v_max_f32_e64 v140, |v156|, |v156|
	buffer_load_dword v191, v35, s[12:15], 0 offen nt
	v_add_u32_e32 v35, 0x20000, v35
	v_max_f32_e32 v105, v105, v140
	v_max3_f32 v34, v34, v102, v105
	s_waitcnt vmcnt(31)
	v_max_f32_e64 v35, |v157|, |v157|
	s_waitcnt vmcnt(30)
	v_max_f32_e64 v102, |v158|, |v158|
	v_max_f32_e32 v35, v35, v102
	s_waitcnt vmcnt(29)
	v_max_f32_e64 v102, |v159|, |v159|
	s_waitcnt vmcnt(28)
	v_max_f32_e64 v105, |v160|, |v160|
	v_max_f32_e32 v102, v102, v105
	v_max3_f32 v34, v34, v35, v102
	s_waitcnt vmcnt(27)
	v_max_f32_e64 v35, |v161|, |v161|
	s_waitcnt vmcnt(26)
	v_max_f32_e64 v102, |v162|, |v162|
	v_max_f32_e32 v35, v35, v102
	s_waitcnt vmcnt(25)
	v_max_f32_e64 v102, |v163|, |v163|
	s_waitcnt vmcnt(24)
	v_max_f32_e64 v105, |v164|, |v164|
	v_max_f32_e32 v102, v102, v105
	v_max3_f32 v34, v34, v35, v102
	s_waitcnt vmcnt(23)
	v_max_f32_e64 v35, |v165|, |v165|
	s_waitcnt vmcnt(22)
	v_max_f32_e64 v102, |v166|, |v166|
	v_max_f32_e32 v35, v35, v102
	s_waitcnt vmcnt(21)
	v_max_f32_e64 v102, |v167|, |v167|
	s_waitcnt vmcnt(20)
	v_max_f32_e64 v105, |v168|, |v168|
	v_max_f32_e32 v102, v102, v105
	v_max3_f32 v34, v34, v35, v102
	s_waitcnt vmcnt(19)
	v_max_f32_e64 v35, |v169|, |v169|
	s_waitcnt vmcnt(18)
	v_max_f32_e64 v102, |v170|, |v170|
	v_max_f32_e32 v35, v35, v102
	s_waitcnt vmcnt(17)
	v_max_f32_e64 v102, |v171|, |v171|
	s_waitcnt vmcnt(16)
	v_max_f32_e64 v105, |v172|, |v172|
	v_max_f32_e32 v102, v102, v105
	v_max3_f32 v34, v34, v35, v102
	s_waitcnt vmcnt(15)
	v_max_f32_e64 v35, |v174|, |v174|
	s_waitcnt vmcnt(14)
	v_max_f32_e64 v102, |v176|, |v176|
	v_max_f32_e32 v35, v35, v102
	v_add_u32_e32 v102, 0x9fe5000, v33
	buffer_load_dword v192, v102, s[12:15], 0 offen nt
	v_add_u32_e32 v102, 0xa005000, v33
	buffer_load_dword v193, v102, s[12:15], 0 offen nt
	v_add_u32_e32 v102, 0x20000, v102
	buffer_load_dword v194, v102, s[12:15], 0 offen nt
	v_add_u32_e32 v102, 0x20000, v102
	buffer_load_dword v195, v102, s[12:15], 0 offen nt
	v_add_u32_e32 v102, 0x20000, v102
	buffer_load_dword v196, v102, s[12:15], 0 offen nt
	v_add_u32_e32 v102, 0x20000, v102
	buffer_load_dword v197, v102, s[12:15], 0 offen nt
	v_add_u32_e32 v102, 0x20000, v102
	buffer_load_dword v198, v102, s[12:15], 0 offen nt
	v_add_u32_e32 v102, 0x20000, v102
	buffer_load_dword v199, v102, s[12:15], 0 offen nt
	v_add_u32_e32 v102, 0x20000, v102
	buffer_load_dword v200, v102, s[12:15], 0 offen nt
	v_add_u32_e32 v102, 0x20000, v102
	buffer_load_dword v201, v102, s[12:15], 0 offen nt
	v_add_u32_e32 v102, 0x20000, v102
	buffer_load_dword v202, v102, s[12:15], 0 offen nt
	v_add_u32_e32 v102, 0x20000, v102
	buffer_load_dword v203, v102, s[12:15], 0 offen nt
	v_add_u32_e32 v102, 0x20000, v102
	buffer_load_dword v204, v102, s[12:15], 0 offen nt
	v_add_u32_e32 v102, 0x20000, v102
	buffer_load_dword v205, v102, s[12:15], 0 offen nt
	v_add_u32_e32 v102, 0x20000, v102
	buffer_load_dword v206, v102, s[12:15], 0 offen nt
	v_add_u32_e32 v102, 0x20000, v102
	buffer_load_dword v207, v102, s[12:15], 0 offen nt
	v_add_u32_e32 v102, 0x20000, v102
	buffer_load_dword v208, v102, s[12:15], 0 offen nt
	v_add_u32_e32 v102, 0x20000, v102
	buffer_load_dword v209, v102, s[12:15], 0 offen nt
	v_add_u32_e32 v102, 0x20000, v102
	buffer_load_dword v210, v102, s[12:15], 0 offen nt
	v_add_u32_e32 v102, 0x20000, v102
	buffer_load_dword v211, v102, s[12:15], 0 offen nt
	v_add_u32_e32 v102, 0x20000, v102
	buffer_load_dword v213, v102, s[12:15], 0 offen nt
	v_add_u32_e32 v102, 0x20000, v102
	buffer_load_dword v215, v102, s[12:15], 0 offen nt
	v_add_u32_e32 v102, 0x20000, v102
	buffer_load_dword v216, v102, s[12:15], 0 offen nt
	v_add_u32_e32 v102, 0x20000, v102
	buffer_load_dword v217, v102, s[12:15], 0 offen nt
	v_add_u32_e32 v102, 0x20000, v102
	buffer_load_dword v212, v102, s[12:15], 0 offen nt
	v_add_u32_e32 v102, 0x20000, v102
	buffer_load_dword v214, v102, s[12:15], 0 offen nt
	v_add_u32_e32 v102, 0x20000, v102
	buffer_load_dword v173, v102, s[12:15], 0 offen nt
	v_add_u32_e32 v102, 0x20000, v102
	buffer_load_dword v175, v102, s[12:15], 0 offen nt
	v_add_u32_e32 v102, 0x20000, v102
	buffer_load_dword v140, v102, s[12:15], 0 offen nt
	v_add_u32_e32 v102, 0x20000, v102
	buffer_load_dword v142, v102, s[12:15], 0 offen nt
	v_add_u32_e32 v105, 0x20000, v102
	buffer_load_dword v102, v105, s[12:15], 0 offen nt
	v_add_u32_e32 v219, 0x20000, v105
	buffer_load_dword v105, v219, s[12:15], 0 offen nt
	s_waitcnt vmcnt(45)
	v_max_f32_e64 v218, |v177|, |v177|
	s_waitcnt vmcnt(44)
	v_max_f32_e64 v220, |v178|, |v178|
	v_max_f32_e32 v218, v218, v220
	v_max3_f32 v34, v34, v35, v218
	s_waitcnt vmcnt(43)
	v_max_f32_e64 v35, |v179|, |v179|
	s_waitcnt vmcnt(42)
	v_max_f32_e64 v218, |v180|, |v180|
	v_max_f32_e32 v35, v35, v218
	s_waitcnt vmcnt(41)
	v_max_f32_e64 v218, |v181|, |v181|
	s_waitcnt vmcnt(40)
	v_max_f32_e64 v220, |v183|, |v183|
	v_max_f32_e32 v218, v218, v220
	v_max3_f32 v34, v34, v35, v218
	s_waitcnt vmcnt(39)
	v_max_f32_e64 v35, |v184|, |v184|
	s_waitcnt vmcnt(38)
	v_max_f32_e64 v218, |v185|, |v185|
	v_max_f32_e32 v35, v35, v218
	s_waitcnt vmcnt(37)
	v_max_f32_e64 v218, |v186|, |v186|
	s_waitcnt vmcnt(36)
	v_max_f32_e64 v220, |v187|, |v187|
	v_max_f32_e32 v218, v218, v220
	v_max3_f32 v34, v34, v35, v218
	s_waitcnt vmcnt(35)
	v_max_f32_e64 v35, |v188|, |v188|
	s_waitcnt vmcnt(34)
	v_max_f32_e64 v218, |v189|, |v189|
	v_max_f32_e32 v35, v35, v218
	s_waitcnt vmcnt(33)
	v_max_f32_e64 v218, |v190|, |v190|
	s_waitcnt vmcnt(32)
	v_max_f32_e64 v220, |v191|, |v191|
	v_max_f32_e32 v218, v218, v220
	v_max3_f32 v34, v34, v35, v218
	v_add_u32_e32 v35, 0x20000, v219
	s_waitcnt vmcnt(30)
	v_max_f32_e64 v218, |v193|, |v193|
	v_max_f32_e64 v35, |v192|, |v192|
	v_max_f32_e32 v35, v35, v218
	s_waitcnt vmcnt(29)
	v_max_f32_e64 v218, |v194|, |v194|
	s_waitcnt vmcnt(28)
	v_max_f32_e64 v219, |v195|, |v195|
	v_max_f32_e32 v218, v218, v219
	v_max3_f32 v34, v34, v35, v218
	s_waitcnt vmcnt(27)
	v_max_f32_e64 v35, |v196|, |v196|
	s_waitcnt vmcnt(26)
	v_max_f32_e64 v218, |v197|, |v197|
	v_max_f32_e32 v35, v35, v218
	s_waitcnt vmcnt(25)
	v_max_f32_e64 v218, |v198|, |v198|
	s_waitcnt vmcnt(24)
	v_max_f32_e64 v219, |v199|, |v199|
	v_max_f32_e32 v218, v218, v219
	v_max3_f32 v34, v34, v35, v218
	s_waitcnt vmcnt(23)
	v_max_f32_e64 v35, |v200|, |v200|
	s_waitcnt vmcnt(22)
	v_max_f32_e64 v218, |v201|, |v201|
	v_max_f32_e32 v35, v35, v218
	s_waitcnt vmcnt(21)
	v_max_f32_e64 v218, |v202|, |v202|
	s_waitcnt vmcnt(20)
	v_max_f32_e64 v219, |v203|, |v203|
	v_max_f32_e32 v218, v218, v219
	v_max3_f32 v34, v34, v35, v218
	s_waitcnt vmcnt(19)
	v_max_f32_e64 v35, |v204|, |v204|
	s_waitcnt vmcnt(18)
	v_max_f32_e64 v218, |v205|, |v205|
	v_max_f32_e32 v35, v35, v218
	s_waitcnt vmcnt(17)
	v_max_f32_e64 v218, |v206|, |v206|
	s_waitcnt vmcnt(16)
	v_max_f32_e64 v219, |v207|, |v207|
	v_max_f32_e32 v218, v218, v219
	v_max3_f32 v34, v34, v35, v218
	s_waitcnt vmcnt(15)
	v_max_f32_e64 v35, |v208|, |v208|
	s_waitcnt vmcnt(14)
	v_max_f32_e64 v218, |v209|, |v209|
	v_max_f32_e32 v35, v35, v218
	s_waitcnt vmcnt(13)
	v_max_f32_e64 v218, |v210|, |v210|
	s_waitcnt vmcnt(12)
	v_max_f32_e64 v219, |v211|, |v211|
	v_max_f32_e32 v218, v218, v219
	v_max3_f32 v34, v34, v35, v218
	s_waitcnt vmcnt(11)
	v_max_f32_e64 v35, |v213|, |v213|
	s_waitcnt vmcnt(10)
	v_max_f32_e64 v218, |v215|, |v215|
	v_max_f32_e32 v35, v35, v218
	s_waitcnt vmcnt(9)
	v_max_f32_e64 v218, |v216|, |v216|
	s_waitcnt vmcnt(8)
	v_max_f32_e64 v219, |v217|, |v217|
	v_max_f32_e32 v218, v218, v219
	v_max3_f32 v34, v34, v35, v218
	s_waitcnt vmcnt(7)
	v_max_f32_e64 v35, |v212|, |v212|
	s_waitcnt vmcnt(6)
	v_max_f32_e64 v218, |v214|, |v214|
	v_max_f32_e32 v35, v35, v218
	s_waitcnt vmcnt(5)
	v_max_f32_e64 v218, |v173|, |v173|
	s_waitcnt vmcnt(4)
	v_max_f32_e64 v219, |v175|, |v175|
	v_max_f32_e32 v218, v218, v219
	v_max3_f32 v34, v34, v35, v218
	s_waitcnt vmcnt(3)
	v_max_f32_e64 v35, |v140|, |v140|
	s_waitcnt vmcnt(2)
	v_max_f32_e64 v218, |v142|, |v142|
	v_max_f32_e32 v35, v35, v218
	s_waitcnt vmcnt(1)
	v_max_f32_e64 v218, |v102|, |v102|
	s_waitcnt vmcnt(0)
	v_max_f32_e64 v219, |v105|, |v105|
	v_max_f32_e32 v218, v218, v219
	v_max3_f32 v34, v34, v35, v218
	v_add_u32_e32 v35, 0xbfe5000, v33
	v_add_u32_e32 v218, 0xc005000, v33
	buffer_load_dword v35, v35, s[12:15], 0 offen nt
	buffer_load_dword v219, v218, s[12:15], 0 offen nt
	v_add_u32_e32 v218, 0x20000, v218
	buffer_load_dword v220, v218, s[12:15], 0 offen nt
	v_add_u32_e32 v218, 0x20000, v218
	buffer_load_dword v221, v218, s[12:15], 0 offen nt
	v_add_u32_e32 v218, 0x20000, v218
	buffer_load_dword v222, v218, s[12:15], 0 offen nt
	v_add_u32_e32 v218, 0x20000, v218
	buffer_load_dword v223, v218, s[12:15], 0 offen nt
	v_add_u32_e32 v218, 0x20000, v218
	buffer_load_dword v224, v218, s[12:15], 0 offen nt
	v_add_u32_e32 v218, 0x20000, v218
	buffer_load_dword v225, v218, s[12:15], 0 offen nt
	v_add_u32_e32 v218, 0x20000, v218
	buffer_load_dword v226, v218, s[12:15], 0 offen nt
	v_add_u32_e32 v218, 0x20000, v218
	buffer_load_dword v227, v218, s[12:15], 0 offen nt
	v_add_u32_e32 v218, 0x20000, v218
	buffer_load_dword v228, v218, s[12:15], 0 offen nt
	v_add_u32_e32 v218, 0x20000, v218
	buffer_load_dword v229, v218, s[12:15], 0 offen nt
	v_add_u32_e32 v218, 0x20000, v218
	buffer_load_dword v230, v218, s[12:15], 0 offen nt
	v_add_u32_e32 v218, 0x20000, v218
	buffer_load_dword v231, v218, s[12:15], 0 offen nt
	v_add_u32_e32 v218, 0x20000, v218
	buffer_load_dword v232, v218, s[12:15], 0 offen nt
	v_add_u32_e32 v218, 0x20000, v218
	buffer_load_dword v233, v218, s[12:15], 0 offen nt
	v_add_u32_e32 v218, 0x20000, v218
	buffer_load_dword v234, v218, s[12:15], 0 offen nt
	v_add_u32_e32 v218, 0x20000, v218
	buffer_load_dword v235, v218, s[12:15], 0 offen nt
	v_add_u32_e32 v218, 0x20000, v218
	buffer_load_dword v236, v218, s[12:15], 0 offen nt
	v_add_u32_e32 v218, 0x20000, v218
	buffer_load_dword v237, v218, s[12:15], 0 offen nt
	v_add_u32_e32 v218, 0x20000, v218
	buffer_load_dword v238, v218, s[12:15], 0 offen nt
	v_add_u32_e32 v218, 0x20000, v218
	buffer_load_dword v239, v218, s[12:15], 0 offen nt
	v_add_u32_e32 v218, 0x20000, v218
	buffer_load_dword v240, v218, s[12:15], 0 offen nt
	v_add_u32_e32 v218, 0x20000, v218
	buffer_load_dword v241, v218, s[12:15], 0 offen nt
	v_add_u32_e32 v218, 0x20000, v218
	buffer_load_dword v242, v218, s[12:15], 0 offen nt
	v_add_u32_e32 v218, 0x20000, v218
	buffer_load_dword v243, v218, s[12:15], 0 offen nt
	v_add_u32_e32 v218, 0x20000, v218
	buffer_load_dword v244, v218, s[12:15], 0 offen nt
	v_add_u32_e32 v218, 0x20000, v218
	buffer_load_dword v245, v218, s[12:15], 0 offen nt
	v_add_u32_e32 v218, 0x20000, v218
	buffer_load_dword v246, v218, s[12:15], 0 offen nt
	v_add_u32_e32 v218, 0x20000, v218
	buffer_load_dword v247, v218, s[12:15], 0 offen nt
	v_add_u32_e32 v218, 0x20000, v218
	buffer_load_dword v248, v218, s[12:15], 0 offen nt
	v_add_u32_e32 v218, 0x20000, v218
	buffer_load_dword v249, v218, s[12:15], 0 offen nt
	v_add_u32_e32 v218, 0x20000, v218
	s_waitcnt vmcnt(30)
	v_max_f32_e64 v250, |v219|, |v219|
	v_max_f32_e64 v218, |v35|, |v35|
	v_max_f32_e32 v218, v218, v250
	v_cvt_pk_bf16_f32 v35, v35, v219
	s_waitcnt vmcnt(29)
	v_max_f32_e64 v219, |v220|, |v220|
	s_waitcnt vmcnt(28)
	v_max_f32_e64 v250, |v221|, |v221|
	v_max_f32_e32 v219, v219, v250
	v_max3_f32 v34, v34, v218, v219
	v_cvt_pk_bf16_f32 v218, v220, v221
	v_add_u32_e32 v219, 0x1000, v43
	ds_write2_b32 v219, v35, v218 offset0:32 offset1:98
	s_waitcnt vmcnt(27)
	v_max_f32_e64 v35, |v222|, |v222|
	s_waitcnt vmcnt(26)
	v_max_f32_e64 v218, |v223|, |v223|
	s_waitcnt vmcnt(25)
	v_max_f32_e64 v220, |v224|, |v224|
	s_waitcnt vmcnt(24)
	v_max_f32_e64 v221, |v225|, |v225|
	v_max_f32_e32 v35, v35, v218
	v_max_f32_e32 v220, v220, v221
	v_cvt_pk_bf16_f32 v218, v222, v223
	v_max3_f32 v34, v34, v35, v220
	v_cvt_pk_bf16_f32 v35, v224, v225
	ds_write2_b32 v219, v218, v35 offset0:164 offset1:230
	s_waitcnt vmcnt(23)
	v_max_f32_e64 v35, |v226|, |v226|
	s_waitcnt vmcnt(22)
	v_max_f32_e64 v218, |v227|, |v227|
	s_waitcnt vmcnt(21)
	v_max_f32_e64 v219, |v228|, |v228|
	s_waitcnt vmcnt(20)
	v_max_f32_e64 v220, |v229|, |v229|
	v_max_f32_e32 v35, v35, v218
	v_max_f32_e32 v219, v219, v220
	v_cvt_pk_bf16_f32 v218, v226, v227
	v_max3_f32 v34, v34, v35, v219
	v_cvt_pk_bf16_f32 v35, v228, v229
	v_add_u32_e32 v219, 0x1400, v43
	ds_write2_b32 v219, v218, v35 offset0:40 offset1:106
	s_waitcnt vmcnt(19)
	v_max_f32_e64 v35, |v230|, |v230|
	s_waitcnt vmcnt(18)
	v_max_f32_e64 v218, |v231|, |v231|
	s_waitcnt vmcnt(17)
	v_max_f32_e64 v220, |v232|, |v232|
	s_waitcnt vmcnt(16)
	v_max_f32_e64 v221, |v233|, |v233|
	v_max_f32_e32 v35, v35, v218
	v_max_f32_e32 v220, v220, v221
	v_cvt_pk_bf16_f32 v218, v230, v231
	v_max3_f32 v34, v34, v35, v220
	v_cvt_pk_bf16_f32 v35, v232, v233
	ds_write2_b32 v219, v218, v35 offset0:172 offset1:238
	s_waitcnt vmcnt(15)
	v_max_f32_e64 v35, |v234|, |v234|
	s_waitcnt vmcnt(14)
	v_max_f32_e64 v218, |v235|, |v235|
	s_waitcnt vmcnt(13)
	v_max_f32_e64 v219, |v236|, |v236|
	s_waitcnt vmcnt(12)
	v_max_f32_e64 v220, |v237|, |v237|
	v_max_f32_e32 v35, v35, v218
	v_max_f32_e32 v219, v219, v220
	v_cvt_pk_bf16_f32 v218, v234, v235
	v_max3_f32 v34, v34, v35, v219
	v_cvt_pk_bf16_f32 v35, v236, v237
	v_add_u32_e32 v219, 0x1800, v43
	ds_write2_b32 v219, v218, v35 offset0:48 offset1:114
	s_waitcnt vmcnt(11)
	v_max_f32_e64 v35, |v238|, |v238|
	s_waitcnt vmcnt(10)
	v_max_f32_e64 v218, |v239|, |v239|
	s_waitcnt vmcnt(9)
	v_max_f32_e64 v220, |v240|, |v240|
	s_waitcnt vmcnt(8)
	v_max_f32_e64 v221, |v241|, |v241|
	v_max_f32_e32 v35, v35, v218
	v_max_f32_e32 v220, v220, v221
	v_cvt_pk_bf16_f32 v218, v238, v239
	v_max3_f32 v34, v34, v35, v220
	v_cvt_pk_bf16_f32 v35, v240, v241
	ds_write2_b32 v219, v218, v35 offset0:180 offset1:246
	s_waitcnt vmcnt(7)
	v_max_f32_e64 v35, |v242|, |v242|
	s_waitcnt vmcnt(6)
	v_max_f32_e64 v218, |v243|, |v243|
	s_waitcnt vmcnt(5)
	v_max_f32_e64 v219, |v244|, |v244|
	s_waitcnt vmcnt(4)
	v_max_f32_e64 v220, |v245|, |v245|
	v_max_f32_e32 v35, v35, v218
	v_max_f32_e32 v219, v219, v220
	v_cvt_pk_bf16_f32 v218, v242, v243
	v_max3_f32 v34, v34, v35, v219
	v_cvt_pk_bf16_f32 v35, v244, v245
	v_add_u32_e32 v219, 0x1c00, v43
	ds_write2_b32 v219, v218, v35 offset0:56 offset1:122
	s_waitcnt vmcnt(3)
	v_max_f32_e64 v35, |v246|, |v246|
	s_waitcnt vmcnt(2)
	v_max_f32_e64 v218, |v247|, |v247|
	s_waitcnt vmcnt(1)
	v_max_f32_e64 v220, |v248|, |v248|
	s_waitcnt vmcnt(0)
	v_max_f32_e64 v221, |v249|, |v249|
	v_max_f32_e32 v35, v35, v218
	v_max_f32_e32 v220, v220, v221
	v_cvt_pk_bf16_f32 v218, v246, v247
	v_max3_f32 v34, v34, v35, v220
	v_cvt_pk_bf16_f32 v35, v248, v249
	ds_write2_b32 v219, v218, v35 offset0:188 offset1:254
	v_add_u32_e32 v35, 0xdfe5000, v33
	v_add_u32_e32 v33, 0xe005000, v33
	buffer_load_dword v35, v35, s[12:15], 0 offen nt
	buffer_load_dword v218, v33, s[12:15], 0 offen nt
	v_add_u32_e32 v33, 0x20000, v33
	buffer_load_dword v219, v33, s[12:15], 0 offen nt
	v_add_u32_e32 v33, 0x20000, v33
	buffer_load_dword v220, v33, s[12:15], 0 offen nt
	v_add_u32_e32 v33, 0x20000, v33
	buffer_load_dword v221, v33, s[12:15], 0 offen nt
	v_add_u32_e32 v33, 0x20000, v33
	buffer_load_dword v222, v33, s[12:15], 0 offen nt
	v_add_u32_e32 v33, 0x20000, v33
	buffer_load_dword v223, v33, s[12:15], 0 offen nt
	v_add_u32_e32 v33, 0x20000, v33
	buffer_load_dword v224, v33, s[12:15], 0 offen nt
	v_add_u32_e32 v33, 0x20000, v33
	buffer_load_dword v225, v33, s[12:15], 0 offen nt
	v_add_u32_e32 v33, 0x20000, v33
	buffer_load_dword v226, v33, s[12:15], 0 offen nt
	v_add_u32_e32 v33, 0x20000, v33
	buffer_load_dword v227, v33, s[12:15], 0 offen nt
	v_add_u32_e32 v33, 0x20000, v33
	buffer_load_dword v228, v33, s[12:15], 0 offen nt
	v_add_u32_e32 v33, 0x20000, v33
	buffer_load_dword v229, v33, s[12:15], 0 offen nt
	v_add_u32_e32 v33, 0x20000, v33
	buffer_load_dword v230, v33, s[12:15], 0 offen nt
	v_add_u32_e32 v33, 0x20000, v33
	buffer_load_dword v231, v33, s[12:15], 0 offen nt
	v_add_u32_e32 v33, 0x20000, v33
	buffer_load_dword v232, v33, s[12:15], 0 offen nt
	v_add_u32_e32 v33, 0x20000, v33
	buffer_load_dword v233, v33, s[12:15], 0 offen nt
	v_add_u32_e32 v33, 0x20000, v33
	buffer_load_dword v234, v33, s[12:15], 0 offen nt
	v_add_u32_e32 v33, 0x20000, v33
	buffer_load_dword v235, v33, s[12:15], 0 offen nt
	v_add_u32_e32 v33, 0x20000, v33
	buffer_load_dword v236, v33, s[12:15], 0 offen nt
	v_add_u32_e32 v33, 0x20000, v33
	buffer_load_dword v237, v33, s[12:15], 0 offen nt
	v_add_u32_e32 v33, 0x20000, v33
	buffer_load_dword v238, v33, s[12:15], 0 offen nt
	v_add_u32_e32 v33, 0x20000, v33
	buffer_load_dword v239, v33, s[12:15], 0 offen nt
	v_add_u32_e32 v33, 0x20000, v33
	buffer_load_dword v240, v33, s[12:15], 0 offen nt
	v_add_u32_e32 v33, 0x20000, v33
	buffer_load_dword v241, v33, s[12:15], 0 offen nt
	v_add_u32_e32 v33, 0x20000, v33
	buffer_load_dword v242, v33, s[12:15], 0 offen nt
	v_add_u32_e32 v33, 0x20000, v33
	buffer_load_dword v243, v33, s[12:15], 0 offen nt
	v_add_u32_e32 v33, 0x20000, v33
	buffer_load_dword v244, v33, s[12:15], 0 offen nt
	v_add_u32_e32 v33, 0x20000, v33
	buffer_load_dword v245, v33, s[12:15], 0 offen nt
	v_add_u32_e32 v33, 0x20000, v33
	buffer_load_dword v246, v33, s[12:15], 0 offen nt
	v_add_u32_e32 v33, 0x20000, v33
	buffer_load_dword v247, v33, s[12:15], 0 offen nt
	v_add_u32_e32 v33, 0x20000, v33
	buffer_load_dword v248, v33, s[12:15], 0 offen nt
	v_add_u32_e32 v33, 0x20000, v33
	s_waitcnt vmcnt(30)
	v_max_f32_e64 v249, |v218|, |v218|
	v_max_f32_e64 v33, |v35|, |v35|
	v_max_f32_e32 v33, v33, v249
	v_cvt_pk_bf16_f32 v35, v35, v218
	s_waitcnt vmcnt(29)
	v_max_f32_e64 v218, |v219|, |v219|
	s_waitcnt vmcnt(28)
	v_max_f32_e64 v249, |v220|, |v220|
	v_max_f32_e32 v218, v218, v249
	v_max3_f32 v33, v34, v33, v218
	v_cvt_pk_bf16_f32 v34, v219, v220
	v_add_u32_e32 v218, 0x2000, v43
	ds_write2_b32 v218, v35, v34 offset0:64 offset1:130
	s_waitcnt vmcnt(27)
	v_max_f32_e64 v34, |v221|, |v221|
	s_waitcnt vmcnt(26)
	v_max_f32_e64 v35, |v222|, |v222|
	s_waitcnt vmcnt(25)
	v_max_f32_e64 v218, |v223|, |v223|
	s_waitcnt vmcnt(24)
	v_max_f32_e64 v219, |v224|, |v224|
	v_max_f32_e32 v34, v34, v35
	v_max_f32_e32 v218, v218, v219
	v_cvt_pk_bf16_f32 v35, v221, v222
	v_max3_f32 v33, v33, v34, v218
	v_cvt_pk_bf16_f32 v34, v223, v224
	v_add_u32_e32 v218, 0x2200, v43
	ds_write2_b32 v218, v35, v34 offset0:68 offset1:134
	s_waitcnt vmcnt(23)
	v_max_f32_e64 v34, |v225|, |v225|
	s_waitcnt vmcnt(22)
	v_max_f32_e64 v35, |v226|, |v226|
	s_waitcnt vmcnt(21)
	v_max_f32_e64 v218, |v227|, |v227|
	s_waitcnt vmcnt(20)
	v_max_f32_e64 v219, |v228|, |v228|
	v_max_f32_e32 v34, v34, v35
	v_max_f32_e32 v218, v218, v219
	v_cvt_pk_bf16_f32 v35, v225, v226
	v_max3_f32 v33, v33, v34, v218
	v_cvt_pk_bf16_f32 v34, v227, v228
	v_add_u32_e32 v218, 0x2400, v43
	ds_write2_b32 v218, v35, v34 offset0:72 offset1:138
	s_waitcnt vmcnt(19)
	v_max_f32_e64 v34, |v229|, |v229|
	s_waitcnt vmcnt(18)
	v_max_f32_e64 v35, |v230|, |v230|
	s_waitcnt vmcnt(17)
	v_max_f32_e64 v218, |v231|, |v231|
	s_waitcnt vmcnt(16)
	v_max_f32_e64 v219, |v232|, |v232|
	v_max_f32_e32 v34, v34, v35
	v_max_f32_e32 v218, v218, v219
	v_cvt_pk_bf16_f32 v35, v229, v230
	v_max3_f32 v33, v33, v34, v218
	v_cvt_pk_bf16_f32 v34, v231, v232
	v_add_u32_e32 v218, 0x2600, v43
	ds_write2_b32 v218, v35, v34 offset0:76 offset1:142
	s_waitcnt vmcnt(15)
	v_max_f32_e64 v34, |v233|, |v233|
	s_waitcnt vmcnt(14)
	v_max_f32_e64 v35, |v234|, |v234|
	s_waitcnt vmcnt(13)
	v_max_f32_e64 v218, |v235|, |v235|
	s_waitcnt vmcnt(12)
	v_max_f32_e64 v219, |v236|, |v236|
	v_max_f32_e32 v34, v34, v35
	v_max_f32_e32 v218, v218, v219
	v_cvt_pk_bf16_f32 v35, v233, v234
	v_max3_f32 v33, v33, v34, v218
	v_cvt_pk_bf16_f32 v34, v235, v236
	v_add_u32_e32 v218, 0x2800, v43
	ds_write2_b32 v218, v35, v34 offset0:80 offset1:146
	s_waitcnt vmcnt(11)
	v_max_f32_e64 v34, |v237|, |v237|
	s_waitcnt vmcnt(10)
	v_max_f32_e64 v35, |v238|, |v238|
	s_waitcnt vmcnt(9)
	v_max_f32_e64 v218, |v239|, |v239|
	s_waitcnt vmcnt(8)
	v_max_f32_e64 v219, |v240|, |v240|
	v_max_f32_e32 v34, v34, v35
	v_max_f32_e32 v218, v218, v219
	v_cvt_pk_bf16_f32 v35, v237, v238
	v_max3_f32 v33, v33, v34, v218
	v_cvt_pk_bf16_f32 v34, v239, v240
	v_add_u32_e32 v218, 0x2a00, v43
	ds_write2_b32 v218, v35, v34 offset0:84 offset1:150
	s_waitcnt vmcnt(7)
	v_max_f32_e64 v34, |v241|, |v241|
	s_waitcnt vmcnt(6)
	v_max_f32_e64 v35, |v242|, |v242|
	s_waitcnt vmcnt(5)
	v_max_f32_e64 v218, |v243|, |v243|
	s_waitcnt vmcnt(4)
	v_max_f32_e64 v219, |v244|, |v244|
	v_max_f32_e32 v34, v34, v35
	v_max_f32_e32 v218, v218, v219
	v_cvt_pk_bf16_f32 v35, v241, v242
	v_max3_f32 v33, v33, v34, v218
	v_cvt_pk_bf16_f32 v34, v243, v244
	v_add_u32_e32 v218, 0x2c00, v43
	ds_write2_b32 v218, v35, v34 offset0:88 offset1:154
	s_waitcnt vmcnt(3)
	v_max_f32_e64 v34, |v245|, |v245|
	s_waitcnt vmcnt(2)
	v_max_f32_e64 v35, |v246|, |v246|
	s_waitcnt vmcnt(1)
	v_max_f32_e64 v218, |v247|, |v247|
	s_waitcnt vmcnt(0)
	v_max_f32_e64 v219, |v248|, |v248|
	v_max_f32_e32 v34, v34, v35
	v_max_f32_e32 v218, v218, v219
	v_cvt_pk_bf16_f32 v35, v245, v246
	v_max3_f32 v33, v33, v34, v218
	v_cvt_pk_bf16_f32 v34, v247, v248
	v_add_u32_e32 v218, 0x2e00, v43
	ds_write2_b32 v218, v35, v34 offset0:92 offset1:158
	v_cndmask_b32_e32 v34, v53, v54, vcc
	v_lshlrev_b32_e32 v34, 2, v34
	ds_bpermute_b32 v34, v34, v33
	s_and_saveexec_b64 s[28:29], s[2:3]
	s_cbranch_execz .LBB0_55
	s_add_i32 s12, s4, s34
	s_waitcnt lgkmcnt(0)
	v_max_f32_e32 v34, v34, v34
	v_max_f32_e32 v33, v33, v33
	v_lshl_add_u32 v35, v182, 2, s12
	v_max_f32_e32 v33, v33, v34
	ds_write_b32 v35, v33

.LBB0_65:
	s_andn2_b64 vcc, exec, s[28:29]
	s_cbranch_vccnz .LBB0_77
	v_add_u32_e32 v33, s43, v45
	v_add_u32_e32 v2, 0xfffe9000, v33
	s_mov_b32 s4, s50
	v_add_u32_e32 v5, 0xffff1000, v33
	buffer_load_dword v2, v2, s[4:7], 0 offen nt
	buffer_load_dword v4, v5, s[4:7], 0 offen nt
	v_add_u32_e32 v6, 0x8000, v5
	buffer_load_dword v5, v6, s[4:7], 0 offen nt
	v_add_u32_e32 v7, 0x8000, v6
	buffer_load_dword v6, v7, s[4:7], 0 offen nt
	v_add_u32_e32 v8, 0x8000, v7
	buffer_load_dword v7, v8, s[4:7], 0 offen nt
	v_add_u32_e32 v9, 0x8000, v8
	buffer_load_dword v8, v9, s[4:7], 0 offen nt
	v_add_u32_e32 v10, 0x8000, v9
	buffer_load_dword v9, v10, s[4:7], 0 offen nt
	v_add_u32_e32 v11, 0x8000, v10
	buffer_load_dword v10, v11, s[4:7], 0 offen nt
	v_add_u32_e32 v12, 0x8000, v11
	buffer_load_dword v11, v12, s[4:7], 0 offen nt
	v_add_u32_e32 v13, 0x8000, v12
	buffer_load_dword v12, v13, s[4:7], 0 offen nt
	v_add_u32_e32 v14, 0x8000, v13
	buffer_load_dword v13, v14, s[4:7], 0 offen nt
	v_add_u32_e32 v15, 0x8000, v14
	buffer_load_dword v14, v15, s[4:7], 0 offen nt
	v_add_u32_e32 v16, 0x8000, v15
	buffer_load_dword v15, v16, s[4:7], 0 offen nt
	v_add_u32_e32 v17, 0x8000, v16
	buffer_load_dword v16, v17, s[4:7], 0 offen nt
	v_add_u32_e32 v18, 0x8000, v17
	buffer_load_dword v17, v18, s[4:7], 0 offen nt
	v_add_u32_e32 v19, 0x8000, v18
	buffer_load_dword v18, v19, s[4:7], 0 offen nt
	v_add_u32_e32 v20, 0x8000, v19
	buffer_load_dword v19, v20, s[4:7], 0 offen nt
	v_add_u32_e32 v21, 0x8000, v20
	buffer_load_dword v20, v21, s[4:7], 0 offen nt
	v_add_u32_e32 v22, 0x8000, v21
	buffer_load_dword v21, v22, s[4:7], 0 offen nt
	v_add_u32_e32 v23, 0x8000, v22
	buffer_load_dword v22, v23, s[4:7], 0 offen nt
	v_add_u32_e32 v24, 0x8000, v23
	buffer_load_dword v23, v24, s[4:7], 0 offen nt
	v_add_u32_e32 v25, 0x8000, v24
	buffer_load_dword v24, v25, s[4:7], 0 offen nt
	v_add_u32_e32 v26, 0x8000, v25
	buffer_load_dword v25, v26, s[4:7], 0 offen nt
	v_add_u32_e32 v27, 0x8000, v26
	buffer_load_dword v26, v27, s[4:7], 0 offen nt
	v_add_u32_e32 v28, 0x8000, v27
	buffer_load_dword v27, v28, s[4:7], 0 offen nt
	v_add_u32_e32 v29, 0x8000, v28
	buffer_load_dword v28, v29, s[4:7], 0 offen nt
	v_add_u32_e32 v30, 0x8000, v29
	buffer_load_dword v29, v30, s[4:7], 0 offen nt
	v_add_u32_e32 v31, 0x8000, v30
	buffer_load_dword v30, v31, s[4:7], 0 offen nt
	v_add_u32_e32 v32, 0x8000, v31
	buffer_load_dword v31, v32, s[4:7], 0 offen nt
	v_add_u32_e32 v34, 0x8000, v32
	buffer_load_dword v32, v34, s[4:7], 0 offen nt
	v_add_u32_e32 v34, 0x8000, v34
	buffer_load_dword v121, v34, s[4:7], 0 offen nt
	v_add_u32_e32 v34, 0x8000, v34
	buffer_load_dword v122, v34, s[4:7], 0 offen nt
	v_add_u32_e32 v34, 0x8000, v34
	s_waitcnt vmcnt(30)
	v_max_f32_e64 v35, |v4|, |v4|
	v_max_f32_e64 v34, |v2|, |v2|
	v_max_f32_e32 v34, v34, v35
	s_waitcnt vmcnt(29)
	v_max_f32_e64 v35, |v5|, |v5|
	s_waitcnt vmcnt(28)
	v_max_f32_e64 v36, |v6|, |v6|
	v_max_f32_e32 v35, v35, v36
	v_max3_f32 v34, v34, 0, v35
	s_waitcnt vmcnt(27)
	v_max_f32_e64 v35, |v7|, |v7|
	s_waitcnt vmcnt(26)
	v_max_f32_e64 v36, |v8|, |v8|
	v_max_f32_e32 v35, v35, v36
	s_waitcnt vmcnt(25)
	v_max_f32_e64 v36, |v9|, |v9|
	s_waitcnt vmcnt(24)
	v_max_f32_e64 v37, |v10|, |v10|
	v_max_f32_e32 v36, v36, v37
	v_max3_f32 v34, v34, v35, v36
	s_waitcnt vmcnt(23)
	v_max_f32_e64 v35, |v11|, |v11|
	s_waitcnt vmcnt(22)
	v_max_f32_e64 v36, |v12|, |v12|
	v_max_f32_e32 v35, v35, v36
	s_waitcnt vmcnt(21)
	v_max_f32_e64 v36, |v13|, |v13|
	s_waitcnt vmcnt(20)
	v_max_f32_e64 v37, |v14|, |v14|
	v_max_f32_e32 v36, v36, v37
	v_max3_f32 v34, v34, v35, v36
	s_waitcnt vmcnt(19)
	v_max_f32_e64 v35, |v15|, |v15|
	s_waitcnt vmcnt(18)
	v_max_f32_e64 v36, |v16|, |v16|
	v_max_f32_e32 v35, v35, v36
	v_add_u32_e32 v57, 0x7f1000, v33
	s_waitcnt vmcnt(17)
	v_max_f32_e64 v36, |v17|, |v17|
	v_add_u32_e32 v89, 0xff1000, v33
	v_cmp_lt_i32_e32 vcc, v54, v55
	s_waitcnt vmcnt(16)
	v_max_f32_e64 v37, |v18|, |v18|
	v_max_f32_e32 v36, v36, v37
	v_max3_f32 v34, v34, v35, v36
	s_waitcnt vmcnt(15)
	v_max_f32_e64 v35, |v19|, |v19|
	s_lshl_b32 s12, s42, 10
	s_add_i32 s12, s12, 0
	s_waitcnt vmcnt(14)
	v_max_f32_e64 v36, |v20|, |v20|
	v_max_f32_e32 v35, v35, v36
	s_add_i32 s12, s12, 0x20800
	s_waitcnt vmcnt(13)
	v_max_f32_e64 v36, |v21|, |v21|
	s_waitcnt vmcnt(12)
	v_max_f32_e64 v37, |v22|, |v22|
	v_max_f32_e32 v36, v36, v37
	v_max3_f32 v34, v34, v35, v36
	s_waitcnt vmcnt(11)
	v_max_f32_e64 v35, |v23|, |v23|
	s_waitcnt vmcnt(10)
	v_max_f32_e64 v36, |v24|, |v24|
	v_max_f32_e32 v35, v35, v36
	v_add_u32_e32 v36, 0x7e9000, v33
	buffer_load_dword v36, v36, s[4:7], 0 offen nt
	buffer_load_dword v37, v57, s[4:7], 0 offen nt
	v_add_u32_e32 v58, 0x8000, v57
	buffer_load_dword v57, v58, s[4:7], 0 offen nt
	v_add_u32_e32 v59, 0x8000, v58
	buffer_load_dword v58, v59, s[4:7], 0 offen nt
	v_add_u32_e32 v60, 0x8000, v59
	buffer_load_dword v59, v60, s[4:7], 0 offen nt
	v_add_u32_e32 v61, 0x8000, v60
	buffer_load_dword v60, v61, s[4:7], 0 offen nt
	v_add_u32_e32 v62, 0x8000, v61
	buffer_load_dword v61, v62, s[4:7], 0 offen nt
	v_add_u32_e32 v63, 0x8000, v62
	buffer_load_dword v62, v63, s[4:7], 0 offen nt
	v_add_u32_e32 v64, 0x8000, v63
	buffer_load_dword v63, v64, s[4:7], 0 offen nt
	v_add_u32_e32 v65, 0x8000, v64
	buffer_load_dword v64, v65, s[4:7], 0 offen nt
	v_add_u32_e32 v66, 0x8000, v65
	buffer_load_dword v65, v66, s[4:7], 0 offen nt
	v_add_u32_e32 v67, 0x8000, v66
	buffer_load_dword v66, v67, s[4:7], 0 offen nt
	v_add_u32_e32 v68, 0x8000, v67
	buffer_load_dword v67, v68, s[4:7], 0 offen nt
	v_add_u32_e32 v69, 0x8000, v68
	buffer_load_dword v68, v69, s[4:7], 0 offen nt
	v_add_u32_e32 v70, 0x8000, v69
	buffer_load_dword v69, v70, s[4:7], 0 offen nt
	v_add_u32_e32 v71, 0x8000, v70
	buffer_load_dword v70, v71, s[4:7], 0 offen nt
	v_add_u32_e32 v72, 0x8000, v71
	buffer_load_dword v71, v72, s[4:7], 0 offen nt
	v_add_u32_e32 v73, 0x8000, v72
	buffer_load_dword v72, v73, s[4:7], 0 offen nt
	v_add_u32_e32 v74, 0x8000, v73
	buffer_load_dword v73, v74, s[4:7], 0 offen nt
	v_add_u32_e32 v75, 0x8000, v74
	buffer_load_dword v74, v75, s[4:7], 0 offen nt
	v_add_u32_e32 v76, 0x8000, v75
	buffer_load_dword v75, v76, s[4:7], 0 offen nt
	v_add_u32_e32 v77, 0x8000, v76
	buffer_load_dword v76, v77, s[4:7], 0 offen nt
	v_add_u32_e32 v78, 0x8000, v77
	buffer_load_dword v77, v78, s[4:7], 0 offen nt
	v_add_u32_e32 v79, 0x8000, v78
	buffer_load_dword v78, v79, s[4:7], 0 offen nt
	v_add_u32_e32 v80, 0x8000, v79
	buffer_load_dword v79, v80, s[4:7], 0 offen nt
	v_add_u32_e32 v83, 0x8000, v80
	buffer_load_dword v80, v83, s[4:7], 0 offen nt
	s_waitcnt vmcnt(35)
	v_max_f32_e64 v81, |v25|, |v25|
	s_waitcnt vmcnt(34)
	v_max_f32_e64 v82, |v26|, |v26|
	v_max_f32_e32 v81, v81, v82
	v_max3_f32 v34, v34, v35, v81
	s_waitcnt vmcnt(33)
	v_max_f32_e64 v35, |v27|, |v27|
	s_waitcnt vmcnt(32)
	v_max_f32_e64 v81, |v28|, |v28|
	v_max_f32_e32 v35, v35, v81
	s_waitcnt vmcnt(31)
	v_max_f32_e64 v81, |v29|, |v29|
	s_waitcnt vmcnt(30)
	v_max_f32_e64 v82, |v30|, |v30|
	v_max_f32_e32 v81, v81, v82
	v_max3_f32 v34, v34, v35, v81
	s_waitcnt vmcnt(29)
	v_max_f32_e64 v35, |v31|, |v31|
	s_waitcnt vmcnt(28)
	v_max_f32_e64 v81, |v32|, |v32|
	v_max_f32_e32 v35, v35, v81
	s_waitcnt vmcnt(27)
	v_max_f32_e64 v81, |v121|, |v121|
	s_waitcnt vmcnt(26)
	v_max_f32_e64 v82, |v122|, |v122|
	v_max_f32_e32 v81, v81, v82
	v_max3_f32 v34, v34, v35, v81
	v_add_u32_e32 v35, 0x8000, v83
	buffer_load_dword v81, v35, s[4:7], 0 offen nt
	v_add_u32_e32 v35, 0x8000, v35
	buffer_load_dword v82, v35, s[4:7], 0 offen nt
	v_add_u32_e32 v35, 0x8000, v35
	buffer_load_dword v83, v35, s[4:7], 0 offen nt
	v_add_u32_e32 v35, 0x8000, v35
	buffer_load_dword v84, v35, s[4:7], 0 offen nt
	v_add_u32_e32 v35, 0x8000, v35
	buffer_load_dword v85, v35, s[4:7], 0 offen nt
	v_add_u32_e32 v35, 0x8000, v35
	buffer_load_dword v86, v35, s[4:7], 0 offen nt
	v_add_u32_e32 v35, 0x8000, v35
	s_waitcnt vmcnt(30)
	v_max_f32_e64 v87, |v37|, |v37|
	v_max_f32_e64 v35, |v36|, |v36|
	v_max_f32_e32 v35, v35, v87
	s_waitcnt vmcnt(29)
	v_max_f32_e64 v87, |v57|, |v57|
	s_waitcnt vmcnt(28)
	v_max_f32_e64 v88, |v58|, |v58|
	v_max_f32_e32 v87, v87, v88
	v_max3_f32 v34, v34, v35, v87
	s_waitcnt vmcnt(27)
	v_max_f32_e64 v35, |v59|, |v59|
	s_waitcnt vmcnt(26)
	v_max_f32_e64 v87, |v60|, |v60|
	v_max_f32_e32 v35, v35, v87
	s_waitcnt vmcnt(25)
	v_max_f32_e64 v87, |v61|, |v61|
	s_waitcnt vmcnt(24)
	v_max_f32_e64 v88, |v62|, |v62|
	v_max_f32_e32 v87, v87, v88
	v_max3_f32 v34, v34, v35, v87
	s_waitcnt vmcnt(23)
	v_max_f32_e64 v35, |v63|, |v63|
	s_waitcnt vmcnt(22)
	v_max_f32_e64 v87, |v64|, |v64|
	v_max_f32_e32 v35, v35, v87
	s_waitcnt vmcnt(21)
	v_max_f32_e64 v87, |v65|, |v65|
	s_waitcnt vmcnt(20)
	v_max_f32_e64 v88, |v66|, |v66|
	v_max_f32_e32 v87, v87, v88
	v_max3_f32 v34, v34, v35, v87
	s_waitcnt vmcnt(19)
	v_max_f32_e64 v35, |v67|, |v67|
	s_waitcnt vmcnt(18)
	v_max_f32_e64 v87, |v68|, |v68|
	v_max_f32_e32 v35, v35, v87
	s_waitcnt vmcnt(17)
	v_max_f32_e64 v87, |v69|, |v69|
	s_waitcnt vmcnt(16)
	v_max_f32_e64 v88, |v70|, |v70|
	v_max_f32_e32 v87, v87, v88
	v_max3_f32 v34, v34, v35, v87
	s_waitcnt vmcnt(15)
	v_max_f32_e64 v35, |v71|, |v71|
	s_waitcnt vmcnt(14)
	v_max_f32_e64 v87, |v72|, |v72|
	v_max_f32_e32 v35, v35, v87
	s_waitcnt vmcnt(13)
	v_max_f32_e64 v87, |v73|, |v73|
	s_waitcnt vmcnt(12)
	v_max_f32_e64 v88, |v74|, |v74|
	v_max_f32_e32 v87, v87, v88
	v_max3_f32 v34, v34, v35, v87
	s_waitcnt vmcnt(11)
	v_max_f32_e64 v35, |v75|, |v75|
	s_waitcnt vmcnt(10)
	v_max_f32_e64 v87, |v76|, |v76|
	v_max_f32_e32 v35, v35, v87
	s_waitcnt vmcnt(9)
	v_max_f32_e64 v87, |v77|, |v77|
	s_waitcnt vmcnt(8)
	v_max_f32_e64 v88, |v78|, |v78|
	v_max_f32_e32 v87, v87, v88
	v_max3_f32 v34, v34, v35, v87
	s_waitcnt vmcnt(7)
	v_max_f32_e64 v35, |v79|, |v79|
	s_waitcnt vmcnt(6)
	v_max_f32_e64 v87, |v80|, |v80|
	v_max_f32_e32 v35, v35, v87
	v_add_u32_e32 v87, 0xfe9000, v33
	buffer_load_dword v87, v87, s[4:7], 0 offen nt
	buffer_load_dword v88, v89, s[4:7], 0 offen nt
	v_add_u32_e32 v90, 0x8000, v89
	buffer_load_dword v89, v90, s[4:7], 0 offen nt
	v_add_u32_e32 v91, 0x8000, v90
	buffer_load_dword v90, v91, s[4:7], 0 offen nt
	v_add_u32_e32 v92, 0x8000, v91
	buffer_load_dword v91, v92, s[4:7], 0 offen nt
	v_add_u32_e32 v93, 0x8000, v92
	buffer_load_dword v92, v93, s[4:7], 0 offen nt
	v_add_u32_e32 v94, 0x8000, v93
	buffer_load_dword v93, v94, s[4:7], 0 offen nt
	v_add_u32_e32 v95, 0x8000, v94
	buffer_load_dword v94, v95, s[4:7], 0 offen nt
	v_add_u32_e32 v96, 0x8000, v95
	buffer_load_dword v95, v96, s[4:7], 0 offen nt
	v_add_u32_e32 v97, 0x8000, v96
	buffer_load_dword v96, v97, s[4:7], 0 offen nt
	v_add_u32_e32 v98, 0x8000, v97
	buffer_load_dword v97, v98, s[4:7], 0 offen nt
	v_add_u32_e32 v99, 0x8000, v98
	buffer_load_dword v98, v99, s[4:7], 0 offen nt
	v_add_u32_e32 v100, 0x8000, v99
	buffer_load_dword v99, v100, s[4:7], 0 offen nt
	v_add_u32_e32 v101, 0x8000, v100
	buffer_load_dword v100, v101, s[4:7], 0 offen nt
	v_add_u32_e32 v102, 0x8000, v101
	buffer_load_dword v101, v102, s[4:7], 0 offen nt
	v_add_u32_e32 v102, 0x8000, v102
	buffer_load_dword v103, v102, s[4:7], 0 offen nt
	v_add_u32_e32 v102, 0x8000, v102
	buffer_load_dword v104, v102, s[4:7], 0 offen nt
	v_add_u32_e32 v102, 0x8000, v102
	buffer_load_dword v106, v102, s[4:7], 0 offen nt
	v_add_u32_e32 v102, 0x8000, v102
	buffer_load_dword v107, v102, s[4:7], 0 offen nt
	v_add_u32_e32 v102, 0x8000, v102
	buffer_load_dword v108, v102, s[4:7], 0 offen nt
	s_waitcnt vmcnt(25)
	v_max_f32_e64 v105, |v81|, |v81|
	s_waitcnt vmcnt(24)
	v_max_f32_e64 v111, |v82|, |v82|
	v_max_f32_e32 v105, v105, v111
	v_add_u32_e32 v102, 0x8000, v102
	v_max3_f32 v34, v34, v35, v105
	s_waitcnt vmcnt(23)
	v_max_f32_e64 v35, |v83|, |v83|
	s_waitcnt vmcnt(22)
	v_max_f32_e64 v105, |v84|, |v84|
	v_max_f32_e32 v35, v35, v105
	s_waitcnt vmcnt(21)
	v_max_f32_e64 v105, |v85|, |v85|
	s_waitcnt vmcnt(20)
	v_max_f32_e64 v111, |v86|, |v86|
	buffer_load_dword v109, v102, s[4:7], 0 offen nt
	v_add_u32_e32 v102, 0x8000, v102
	v_max_f32_e32 v105, v105, v111
	v_max3_f32 v34, v34, v35, v105
	v_add_u32_e32 v35, 0x8000, v102
	buffer_load_dword v110, v102, s[4:7], 0 offen nt
	buffer_load_dword v111, v35, s[4:7], 0 offen nt
	v_add_u32_e32 v35, 0x8000, v35
	buffer_load_dword v112, v35, s[4:7], 0 offen nt
	v_add_u32_e32 v35, 0x8000, v35
	buffer_load_dword v113, v35, s[4:7], 0 offen nt
	v_add_u32_e32 v35, 0x8000, v35
	buffer_load_dword v114, v35, s[4:7], 0 offen nt
	v_add_u32_e32 v35, 0x8000, v35
	buffer_load_dword v115, v35, s[4:7], 0 offen nt
	v_add_u32_e32 v35, 0x8000, v35
	buffer_load_dword v116, v35, s[4:7], 0 offen nt
	v_add_u32_e32 v35, 0x8000, v35
	buffer_load_dword v117, v35, s[4:7], 0 offen nt
	v_add_u32_e32 v35, 0x8000, v35
	buffer_load_dword v118, v35, s[4:7], 0 offen nt
	v_add_u32_e32 v35, 0x8000, v35
	buffer_load_dword v119, v35, s[4:7], 0 offen nt
	v_add_u32_e32 v35, 0x8000, v35
	buffer_load_dword v120, v35, s[4:7], 0 offen nt
	v_add_u32_e32 v35, 0x8000, v35
	s_waitcnt vmcnt(30)
	v_max_f32_e64 v102, |v88|, |v88|
	v_max_f32_e64 v35, |v87|, |v87|
	v_max_f32_e32 v35, v35, v102
	s_waitcnt vmcnt(29)
	v_max_f32_e64 v102, |v89|, |v89|
	s_waitcnt vmcnt(28)
	v_max_f32_e64 v105, |v90|, |v90|
	v_max_f32_e32 v102, v102, v105
	v_max3_f32 v34, v34, v35, v102
	s_waitcnt vmcnt(27)
	v_max_f32_e64 v35, |v91|, |v91|
	s_waitcnt vmcnt(26)
	v_max_f32_e64 v102, |v92|, |v92|
	v_max_f32_e32 v35, v35, v102
	s_waitcnt vmcnt(25)
	v_max_f32_e64 v102, |v93|, |v93|
	s_waitcnt vmcnt(24)
	v_max_f32_e64 v105, |v94|, |v94|
	v_max_f32_e32 v102, v102, v105
	v_max3_f32 v34, v34, v35, v102
	s_waitcnt vmcnt(23)
	v_max_f32_e64 v35, |v95|, |v95|
	s_waitcnt vmcnt(22)
	v_max_f32_e64 v102, |v96|, |v96|
	v_max_f32_e32 v35, v35, v102
	s_waitcnt vmcnt(21)
	v_max_f32_e64 v102, |v97|, |v97|
	s_waitcnt vmcnt(20)
	v_max_f32_e64 v105, |v98|, |v98|
	v_max_f32_e32 v102, v102, v105
	v_max3_f32 v34, v34, v35, v102
	s_waitcnt vmcnt(19)
	v_max_f32_e64 v35, |v99|, |v99|
	s_waitcnt vmcnt(18)
	v_max_f32_e64 v102, |v100|, |v100|
	v_max_f32_e32 v35, v35, v102
	s_waitcnt vmcnt(17)
	v_max_f32_e64 v102, |v101|, |v101|
	s_waitcnt vmcnt(16)
	v_max_f32_e64 v105, |v103|, |v103|
	v_max_f32_e32 v102, v102, v105
	v_max3_f32 v34, v34, v35, v102
	s_waitcnt vmcnt(15)
	v_max_f32_e64 v35, |v104|, |v104|
	s_waitcnt vmcnt(14)
	v_max_f32_e64 v102, |v106|, |v106|
	v_max_f32_e32 v35, v35, v102
	s_waitcnt vmcnt(13)
	v_max_f32_e64 v102, |v107|, |v107|
	s_waitcnt vmcnt(12)
	v_max_f32_e64 v105, |v108|, |v108|
	v_max_f32_e32 v102, v102, v105
	v_add_u32_e32 v105, 0x17e9000, v33
	buffer_load_dword v123, v105, s[4:7], 0 offen nt
	v_add_u32_e32 v105, 0x17f1000, v33
	buffer_load_dword v124, v105, s[4:7], 0 offen nt
	v_add_u32_e32 v105, 0x8000, v105
	buffer_load_dword v125, v105, s[4:7], 0 offen nt
	v_add_u32_e32 v105, 0x8000, v105
	buffer_load_dword v126, v105, s[4:7], 0 offen nt
	v_add_u32_e32 v105, 0x8000, v105
	buffer_load_dword v127, v105, s[4:7], 0 offen nt
	v_add_u32_e32 v105, 0x8000, v105
	buffer_load_dword v128, v105, s[4:7], 0 offen nt
	v_add_u32_e32 v105, 0x8000, v105
	buffer_load_dword v129, v105, s[4:7], 0 offen nt
	v_add_u32_e32 v105, 0x8000, v105
	buffer_load_dword v130, v105, s[4:7], 0 offen nt
	v_add_u32_e32 v105, 0x8000, v105
	buffer_load_dword v131, v105, s[4:7], 0 offen nt
	v_add_u32_e32 v105, 0x8000, v105
	buffer_load_dword v132, v105, s[4:7], 0 offen nt
	v_add_u32_e32 v105, 0x8000, v105
	buffer_load_dword v133, v105, s[4:7], 0 offen nt
	v_add_u32_e32 v105, 0x8000, v105
	buffer_load_dword v134, v105, s[4:7], 0 offen nt
	v_add_u32_e32 v105, 0x8000, v105
	buffer_load_dword v135, v105, s[4:7], 0 offen nt
	v_add_u32_e32 v105, 0x8000, v105
	buffer_load_dword v136, v105, s[4:7], 0 offen nt
	v_add_u32_e32 v105, 0x8000, v105
	buffer_load_dword v137, v105, s[4:7], 0 offen nt
	v_add_u32_e32 v105, 0x8000, v105
	buffer_load_dword v138, v105, s[4:7], 0 offen nt
	v_add_u32_e32 v105, 0x8000, v105
	buffer_load_dword v139, v105, s[4:7], 0 offen nt
	v_add_u32_e32 v105, 0x8000, v105
	buffer_load_dword v141, v105, s[4:7], 0 offen nt
	v_add_u32_e32 v105, 0x8000, v105
	buffer_load_dword v143, v105, s[4:7], 0 offen nt
	v_add_u32_e32 v105, 0x8000, v105
	buffer_load_dword v144, v105, s[4:7], 0 offen nt
	v_add_u32_e32 v105, 0x8000, v105
	buffer_load_dword v145, v105, s[4:7], 0 offen nt
	v_add_u32_e32 v105, 0x8000, v105
	buffer_load_dword v146, v105, s[4:7], 0 offen nt
	v_add_u32_e32 v105, 0x8000, v105
	buffer_load_dword v147, v105, s[4:7], 0 offen nt
	v_add_u32_e32 v105, 0x8000, v105
	buffer_load_dword v148, v105, s[4:7], 0 offen nt
	v_add_u32_e32 v105, 0x8000, v105
	buffer_load_dword v149, v105, s[4:7], 0 offen nt
	v_add_u32_e32 v105, 0x8000, v105
	buffer_load_dword v150, v105, s[4:7], 0 offen nt
	v_add_u32_e32 v105, 0x8000, v105
	buffer_load_dword v151, v105, s[4:7], 0 offen nt
	v_add_u32_e32 v105, 0x8000, v105
	buffer_load_dword v152, v105, s[4:7], 0 offen nt
	v_max3_f32 v34, v34, v35, v102
	s_waitcnt vmcnt(39)
	v_max_f32_e64 v35, |v109|, |v109|
	s_waitcnt vmcnt(38)
	v_max_f32_e64 v102, |v110|, |v110|
	v_max_f32_e32 v35, v35, v102
	s_waitcnt vmcnt(37)
	v_max_f32_e64 v102, |v111|, |v111|
	s_waitcnt vmcnt(36)
	v_max_f32_e64 v140, |v112|, |v112|
	v_max_f32_e32 v102, v102, v140
	v_max3_f32 v34, v34, v35, v102
	s_waitcnt vmcnt(35)
	v_max_f32_e64 v35, |v113|, |v113|
	s_waitcnt vmcnt(34)
	v_max_f32_e64 v102, |v114|, |v114|
	v_max_f32_e32 v35, v35, v102
	s_waitcnt vmcnt(33)
	v_max_f32_e64 v102, |v115|, |v115|
	s_waitcnt vmcnt(32)
	v_max_f32_e64 v140, |v116|, |v116|
	v_max_f32_e32 v102, v102, v140
	v_max3_f32 v34, v34, v35, v102
	s_waitcnt vmcnt(31)
	v_max_f32_e64 v35, |v117|, |v117|
	s_waitcnt vmcnt(30)
	v_max_f32_e64 v102, |v118|, |v118|
	v_max_f32_e32 v35, v35, v102
	s_waitcnt vmcnt(29)
	v_max_f32_e64 v102, |v119|, |v119|
	s_waitcnt vmcnt(28)
	v_max_f32_e64 v140, |v120|, |v120|
	v_max_f32_e32 v102, v102, v140
	v_max3_f32 v34, v34, v35, v102
	v_add_u32_e32 v35, 0x8000, v105
	buffer_load_dword v153, v35, s[4:7], 0 offen nt
	v_add_u32_e32 v35, 0x8000, v35
	buffer_load_dword v154, v35, s[4:7], 0 offen nt
	v_add_u32_e32 v35, 0x8000, v35
	buffer_load_dword v155, v35, s[4:7], 0 offen nt
	v_add_u32_e32 v35, 0x8000, v35
	buffer_load_dword v156, v35, s[4:7], 0 offen nt
	v_add_u32_e32 v35, 0x8000, v35
	s_waitcnt vmcnt(30)
	v_max_f32_e64 v102, |v124|, |v124|
	v_max_f32_e64 v35, |v123|, |v123|
	v_max_f32_e32 v35, v35, v102
	s_waitcnt vmcnt(29)
	v_max_f32_e64 v102, |v125|, |v125|
	s_waitcnt vmcnt(28)
	v_max_f32_e64 v105, |v126|, |v126|
	v_max_f32_e32 v102, v102, v105
	v_max3_f32 v34, v34, v35, v102
	s_waitcnt vmcnt(27)
	v_max_f32_e64 v35, |v127|, |v127|
	s_waitcnt vmcnt(26)
	v_max_f32_e64 v102, |v128|, |v128|
	v_max_f32_e32 v35, v35, v102
	s_waitcnt vmcnt(25)
	v_max_f32_e64 v102, |v129|, |v129|
	s_waitcnt vmcnt(24)
	v_max_f32_e64 v105, |v130|, |v130|
	v_max_f32_e32 v102, v102, v105
	v_max3_f32 v34, v34, v35, v102
	s_waitcnt vmcnt(23)
	v_max_f32_e64 v35, |v131|, |v131|
	s_waitcnt vmcnt(22)
	v_max_f32_e64 v102, |v132|, |v132|
	v_max_f32_e32 v35, v35, v102
	s_waitcnt vmcnt(21)
	v_max_f32_e64 v102, |v133|, |v133|
	s_waitcnt vmcnt(20)
	v_max_f32_e64 v105, |v134|, |v134|
	v_max_f32_e32 v102, v102, v105
	v_max3_f32 v34, v34, v35, v102
	s_waitcnt vmcnt(19)
	v_max_f32_e64 v35, |v135|, |v135|
	s_waitcnt vmcnt(18)
	v_max_f32_e64 v102, |v136|, |v136|
	v_max_f32_e32 v35, v35, v102
	s_waitcnt vmcnt(17)
	v_max_f32_e64 v102, |v137|, |v137|
	s_waitcnt vmcnt(16)
	v_max_f32_e64 v105, |v138|, |v138|
	v_max_f32_e32 v102, v102, v105
	v_max3_f32 v34, v34, v35, v102
	s_waitcnt vmcnt(15)
	v_max_f32_e64 v35, |v139|, |v139|
	s_waitcnt vmcnt(14)
	v_max_f32_e64 v102, |v141|, |v141|
	v_max_f32_e32 v35, v35, v102
	s_waitcnt vmcnt(13)
	v_max_f32_e64 v102, |v143|, |v143|
	s_waitcnt vmcnt(12)
	v_max_f32_e64 v105, |v144|, |v144|
	v_max_f32_e32 v102, v102, v105
	v_max3_f32 v34, v34, v35, v102
	s_waitcnt vmcnt(11)
	v_max_f32_e64 v35, |v145|, |v145|
	s_waitcnt vmcnt(10)
	v_max_f32_e64 v102, |v146|, |v146|
	v_max_f32_e32 v35, v35, v102
	s_waitcnt vmcnt(9)
	v_max_f32_e64 v102, |v147|, |v147|
	s_waitcnt vmcnt(8)
	v_max_f32_e64 v105, |v148|, |v148|
	v_max_f32_e32 v102, v102, v105
	v_max3_f32 v34, v34, v35, v102
	s_waitcnt vmcnt(7)
	v_max_f32_e64 v35, |v149|, |v149|
	s_waitcnt vmcnt(6)
	v_max_f32_e64 v102, |v150|, |v150|
	v_max_f32_e32 v35, v35, v102
	s_waitcnt vmcnt(5)
	v_max_f32_e64 v102, |v151|, |v151|
	s_waitcnt vmcnt(4)
	v_max_f32_e64 v105, |v152|, |v152|
	v_max_f32_e32 v102, v102, v105
	v_max3_f32 v34, v34, v35, v102
	v_add_u32_e32 v35, 0x1fe9000, v33
	buffer_load_dword v157, v35, s[4:7], 0 offen nt
	v_add_u32_e32 v35, 0x1ff1000, v33
	buffer_load_dword v158, v35, s[4:7], 0 offen nt
	v_add_u32_e32 v35, 0x8000, v35
	buffer_load_dword v159, v35, s[4:7], 0 offen nt
	v_add_u32_e32 v35, 0x8000, v35
	buffer_load_dword v160, v35, s[4:7], 0 offen nt
	v_add_u32_e32 v35, 0x8000, v35
	buffer_load_dword v161, v35, s[4:7], 0 offen nt
	v_add_u32_e32 v35, 0x8000, v35
	buffer_load_dword v162, v35, s[4:7], 0 offen nt
	v_add_u32_e32 v35, 0x8000, v35
	buffer_load_dword v163, v35, s[4:7], 0 offen nt
	v_add_u32_e32 v35, 0x8000, v35
	buffer_load_dword v164, v35, s[4:7], 0 offen nt
	v_add_u32_e32 v35, 0x8000, v35
	buffer_load_dword v165, v35, s[4:7], 0 offen nt
	v_add_u32_e32 v35, 0x8000, v35
	buffer_load_dword v166, v35, s[4:7], 0 offen nt
	v_add_u32_e32 v35, 0x8000, v35
	buffer_load_dword v167, v35, s[4:7], 0 offen nt
	v_add_u32_e32 v35, 0x8000, v35
	buffer_load_dword v168, v35, s[4:7], 0 offen nt
	v_add_u32_e32 v35, 0x8000, v35
	buffer_load_dword v169, v35, s[4:7], 0 offen nt
	v_add_u32_e32 v35, 0x8000, v35
	buffer_load_dword v170, v35, s[4:7], 0 offen nt
	v_add_u32_e32 v35, 0x8000, v35
	buffer_load_dword v171, v35, s[4:7], 0 offen nt
	v_add_u32_e32 v35, 0x8000, v35
	buffer_load_dword v172, v35, s[4:7], 0 offen nt
	v_add_u32_e32 v35, 0x8000, v35
	buffer_load_dword v174, v35, s[4:7], 0 offen nt
	v_add_u32_e32 v35, 0x8000, v35
	buffer_load_dword v176, v35, s[4:7], 0 offen nt
	v_add_u32_e32 v35, 0x8000, v35
	buffer_load_dword v177, v35, s[4:7], 0 offen nt
	v_add_u32_e32 v35, 0x8000, v35
	buffer_load_dword v178, v35, s[4:7], 0 offen nt
	v_add_u32_e32 v35, 0x8000, v35
	buffer_load_dword v179, v35, s[4:7], 0 offen nt
	v_add_u32_e32 v35, 0x8000, v35
	buffer_load_dword v180, v35, s[4:7], 0 offen nt
	v_add_u32_e32 v35, 0x8000, v35
	buffer_load_dword v181, v35, s[4:7], 0 offen nt
	v_add_u32_e32 v35, 0x8000, v35
	buffer_load_dword v183, v35, s[4:7], 0 offen nt
	v_add_u32_e32 v35, 0x8000, v35
	buffer_load_dword v184, v35, s[4:7], 0 offen nt
	v_add_u32_e32 v35, 0x8000, v35
	buffer_load_dword v185, v35, s[4:7], 0 offen nt
	v_add_u32_e32 v35, 0x8000, v35
	buffer_load_dword v186, v35, s[4:7], 0 offen nt
	v_add_u32_e32 v35, 0x8000, v35
	buffer_load_dword v187, v35, s[4:7], 0 offen nt
	v_add_u32_e32 v35, 0x8000, v35
	buffer_load_dword v188, v35, s[4:7], 0 offen nt
	v_add_u32_e32 v35, 0x8000, v35
	buffer_load_dword v189, v35, s[4:7], 0 offen nt
	v_add_u32_e32 v35, 0x8000, v35
	buffer_load_dword v190, v35, s[4:7], 0 offen nt
	v_add_u32_e32 v35, 0x8000, v35
	s_waitcnt vmcnt(34)
	v_max_f32_e64 v102, |v153|, |v153|
	s_waitcnt vmcnt(33)
	v_max_f32_e64 v105, |v154|, |v154|
	v_max_f32_e32 v102, v102, v105
	s_waitcnt vmcnt(32)
	v_max_f32_e64 v105, |v155|, |v155|
	s_waitcnt vmcnt(31)
	v_max_f32_e64 v140, |v156|, |v156|
	buffer_load_dword v191, v35, s[4:7], 0 offen nt
	v_add_u32_e32 v35, 0x8000, v35
	v_max_f32_e32 v105, v105, v140
	v_max3_f32 v34, v34, v102, v105
	s_waitcnt vmcnt(31)
	v_max_f32_e64 v35, |v157|, |v157|
	s_waitcnt vmcnt(30)
	v_max_f32_e64 v102, |v158|, |v158|
	v_max_f32_e32 v35, v35, v102
	s_waitcnt vmcnt(29)
	v_max_f32_e64 v102, |v159|, |v159|
	s_waitcnt vmcnt(28)
	v_max_f32_e64 v105, |v160|, |v160|
	v_max_f32_e32 v102, v102, v105
	v_max3_f32 v34, v34, v35, v102
	s_waitcnt vmcnt(27)
	v_max_f32_e64 v35, |v161|, |v161|
	s_waitcnt vmcnt(26)
	v_max_f32_e64 v102, |v162|, |v162|
	v_max_f32_e32 v35, v35, v102
	s_waitcnt vmcnt(25)
	v_max_f32_e64 v102, |v163|, |v163|
	s_waitcnt vmcnt(24)
	v_max_f32_e64 v105, |v164|, |v164|
	v_max_f32_e32 v102, v102, v105
	v_max3_f32 v34, v34, v35, v102
	s_waitcnt vmcnt(23)
	v_max_f32_e64 v35, |v165|, |v165|
	s_waitcnt vmcnt(22)
	v_max_f32_e64 v102, |v166|, |v166|
	v_max_f32_e32 v35, v35, v102
	s_waitcnt vmcnt(21)
	v_max_f32_e64 v102, |v167|, |v167|
	s_waitcnt vmcnt(20)
	v_max_f32_e64 v105, |v168|, |v168|
	v_max_f32_e32 v102, v102, v105
	v_max3_f32 v34, v34, v35, v102
	s_waitcnt vmcnt(19)
	v_max_f32_e64 v35, |v169|, |v169|
	s_waitcnt vmcnt(18)
	v_max_f32_e64 v102, |v170|, |v170|
	v_max_f32_e32 v35, v35, v102
	s_waitcnt vmcnt(17)
	v_max_f32_e64 v102, |v171|, |v171|
	s_waitcnt vmcnt(16)
	v_max_f32_e64 v105, |v172|, |v172|
	v_max_f32_e32 v102, v102, v105
	v_max3_f32 v34, v34, v35, v102
	s_waitcnt vmcnt(15)
	v_max_f32_e64 v35, |v174|, |v174|
	s_waitcnt vmcnt(14)
	v_max_f32_e64 v102, |v176|, |v176|
	v_max_f32_e32 v35, v35, v102
	v_add_u32_e32 v102, 0x27e9000, v33
	buffer_load_dword v192, v102, s[4:7], 0 offen nt
	v_add_u32_e32 v102, 0x27f1000, v33
	buffer_load_dword v193, v102, s[4:7], 0 offen nt
	v_add_u32_e32 v102, 0x8000, v102
	buffer_load_dword v194, v102, s[4:7], 0 offen nt
	v_add_u32_e32 v102, 0x8000, v102
	buffer_load_dword v195, v102, s[4:7], 0 offen nt
	v_add_u32_e32 v102, 0x8000, v102
	buffer_load_dword v196, v102, s[4:7], 0 offen nt
	v_add_u32_e32 v102, 0x8000, v102
	buffer_load_dword v197, v102, s[4:7], 0 offen nt
	v_add_u32_e32 v102, 0x8000, v102
	buffer_load_dword v198, v102, s[4:7], 0 offen nt
	v_add_u32_e32 v102, 0x8000, v102
	buffer_load_dword v199, v102, s[4:7], 0 offen nt
	v_add_u32_e32 v102, 0x8000, v102
	buffer_load_dword v200, v102, s[4:7], 0 offen nt
	v_add_u32_e32 v102, 0x8000, v102
	buffer_load_dword v201, v102, s[4:7], 0 offen nt
	v_add_u32_e32 v102, 0x8000, v102
	buffer_load_dword v202, v102, s[4:7], 0 offen nt
	v_add_u32_e32 v102, 0x8000, v102
	buffer_load_dword v203, v102, s[4:7], 0 offen nt
	v_add_u32_e32 v102, 0x8000, v102
	buffer_load_dword v204, v102, s[4:7], 0 offen nt
	v_add_u32_e32 v102, 0x8000, v102
	buffer_load_dword v205, v102, s[4:7], 0 offen nt
	v_add_u32_e32 v102, 0x8000, v102
	buffer_load_dword v206, v102, s[4:7], 0 offen nt
	v_add_u32_e32 v102, 0x8000, v102
	buffer_load_dword v207, v102, s[4:7], 0 offen nt
	v_add_u32_e32 v102, 0x8000, v102
	buffer_load_dword v208, v102, s[4:7], 0 offen nt
	v_add_u32_e32 v102, 0x8000, v102
	buffer_load_dword v209, v102, s[4:7], 0 offen nt
	v_add_u32_e32 v102, 0x8000, v102
	buffer_load_dword v210, v102, s[4:7], 0 offen nt
	v_add_u32_e32 v102, 0x8000, v102
	buffer_load_dword v211, v102, s[4:7], 0 offen nt
	v_add_u32_e32 v102, 0x8000, v102
	buffer_load_dword v213, v102, s[4:7], 0 offen nt
	v_add_u32_e32 v102, 0x8000, v102
	buffer_load_dword v215, v102, s[4:7], 0 offen nt
	v_add_u32_e32 v102, 0x8000, v102
	buffer_load_dword v216, v102, s[4:7], 0 offen nt
	v_add_u32_e32 v102, 0x8000, v102
	buffer_load_dword v217, v102, s[4:7], 0 offen nt
	v_add_u32_e32 v102, 0x8000, v102
	buffer_load_dword v212, v102, s[4:7], 0 offen nt
	v_add_u32_e32 v102, 0x8000, v102
	buffer_load_dword v214, v102, s[4:7], 0 offen nt
	v_add_u32_e32 v102, 0x8000, v102
	buffer_load_dword v173, v102, s[4:7], 0 offen nt
	v_add_u32_e32 v102, 0x8000, v102
	buffer_load_dword v175, v102, s[4:7], 0 offen nt
	v_add_u32_e32 v102, 0x8000, v102
	buffer_load_dword v140, v102, s[4:7], 0 offen nt
	v_add_u32_e32 v102, 0x8000, v102
	buffer_load_dword v142, v102, s[4:7], 0 offen nt
	v_add_u32_e32 v105, 0x8000, v102
	buffer_load_dword v102, v105, s[4:7], 0 offen nt
	v_add_u32_e32 v219, 0x8000, v105
	buffer_load_dword v105, v219, s[4:7], 0 offen nt
	s_waitcnt vmcnt(45)
	v_max_f32_e64 v218, |v177|, |v177|
	s_waitcnt vmcnt(44)
	v_max_f32_e64 v220, |v178|, |v178|
	v_max_f32_e32 v218, v218, v220
	v_max3_f32 v34, v34, v35, v218
	s_waitcnt vmcnt(43)
	v_max_f32_e64 v35, |v179|, |v179|
	s_waitcnt vmcnt(42)
	v_max_f32_e64 v218, |v180|, |v180|
	v_max_f32_e32 v35, v35, v218
	s_waitcnt vmcnt(41)
	v_max_f32_e64 v218, |v181|, |v181|
	s_waitcnt vmcnt(40)
	v_max_f32_e64 v220, |v183|, |v183|
	v_max_f32_e32 v218, v218, v220
	v_max3_f32 v34, v34, v35, v218
	s_waitcnt vmcnt(39)
	v_max_f32_e64 v35, |v184|, |v184|
	s_waitcnt vmcnt(38)
	v_max_f32_e64 v218, |v185|, |v185|
	v_max_f32_e32 v35, v35, v218
	s_waitcnt vmcnt(37)
	v_max_f32_e64 v218, |v186|, |v186|
	s_waitcnt vmcnt(36)
	v_max_f32_e64 v220, |v187|, |v187|
	v_max_f32_e32 v218, v218, v220
	v_max3_f32 v34, v34, v35, v218
	s_waitcnt vmcnt(35)
	v_max_f32_e64 v35, |v188|, |v188|
	s_waitcnt vmcnt(34)
	v_max_f32_e64 v218, |v189|, |v189|
	v_max_f32_e32 v35, v35, v218
	s_waitcnt vmcnt(33)
	v_max_f32_e64 v218, |v190|, |v190|
	s_waitcnt vmcnt(32)
	v_max_f32_e64 v220, |v191|, |v191|
	v_max_f32_e32 v218, v218, v220
	v_max3_f32 v34, v34, v35, v218
	v_add_u32_e32 v35, 0x8000, v219
	s_waitcnt vmcnt(30)
	v_max_f32_e64 v218, |v193|, |v193|
	v_max_f32_e64 v35, |v192|, |v192|
	v_max_f32_e32 v35, v35, v218
	s_waitcnt vmcnt(29)
	v_max_f32_e64 v218, |v194|, |v194|
	s_waitcnt vmcnt(28)
	v_max_f32_e64 v219, |v195|, |v195|
	v_max_f32_e32 v218, v218, v219
	v_max3_f32 v34, v34, v35, v218
	s_waitcnt vmcnt(27)
	v_max_f32_e64 v35, |v196|, |v196|
	s_waitcnt vmcnt(26)
	v_max_f32_e64 v218, |v197|, |v197|
	v_max_f32_e32 v35, v35, v218
	s_waitcnt vmcnt(25)
	v_max_f32_e64 v218, |v198|, |v198|
	s_waitcnt vmcnt(24)
	v_max_f32_e64 v219, |v199|, |v199|
	v_max_f32_e32 v218, v218, v219
	v_max3_f32 v34, v34, v35, v218
	s_waitcnt vmcnt(23)
	v_max_f32_e64 v35, |v200|, |v200|
	s_waitcnt vmcnt(22)
	v_max_f32_e64 v218, |v201|, |v201|
	v_max_f32_e32 v35, v35, v218
	s_waitcnt vmcnt(21)
	v_max_f32_e64 v218, |v202|, |v202|
	s_waitcnt vmcnt(20)
	v_max_f32_e64 v219, |v203|, |v203|
	v_max_f32_e32 v218, v218, v219
	v_max3_f32 v34, v34, v35, v218
	s_waitcnt vmcnt(19)
	v_max_f32_e64 v35, |v204|, |v204|
	s_waitcnt vmcnt(18)
	v_max_f32_e64 v218, |v205|, |v205|
	v_max_f32_e32 v35, v35, v218
	s_waitcnt vmcnt(17)
	v_max_f32_e64 v218, |v206|, |v206|
	s_waitcnt vmcnt(16)
	v_max_f32_e64 v219, |v207|, |v207|
	v_max_f32_e32 v218, v218, v219
	v_max3_f32 v34, v34, v35, v218
	s_waitcnt vmcnt(15)
	v_max_f32_e64 v35, |v208|, |v208|
	s_waitcnt vmcnt(14)
	v_max_f32_e64 v218, |v209|, |v209|
	v_max_f32_e32 v35, v35, v218
	s_waitcnt vmcnt(13)
	v_max_f32_e64 v218, |v210|, |v210|
	s_waitcnt vmcnt(12)
	v_max_f32_e64 v219, |v211|, |v211|
	v_max_f32_e32 v218, v218, v219
	v_max3_f32 v34, v34, v35, v218
	s_waitcnt vmcnt(11)
	v_max_f32_e64 v35, |v213|, |v213|
	s_waitcnt vmcnt(10)
	v_max_f32_e64 v218, |v215|, |v215|
	v_max_f32_e32 v35, v35, v218
	s_waitcnt vmcnt(9)
	v_max_f32_e64 v218, |v216|, |v216|
	s_waitcnt vmcnt(8)
	v_max_f32_e64 v219, |v217|, |v217|
	v_max_f32_e32 v218, v218, v219
	v_max3_f32 v34, v34, v35, v218
	s_waitcnt vmcnt(7)
	v_max_f32_e64 v35, |v212|, |v212|
	s_waitcnt vmcnt(6)
	v_max_f32_e64 v218, |v214|, |v214|
	v_max_f32_e32 v35, v35, v218
	s_waitcnt vmcnt(5)
	v_max_f32_e64 v218, |v173|, |v173|
	s_waitcnt vmcnt(4)
	v_max_f32_e64 v219, |v175|, |v175|
	v_max_f32_e32 v218, v218, v219
	v_max3_f32 v34, v34, v35, v218
	s_waitcnt vmcnt(3)
	v_max_f32_e64 v35, |v140|, |v140|
	s_waitcnt vmcnt(2)
	v_max_f32_e64 v218, |v142|, |v142|
	v_max_f32_e32 v35, v35, v218
	s_waitcnt vmcnt(1)
	v_max_f32_e64 v218, |v102|, |v102|
	s_waitcnt vmcnt(0)
	v_max_f32_e64 v219, |v105|, |v105|
	v_max_f32_e32 v218, v218, v219
	v_max3_f32 v34, v34, v35, v218
	v_add_u32_e32 v35, 0x2fe9000, v33
	v_add_u32_e32 v218, 0x2ff1000, v33
	buffer_load_dword v35, v35, s[4:7], 0 offen nt
	buffer_load_dword v219, v218, s[4:7], 0 offen nt
	v_add_u32_e32 v218, 0x8000, v218
	buffer_load_dword v220, v218, s[4:7], 0 offen nt
	v_add_u32_e32 v218, 0x8000, v218
	buffer_load_dword v221, v218, s[4:7], 0 offen nt
	v_add_u32_e32 v218, 0x8000, v218
	buffer_load_dword v222, v218, s[4:7], 0 offen nt
	v_add_u32_e32 v218, 0x8000, v218
	buffer_load_dword v223, v218, s[4:7], 0 offen nt
	v_add_u32_e32 v218, 0x8000, v218
	buffer_load_dword v224, v218, s[4:7], 0 offen nt
	v_add_u32_e32 v218, 0x8000, v218
	buffer_load_dword v225, v218, s[4:7], 0 offen nt
	v_add_u32_e32 v218, 0x8000, v218
	buffer_load_dword v226, v218, s[4:7], 0 offen nt
	v_add_u32_e32 v218, 0x8000, v218
	buffer_load_dword v227, v218, s[4:7], 0 offen nt
	v_add_u32_e32 v218, 0x8000, v218
	buffer_load_dword v228, v218, s[4:7], 0 offen nt
	v_add_u32_e32 v218, 0x8000, v218
	buffer_load_dword v229, v218, s[4:7], 0 offen nt
	v_add_u32_e32 v218, 0x8000, v218
	buffer_load_dword v230, v218, s[4:7], 0 offen nt
	v_add_u32_e32 v218, 0x8000, v218
	buffer_load_dword v231, v218, s[4:7], 0 offen nt
	v_add_u32_e32 v218, 0x8000, v218
	buffer_load_dword v232, v218, s[4:7], 0 offen nt
	v_add_u32_e32 v218, 0x8000, v218
	buffer_load_dword v233, v218, s[4:7], 0 offen nt
	v_add_u32_e32 v218, 0x8000, v218
	buffer_load_dword v234, v218, s[4:7], 0 offen nt
	v_add_u32_e32 v218, 0x8000, v218
	buffer_load_dword v235, v218, s[4:7], 0 offen nt
	v_add_u32_e32 v218, 0x8000, v218
	buffer_load_dword v236, v218, s[4:7], 0 offen nt
	v_add_u32_e32 v218, 0x8000, v218
	buffer_load_dword v237, v218, s[4:7], 0 offen nt
	v_add_u32_e32 v218, 0x8000, v218
	buffer_load_dword v238, v218, s[4:7], 0 offen nt
	v_add_u32_e32 v218, 0x8000, v218
	buffer_load_dword v239, v218, s[4:7], 0 offen nt
	v_add_u32_e32 v218, 0x8000, v218
	buffer_load_dword v240, v218, s[4:7], 0 offen nt
	v_add_u32_e32 v218, 0x8000, v218
	buffer_load_dword v241, v218, s[4:7], 0 offen nt
	v_add_u32_e32 v218, 0x8000, v218
	buffer_load_dword v242, v218, s[4:7], 0 offen nt
	v_add_u32_e32 v218, 0x8000, v218
	buffer_load_dword v243, v218, s[4:7], 0 offen nt
	v_add_u32_e32 v218, 0x8000, v218
	buffer_load_dword v244, v218, s[4:7], 0 offen nt
	v_add_u32_e32 v218, 0x8000, v218
	buffer_load_dword v245, v218, s[4:7], 0 offen nt
	v_add_u32_e32 v218, 0x8000, v218
	buffer_load_dword v246, v218, s[4:7], 0 offen nt
	v_add_u32_e32 v218, 0x8000, v218
	buffer_load_dword v247, v218, s[4:7], 0 offen nt
	v_add_u32_e32 v218, 0x8000, v218
	buffer_load_dword v248, v218, s[4:7], 0 offen nt
	v_add_u32_e32 v218, 0x8000, v218
	buffer_load_dword v249, v218, s[4:7], 0 offen nt
	v_add_u32_e32 v218, 0x8000, v218
	s_waitcnt vmcnt(30)
	v_max_f32_e64 v250, |v219|, |v219|
	v_max_f32_e64 v218, |v35|, |v35|
	v_max_f32_e32 v218, v218, v250
	v_cvt_pk_bf16_f32 v35, v35, v219
	s_waitcnt vmcnt(29)
	v_max_f32_e64 v219, |v220|, |v220|
	s_waitcnt vmcnt(28)
	v_max_f32_e64 v250, |v221|, |v221|
	v_max_f32_e32 v219, v219, v250
	v_max3_f32 v34, v34, v218, v219
	v_cvt_pk_bf16_f32 v218, v220, v221
	v_add_u32_e32 v219, 0x1000, v43
	ds_write2_b32 v219, v35, v218 offset0:32 offset1:98
	s_waitcnt vmcnt(27)
	v_max_f32_e64 v35, |v222|, |v222|
	s_waitcnt vmcnt(26)
	v_max_f32_e64 v218, |v223|, |v223|
	s_waitcnt vmcnt(25)
	v_max_f32_e64 v220, |v224|, |v224|
	s_waitcnt vmcnt(24)
	v_max_f32_e64 v221, |v225|, |v225|
	v_max_f32_e32 v35, v35, v218
	v_max_f32_e32 v220, v220, v221
	v_cvt_pk_bf16_f32 v218, v222, v223
	v_max3_f32 v34, v34, v35, v220
	v_cvt_pk_bf16_f32 v35, v224, v225
	ds_write2_b32 v219, v218, v35 offset0:164 offset1:230
	s_waitcnt vmcnt(23)
	v_max_f32_e64 v35, |v226|, |v226|
	s_waitcnt vmcnt(22)
	v_max_f32_e64 v218, |v227|, |v227|
	s_waitcnt vmcnt(21)
	v_max_f32_e64 v219, |v228|, |v228|
	s_waitcnt vmcnt(20)
	v_max_f32_e64 v220, |v229|, |v229|
	v_max_f32_e32 v35, v35, v218
	v_max_f32_e32 v219, v219, v220
	v_cvt_pk_bf16_f32 v218, v226, v227
	v_max3_f32 v34, v34, v35, v219
	v_cvt_pk_bf16_f32 v35, v228, v229
	v_add_u32_e32 v219, 0x1400, v43
	ds_write2_b32 v219, v218, v35 offset0:40 offset1:106
	s_waitcnt vmcnt(19)
	v_max_f32_e64 v35, |v230|, |v230|
	s_waitcnt vmcnt(18)
	v_max_f32_e64 v218, |v231|, |v231|
	s_waitcnt vmcnt(17)
	v_max_f32_e64 v220, |v232|, |v232|
	s_waitcnt vmcnt(16)
	v_max_f32_e64 v221, |v233|, |v233|
	v_max_f32_e32 v35, v35, v218
	v_max_f32_e32 v220, v220, v221
	v_cvt_pk_bf16_f32 v218, v230, v231
	v_max3_f32 v34, v34, v35, v220
	v_cvt_pk_bf16_f32 v35, v232, v233
	ds_write2_b32 v219, v218, v35 offset0:172 offset1:238
	s_waitcnt vmcnt(15)
	v_max_f32_e64 v35, |v234|, |v234|
	s_waitcnt vmcnt(14)
	v_max_f32_e64 v218, |v235|, |v235|
	s_waitcnt vmcnt(13)
	v_max_f32_e64 v219, |v236|, |v236|
	s_waitcnt vmcnt(12)
	v_max_f32_e64 v220, |v237|, |v237|
	v_max_f32_e32 v35, v35, v218
	v_max_f32_e32 v219, v219, v220
	v_cvt_pk_bf16_f32 v218, v234, v235
	v_max3_f32 v34, v34, v35, v219
	v_cvt_pk_bf16_f32 v35, v236, v237
	v_add_u32_e32 v219, 0x1800, v43
	ds_write2_b32 v219, v218, v35 offset0:48 offset1:114
	s_waitcnt vmcnt(11)
	v_max_f32_e64 v35, |v238|, |v238|
	s_waitcnt vmcnt(10)
	v_max_f32_e64 v218, |v239|, |v239|
	s_waitcnt vmcnt(9)
	v_max_f32_e64 v220, |v240|, |v240|
	s_waitcnt vmcnt(8)
	v_max_f32_e64 v221, |v241|, |v241|
	v_max_f32_e32 v35, v35, v218
	v_max_f32_e32 v220, v220, v221
	v_cvt_pk_bf16_f32 v218, v238, v239
	v_max3_f32 v34, v34, v35, v220
	v_cvt_pk_bf16_f32 v35, v240, v241
	ds_write2_b32 v219, v218, v35 offset0:180 offset1:246
	s_waitcnt vmcnt(7)
	v_max_f32_e64 v35, |v242|, |v242|
	s_waitcnt vmcnt(6)
	v_max_f32_e64 v218, |v243|, |v243|
	s_waitcnt vmcnt(5)
	v_max_f32_e64 v219, |v244|, |v244|
	s_waitcnt vmcnt(4)
	v_max_f32_e64 v220, |v245|, |v245|
	v_max_f32_e32 v35, v35, v218
	v_max_f32_e32 v219, v219, v220
	v_cvt_pk_bf16_f32 v218, v242, v243
	v_max3_f32 v34, v34, v35, v219
	v_cvt_pk_bf16_f32 v35, v244, v245
	v_add_u32_e32 v219, 0x1c00, v43
	ds_write2_b32 v219, v218, v35 offset0:56 offset1:122
	s_waitcnt vmcnt(3)
	v_max_f32_e64 v35, |v246|, |v246|
	s_waitcnt vmcnt(2)
	v_max_f32_e64 v218, |v247|, |v247|
	s_waitcnt vmcnt(1)
	v_max_f32_e64 v220, |v248|, |v248|
	s_waitcnt vmcnt(0)
	v_max_f32_e64 v221, |v249|, |v249|
	v_max_f32_e32 v35, v35, v218
	v_max_f32_e32 v220, v220, v221
	v_cvt_pk_bf16_f32 v218, v246, v247
	v_max3_f32 v34, v34, v35, v220
	v_cvt_pk_bf16_f32 v35, v248, v249
	ds_write2_b32 v219, v218, v35 offset0:188 offset1:254
	v_add_u32_e32 v35, 0x37e9000, v33
	v_add_u32_e32 v33, 0x37f1000, v33
	buffer_load_dword v35, v35, s[4:7], 0 offen nt
	buffer_load_dword v218, v33, s[4:7], 0 offen nt
	v_add_u32_e32 v33, 0x8000, v33
	buffer_load_dword v219, v33, s[4:7], 0 offen nt
	v_add_u32_e32 v33, 0x8000, v33
	buffer_load_dword v220, v33, s[4:7], 0 offen nt
	v_add_u32_e32 v33, 0x8000, v33
	buffer_load_dword v221, v33, s[4:7], 0 offen nt
	v_add_u32_e32 v33, 0x8000, v33
	buffer_load_dword v222, v33, s[4:7], 0 offen nt
	v_add_u32_e32 v33, 0x8000, v33
	buffer_load_dword v223, v33, s[4:7], 0 offen nt
	v_add_u32_e32 v33, 0x8000, v33
	buffer_load_dword v224, v33, s[4:7], 0 offen nt
	v_add_u32_e32 v33, 0x8000, v33
	buffer_load_dword v225, v33, s[4:7], 0 offen nt
	v_add_u32_e32 v33, 0x8000, v33
	buffer_load_dword v226, v33, s[4:7], 0 offen nt
	v_add_u32_e32 v33, 0x8000, v33
	buffer_load_dword v227, v33, s[4:7], 0 offen nt
	v_add_u32_e32 v33, 0x8000, v33
	buffer_load_dword v228, v33, s[4:7], 0 offen nt
	v_add_u32_e32 v33, 0x8000, v33
	buffer_load_dword v229, v33, s[4:7], 0 offen nt
	v_add_u32_e32 v33, 0x8000, v33
	buffer_load_dword v230, v33, s[4:7], 0 offen nt
	v_add_u32_e32 v33, 0x8000, v33
	buffer_load_dword v231, v33, s[4:7], 0 offen nt
	v_add_u32_e32 v33, 0x8000, v33
	buffer_load_dword v232, v33, s[4:7], 0 offen nt
	v_add_u32_e32 v33, 0x8000, v33
	buffer_load_dword v233, v33, s[4:7], 0 offen nt
	v_add_u32_e32 v33, 0x8000, v33
	buffer_load_dword v234, v33, s[4:7], 0 offen nt
	v_add_u32_e32 v33, 0x8000, v33
	buffer_load_dword v235, v33, s[4:7], 0 offen nt
	v_add_u32_e32 v33, 0x8000, v33
	buffer_load_dword v236, v33, s[4:7], 0 offen nt
	v_add_u32_e32 v33, 0x8000, v33
	buffer_load_dword v237, v33, s[4:7], 0 offen nt
	v_add_u32_e32 v33, 0x8000, v33
	buffer_load_dword v238, v33, s[4:7], 0 offen nt
	v_add_u32_e32 v33, 0x8000, v33
	buffer_load_dword v239, v33, s[4:7], 0 offen nt
	v_add_u32_e32 v33, 0x8000, v33
	buffer_load_dword v240, v33, s[4:7], 0 offen nt
	v_add_u32_e32 v33, 0x8000, v33
	buffer_load_dword v241, v33, s[4:7], 0 offen nt
	v_add_u32_e32 v33, 0x8000, v33
	buffer_load_dword v242, v33, s[4:7], 0 offen nt
	v_add_u32_e32 v33, 0x8000, v33
	buffer_load_dword v243, v33, s[4:7], 0 offen nt
	v_add_u32_e32 v33, 0x8000, v33
	buffer_load_dword v244, v33, s[4:7], 0 offen nt
	v_add_u32_e32 v33, 0x8000, v33
	buffer_load_dword v245, v33, s[4:7], 0 offen nt
	v_add_u32_e32 v33, 0x8000, v33
	buffer_load_dword v246, v33, s[4:7], 0 offen nt
	v_add_u32_e32 v33, 0x8000, v33
	buffer_load_dword v247, v33, s[4:7], 0 offen nt
	v_add_u32_e32 v33, 0x8000, v33
	buffer_load_dword v248, v33, s[4:7], 0 offen nt
	v_add_u32_e32 v33, 0x8000, v33
	s_waitcnt vmcnt(30)
	v_max_f32_e64 v249, |v218|, |v218|
	v_max_f32_e64 v33, |v35|, |v35|
	v_max_f32_e32 v33, v33, v249
	v_cvt_pk_bf16_f32 v35, v35, v218
	s_waitcnt vmcnt(29)
	v_max_f32_e64 v218, |v219|, |v219|
	s_waitcnt vmcnt(28)
	v_max_f32_e64 v249, |v220|, |v220|
	v_max_f32_e32 v218, v218, v249
	v_max3_f32 v33, v34, v33, v218
	v_cvt_pk_bf16_f32 v34, v219, v220
	v_add_u32_e32 v218, 0x2000, v43
	ds_write2_b32 v218, v35, v34 offset0:64 offset1:130
	s_waitcnt vmcnt(27)
	v_max_f32_e64 v34, |v221|, |v221|
	s_waitcnt vmcnt(26)
	v_max_f32_e64 v35, |v222|, |v222|
	s_waitcnt vmcnt(25)
	v_max_f32_e64 v218, |v223|, |v223|
	s_waitcnt vmcnt(24)
	v_max_f32_e64 v219, |v224|, |v224|
	v_max_f32_e32 v34, v34, v35
	v_max_f32_e32 v218, v218, v219
	v_cvt_pk_bf16_f32 v35, v221, v222
	v_max3_f32 v33, v33, v34, v218
	v_cvt_pk_bf16_f32 v34, v223, v224
	v_add_u32_e32 v218, 0x2200, v43
	ds_write2_b32 v218, v35, v34 offset0:68 offset1:134
	s_waitcnt vmcnt(23)
	v_max_f32_e64 v34, |v225|, |v225|
	s_waitcnt vmcnt(22)
	v_max_f32_e64 v35, |v226|, |v226|
	s_waitcnt vmcnt(21)
	v_max_f32_e64 v218, |v227|, |v227|
	s_waitcnt vmcnt(20)
	v_max_f32_e64 v219, |v228|, |v228|
	v_max_f32_e32 v34, v34, v35
	v_max_f32_e32 v218, v218, v219
	v_cvt_pk_bf16_f32 v35, v225, v226
	v_max3_f32 v33, v33, v34, v218
	v_cvt_pk_bf16_f32 v34, v227, v228
	v_add_u32_e32 v218, 0x2400, v43
	ds_write2_b32 v218, v35, v34 offset0:72 offset1:138
	s_waitcnt vmcnt(19)
	v_max_f32_e64 v34, |v229|, |v229|
	s_waitcnt vmcnt(18)
	v_max_f32_e64 v35, |v230|, |v230|
	s_waitcnt vmcnt(17)
	v_max_f32_e64 v218, |v231|, |v231|
	s_waitcnt vmcnt(16)
	v_max_f32_e64 v219, |v232|, |v232|
	v_max_f32_e32 v34, v34, v35
	v_max_f32_e32 v218, v218, v219
	v_cvt_pk_bf16_f32 v35, v229, v230
	v_max3_f32 v33, v33, v34, v218
	v_cvt_pk_bf16_f32 v34, v231, v232
	v_add_u32_e32 v218, 0x2600, v43
	ds_write2_b32 v218, v35, v34 offset0:76 offset1:142
	s_waitcnt vmcnt(15)
	v_max_f32_e64 v34, |v233|, |v233|
	s_waitcnt vmcnt(14)
	v_max_f32_e64 v35, |v234|, |v234|
	s_waitcnt vmcnt(13)
	v_max_f32_e64 v218, |v235|, |v235|
	s_waitcnt vmcnt(12)
	v_max_f32_e64 v219, |v236|, |v236|
	v_max_f32_e32 v34, v34, v35
	v_max_f32_e32 v218, v218, v219
	v_cvt_pk_bf16_f32 v35, v233, v234
	v_max3_f32 v33, v33, v34, v218
	v_cvt_pk_bf16_f32 v34, v235, v236
	v_add_u32_e32 v218, 0x2800, v43
	ds_write2_b32 v218, v35, v34 offset0:80 offset1:146
	s_waitcnt vmcnt(11)
	v_max_f32_e64 v34, |v237|, |v237|
	s_waitcnt vmcnt(10)
	v_max_f32_e64 v35, |v238|, |v238|
	s_waitcnt vmcnt(9)
	v_max_f32_e64 v218, |v239|, |v239|
	s_waitcnt vmcnt(8)
	v_max_f32_e64 v219, |v240|, |v240|
	v_max_f32_e32 v34, v34, v35
	v_max_f32_e32 v218, v218, v219
	v_cvt_pk_bf16_f32 v35, v237, v238
	v_max3_f32 v33, v33, v34, v218
	v_cvt_pk_bf16_f32 v34, v239, v240
	v_add_u32_e32 v218, 0x2a00, v43
	ds_write2_b32 v218, v35, v34 offset0:84 offset1:150
	s_waitcnt vmcnt(7)
	v_max_f32_e64 v34, |v241|, |v241|
	s_waitcnt vmcnt(6)
	v_max_f32_e64 v35, |v242|, |v242|
	s_waitcnt vmcnt(5)
	v_max_f32_e64 v218, |v243|, |v243|
	s_waitcnt vmcnt(4)
	v_max_f32_e64 v219, |v244|, |v244|
	v_max_f32_e32 v34, v34, v35
	v_max_f32_e32 v218, v218, v219
	v_cvt_pk_bf16_f32 v35, v241, v242
	v_max3_f32 v33, v33, v34, v218
	v_cvt_pk_bf16_f32 v34, v243, v244
	v_add_u32_e32 v218, 0x2c00, v43
	ds_write2_b32 v218, v35, v34 offset0:88 offset1:154
	s_waitcnt vmcnt(3)
	v_max_f32_e64 v34, |v245|, |v245|
	s_waitcnt vmcnt(2)
	v_max_f32_e64 v35, |v246|, |v246|
	s_waitcnt vmcnt(1)
	v_max_f32_e64 v218, |v247|, |v247|
	s_waitcnt vmcnt(0)
	v_max_f32_e64 v219, |v248|, |v248|
	v_max_f32_e32 v34, v34, v35
	v_max_f32_e32 v218, v218, v219
	v_cvt_pk_bf16_f32 v35, v245, v246
	v_max3_f32 v33, v33, v34, v218
	v_cvt_pk_bf16_f32 v34, v247, v248
	v_add_u32_e32 v218, 0x2e00, v43
	ds_write2_b32 v218, v35, v34 offset0:92 offset1:158
	v_cndmask_b32_e32 v34, v53, v54, vcc
	v_lshlrev_b32_e32 v34, 2, v34
	ds_bpermute_b32 v34, v34, v33
	s_and_saveexec_b64 s[28:29], s[2:3]
	s_cbranch_execz .LBB0_68
	s_add_i32 s4, s12, s34
	s_waitcnt lgkmcnt(0)
	v_max_f32_e32 v34, v34, v34
	v_max_f32_e32 v33, v33, v33
	v_lshl_add_u32 v35, v182, 2, s4
	v_max_f32_e32 v33, v33, v34
	ds_write_b32 v35, v33

.LBB0_78:
	s_andn2_b64 vcc, exec, s[28:29]
	s_cbranch_vccnz .LBB0_24
	v_add_u32_e32 v34, s43, v52
	s_mov_b32 s78, 0x17000000
	s_mov_b32 s79, s7
	v_add_u32_e32 v2, 0x2e000, v34
	buffer_load_dword v4, v34, s[76:79], 0 offen nt
	buffer_load_dword v5, v2, s[76:79], 0 offen nt
	v_add_u32_e32 v2, 0x2e000, v2
	buffer_load_dword v6, v2, s[76:79], 0 offen nt
	v_add_u32_e32 v2, 0x2e000, v2
	buffer_load_dword v7, v2, s[76:79], 0 offen nt
	v_add_u32_e32 v2, 0x2e000, v2
	buffer_load_dword v8, v2, s[76:79], 0 offen nt
	v_add_u32_e32 v2, 0x2e000, v2
	buffer_load_dword v9, v2, s[76:79], 0 offen nt
	v_add_u32_e32 v2, 0x2e000, v2
	buffer_load_dword v10, v2, s[76:79], 0 offen nt
	v_add_u32_e32 v2, 0x2e000, v2
	buffer_load_dword v11, v2, s[76:79], 0 offen nt
	v_add_u32_e32 v2, 0x2e000, v2
	buffer_load_dword v12, v2, s[76:79], 0 offen nt
	v_add_u32_e32 v2, 0x2e000, v2
	buffer_load_dword v13, v2, s[76:79], 0 offen nt
	v_add_u32_e32 v2, 0x2e000, v2
	buffer_load_dword v14, v2, s[76:79], 0 offen nt
	v_add_u32_e32 v2, 0x2e000, v2
	buffer_load_dword v15, v2, s[76:79], 0 offen nt
	v_add_u32_e32 v2, 0x2e000, v2
	buffer_load_dword v16, v2, s[76:79], 0 offen nt
	v_add_u32_e32 v2, 0x2e000, v2
	buffer_load_dword v17, v2, s[76:79], 0 offen nt
	v_add_u32_e32 v2, 0x2e000, v2
	buffer_load_dword v18, v2, s[76:79], 0 offen nt
	v_add_u32_e32 v2, 0x2e000, v2
	buffer_load_dword v19, v2, s[76:79], 0 offen nt
	v_add_u32_e32 v2, 0x2e000, v2
	buffer_load_dword v20, v2, s[76:79], 0 offen nt
	v_add_u32_e32 v2, 0x2e000, v2
	buffer_load_dword v21, v2, s[76:79], 0 offen nt
	v_add_u32_e32 v2, 0x2e000, v2
	buffer_load_dword v22, v2, s[76:79], 0 offen nt
	v_add_u32_e32 v2, 0x2e000, v2
	buffer_load_dword v23, v2, s[76:79], 0 offen nt
	v_add_u32_e32 v2, 0x2e000, v2
	buffer_load_dword v24, v2, s[76:79], 0 offen nt
	v_add_u32_e32 v2, 0x2e000, v2
	buffer_load_dword v25, v2, s[76:79], 0 offen nt
	v_add_u32_e32 v2, 0x2e000, v2
	buffer_load_dword v26, v2, s[76:79], 0 offen nt
	v_add_u32_e32 v2, 0x2e000, v2
	buffer_load_dword v27, v2, s[76:79], 0 offen nt
	v_add_u32_e32 v2, 0x2e000, v2
	buffer_load_dword v28, v2, s[76:79], 0 offen nt
	v_add_u32_e32 v2, 0x2e000, v2
	buffer_load_dword v29, v2, s[76:79], 0 offen nt
	v_add_u32_e32 v2, 0x2e000, v2
	buffer_load_dword v30, v2, s[76:79], 0 offen nt
	v_add_u32_e32 v2, 0x2e000, v2
	buffer_load_dword v31, v2, s[76:79], 0 offen nt
	v_add_u32_e32 v2, 0x2e000, v2
	buffer_load_dword v32, v2, s[76:79], 0 offen nt
	v_add_u32_e32 v2, 0x2e000, v2
	buffer_load_dword v33, v2, s[76:79], 0 offen nt
	v_add_u32_e32 v2, 0x2e000, v2
	buffer_load_dword v36, v2, s[76:79], 0 offen nt
	v_add_u32_e32 v2, 0x2e000, v2
	buffer_load_dword v37, v2, s[76:79], 0 offen nt
	v_add_u32_e32 v2, 0x2e000, v2
	s_waitcnt vmcnt(30)
	v_max_f32_e64 v35, |v5|, |v5|
	v_max_f32_e64 v2, |v4|, |v4|
	v_max_f32_e32 v2, v2, v35
	s_waitcnt vmcnt(29)
	v_max_f32_e64 v35, |v6|, |v6|
	s_waitcnt vmcnt(28)
	v_max_f32_e64 v57, |v7|, |v7|
	v_max_f32_e32 v35, v35, v57
	v_max3_f32 v2, v2, 0, v35
	s_waitcnt vmcnt(27)
	v_max_f32_e64 v35, |v8|, |v8|
	s_waitcnt vmcnt(26)
	v_max_f32_e64 v57, |v9|, |v9|
	v_max_f32_e32 v35, v35, v57
	s_waitcnt vmcnt(25)
	v_max_f32_e64 v57, |v10|, |v10|
	s_waitcnt vmcnt(24)
	v_max_f32_e64 v58, |v11|, |v11|
	v_max_f32_e32 v57, v57, v58
	v_max3_f32 v2, v2, v35, v57
	s_waitcnt vmcnt(23)
	v_max_f32_e64 v35, |v12|, |v12|
	s_waitcnt vmcnt(22)
	v_max_f32_e64 v57, |v13|, |v13|
	v_max_f32_e32 v35, v35, v57
	s_waitcnt vmcnt(21)
	v_max_f32_e64 v57, |v14|, |v14|
	s_waitcnt vmcnt(20)
	v_max_f32_e64 v58, |v15|, |v15|
	v_max_f32_e32 v57, v57, v58
	v_max3_f32 v2, v2, v35, v57
	s_waitcnt vmcnt(19)
	v_max_f32_e64 v35, |v16|, |v16|
	s_waitcnt vmcnt(18)
	v_max_f32_e64 v57, |v17|, |v17|
	v_max_f32_e32 v35, v35, v57
	v_cmp_lt_i32_e32 vcc, v54, v55
	s_waitcnt vmcnt(17)
	v_max_f32_e64 v57, |v18|, |v18|
	s_lshl_b32 s4, s42, 10
	s_add_i32 s4, s4, 0
	s_waitcnt vmcnt(16)
	v_max_f32_e64 v58, |v19|, |v19|
	v_max_f32_e32 v57, v57, v58
	v_max3_f32 v2, v2, v35, v57
	s_waitcnt vmcnt(15)
	v_max_f32_e64 v35, |v20|, |v20|
	s_add_i32 s4, s4, 0x20800
	s_waitcnt vmcnt(14)
	v_max_f32_e64 v57, |v21|, |v21|
	v_max_f32_e32 v35, v35, v57
	s_waitcnt vmcnt(13)
	v_max_f32_e64 v57, |v22|, |v22|
	s_waitcnt vmcnt(12)
	v_max_f32_e64 v58, |v23|, |v23|
	v_max_f32_e32 v57, v57, v58
	v_max3_f32 v2, v2, v35, v57
	s_waitcnt vmcnt(11)
	v_max_f32_e64 v35, |v24|, |v24|
	s_waitcnt vmcnt(10)
	v_max_f32_e64 v57, |v25|, |v25|
	v_max_f32_e32 v35, v35, v57
	s_waitcnt vmcnt(9)
	v_max_f32_e64 v57, |v26|, |v26|
	s_waitcnt vmcnt(8)
	v_max_f32_e64 v58, |v27|, |v27|
	v_max_f32_e32 v57, v57, v58
	v_max3_f32 v2, v2, v35, v57
	s_waitcnt vmcnt(7)
	v_max_f32_e64 v35, |v28|, |v28|
	s_waitcnt vmcnt(6)
	v_max_f32_e64 v57, |v29|, |v29|
	v_max_f32_e32 v35, v35, v57
	s_waitcnt vmcnt(5)
	v_max_f32_e64 v57, |v30|, |v30|
	s_waitcnt vmcnt(4)
	v_max_f32_e64 v58, |v31|, |v31|
	v_max_f32_e32 v57, v57, v58
	v_max3_f32 v2, v2, v35, v57
	s_waitcnt vmcnt(3)
	v_max_f32_e64 v35, |v32|, |v32|
	s_waitcnt vmcnt(2)
	v_max_f32_e64 v57, |v33|, |v33|
	v_max_f32_e32 v35, v35, v57
	s_waitcnt vmcnt(1)
	v_max_f32_e64 v57, |v36|, |v36|
	s_waitcnt vmcnt(0)
	v_max_f32_e64 v58, |v37|, |v37|
	v_max_f32_e32 v57, v57, v58
	v_max3_f32 v35, v2, v35, v57
	v_add_u32_e32 v2, 0x2e00000, v34
	v_add_u32_e32 v58, 0x2e2e000, v34
	buffer_load_dword v2, v2, s[76:79], 0 offen nt
	buffer_load_dword v57, v58, s[76:79], 0 offen nt
	v_add_u32_e32 v59, 0x2e000, v58
	buffer_load_dword v58, v59, s[76:79], 0 offen nt
	v_add_u32_e32 v60, 0x2e000, v59
	buffer_load_dword v59, v60, s[76:79], 0 offen nt
	v_add_u32_e32 v61, 0x2e000, v60
	buffer_load_dword v60, v61, s[76:79], 0 offen nt
	v_add_u32_e32 v62, 0x2e000, v61
	buffer_load_dword v61, v62, s[76:79], 0 offen nt
	v_add_u32_e32 v63, 0x2e000, v62
	buffer_load_dword v62, v63, s[76:79], 0 offen nt
	v_add_u32_e32 v64, 0x2e000, v63
	buffer_load_dword v63, v64, s[76:79], 0 offen nt
	v_add_u32_e32 v65, 0x2e000, v64
	buffer_load_dword v64, v65, s[76:79], 0 offen nt
	v_add_u32_e32 v66, 0x2e000, v65
	buffer_load_dword v65, v66, s[76:79], 0 offen nt
	v_add_u32_e32 v67, 0x2e000, v66
	buffer_load_dword v66, v67, s[76:79], 0 offen nt
	v_add_u32_e32 v68, 0x2e000, v67
	buffer_load_dword v67, v68, s[76:79], 0 offen nt
	v_add_u32_e32 v69, 0x2e000, v68
	buffer_load_dword v68, v69, s[76:79], 0 offen nt
	v_add_u32_e32 v70, 0x2e000, v69
	buffer_load_dword v69, v70, s[76:79], 0 offen nt
	v_add_u32_e32 v71, 0x2e000, v70
	buffer_load_dword v70, v71, s[76:79], 0 offen nt
	v_add_u32_e32 v72, 0x2e000, v71
	buffer_load_dword v71, v72, s[76:79], 0 offen nt
	v_add_u32_e32 v73, 0x2e000, v72
	buffer_load_dword v72, v73, s[76:79], 0 offen nt
	v_add_u32_e32 v74, 0x2e000, v73
	buffer_load_dword v73, v74, s[76:79], 0 offen nt
	v_add_u32_e32 v75, 0x2e000, v74
	buffer_load_dword v74, v75, s[76:79], 0 offen nt
	v_add_u32_e32 v76, 0x2e000, v75
	buffer_load_dword v75, v76, s[76:79], 0 offen nt
	v_add_u32_e32 v77, 0x2e000, v76
	buffer_load_dword v76, v77, s[76:79], 0 offen nt
	v_add_u32_e32 v78, 0x2e000, v77
	buffer_load_dword v77, v78, s[76:79], 0 offen nt
	v_add_u32_e32 v79, 0x2e000, v78
	buffer_load_dword v78, v79, s[76:79], 0 offen nt
	v_add_u32_e32 v80, 0x2e000, v79
	buffer_load_dword v79, v80, s[76:79], 0 offen nt
	v_add_u32_e32 v81, 0x2e000, v80
	buffer_load_dword v80, v81, s[76:79], 0 offen nt
	v_add_u32_e32 v82, 0x2e000, v81
	buffer_load_dword v81, v82, s[76:79], 0 offen nt
	v_add_u32_e32 v83, 0x2e000, v82
	buffer_load_dword v82, v83, s[76:79], 0 offen nt
	v_add_u32_e32 v84, 0x2e000, v83
	buffer_load_dword v83, v84, s[76:79], 0 offen nt
	v_add_u32_e32 v85, 0x2e000, v84
	buffer_load_dword v84, v85, s[76:79], 0 offen nt
	v_add_u32_e32 v86, 0x2e000, v85
	buffer_load_dword v85, v86, s[76:79], 0 offen nt
	v_add_u32_e32 v87, 0x2e000, v86
	buffer_load_dword v86, v87, s[76:79], 0 offen nt
	v_add_u32_e32 v88, 0x2e000, v87
	buffer_load_dword v87, v88, s[76:79], 0 offen nt
	v_add_u32_e32 v88, 0x2e000, v88
	s_waitcnt vmcnt(30)
	v_max_f32_e64 v89, |v57|, |v57|
	v_max_f32_e64 v88, |v2|, |v2|
	v_max_f32_e32 v88, v88, v89
	s_waitcnt vmcnt(29)
	v_max_f32_e64 v89, |v58|, |v58|
	s_waitcnt vmcnt(28)
	v_max_f32_e64 v90, |v59|, |v59|
	v_max_f32_e32 v89, v89, v90
	v_max3_f32 v35, v35, v88, v89
	s_waitcnt vmcnt(27)
	v_max_f32_e64 v88, |v60|, |v60|
	s_waitcnt vmcnt(26)
	v_max_f32_e64 v89, |v61|, |v61|
	v_max_f32_e32 v88, v88, v89
	s_waitcnt vmcnt(25)
	v_max_f32_e64 v89, |v62|, |v62|
	s_waitcnt vmcnt(24)
	v_max_f32_e64 v90, |v63|, |v63|
	v_max_f32_e32 v89, v89, v90
	v_max3_f32 v35, v35, v88, v89
	s_waitcnt vmcnt(23)
	v_max_f32_e64 v88, |v64|, |v64|
	s_waitcnt vmcnt(22)
	v_max_f32_e64 v89, |v65|, |v65|
	v_max_f32_e32 v88, v88, v89
	s_waitcnt vmcnt(21)
	v_max_f32_e64 v89, |v66|, |v66|
	s_waitcnt vmcnt(20)
	v_max_f32_e64 v90, |v67|, |v67|
	v_max_f32_e32 v89, v89, v90
	v_max3_f32 v35, v35, v88, v89
	s_waitcnt vmcnt(19)
	v_max_f32_e64 v88, |v68|, |v68|
	s_waitcnt vmcnt(18)
	v_max_f32_e64 v89, |v69|, |v69|
	v_max_f32_e32 v88, v88, v89
	s_waitcnt vmcnt(17)
	v_max_f32_e64 v89, |v70|, |v70|
	s_waitcnt vmcnt(16)
	v_max_f32_e64 v90, |v71|, |v71|
	v_max_f32_e32 v89, v89, v90
	v_max3_f32 v35, v35, v88, v89
	s_waitcnt vmcnt(15)
	v_max_f32_e64 v88, |v72|, |v72|
	s_waitcnt vmcnt(14)
	v_max_f32_e64 v89, |v73|, |v73|
	v_max_f32_e32 v88, v88, v89
	s_waitcnt vmcnt(13)
	v_max_f32_e64 v89, |v74|, |v74|
	s_waitcnt vmcnt(12)
	v_max_f32_e64 v90, |v75|, |v75|
	v_max_f32_e32 v89, v89, v90
	v_max3_f32 v35, v35, v88, v89
	s_waitcnt vmcnt(11)
	v_max_f32_e64 v88, |v76|, |v76|
	s_waitcnt vmcnt(10)
	v_max_f32_e64 v89, |v77|, |v77|
	v_max_f32_e32 v88, v88, v89
	s_waitcnt vmcnt(9)
	v_max_f32_e64 v89, |v78|, |v78|
	s_waitcnt vmcnt(8)
	v_max_f32_e64 v90, |v79|, |v79|
	v_max_f32_e32 v89, v89, v90
	v_max3_f32 v35, v35, v88, v89
	s_waitcnt vmcnt(7)
	v_max_f32_e64 v88, |v80|, |v80|
	s_waitcnt vmcnt(6)
	v_max_f32_e64 v89, |v81|, |v81|
	v_max_f32_e32 v88, v88, v89
	s_waitcnt vmcnt(5)
	v_max_f32_e64 v89, |v82|, |v82|
	s_waitcnt vmcnt(4)
	v_max_f32_e64 v90, |v83|, |v83|
	v_max_f32_e32 v89, v89, v90
	v_max3_f32 v35, v35, v88, v89
	s_waitcnt vmcnt(3)
	v_max_f32_e64 v88, |v84|, |v84|
	s_waitcnt vmcnt(2)
	v_max_f32_e64 v89, |v85|, |v85|
	v_max_f32_e32 v88, v88, v89
	s_waitcnt vmcnt(1)
	v_max_f32_e64 v89, |v86|, |v86|
	s_waitcnt vmcnt(0)
	v_max_f32_e64 v90, |v87|, |v87|
	v_max_f32_e32 v89, v89, v90
	v_max3_f32 v35, v35, v88, v89
	v_add_u32_e32 v88, 0x5c00000, v34
	v_add_u32_e32 v90, 0x5c2e000, v34
	buffer_load_dword v88, v88, s[76:79], 0 offen nt
	buffer_load_dword v89, v90, s[76:79], 0 offen nt
	v_add_u32_e32 v91, 0x2e000, v90
	buffer_load_dword v90, v91, s[76:79], 0 offen nt
	v_add_u32_e32 v92, 0x2e000, v91
	buffer_load_dword v91, v92, s[76:79], 0 offen nt
	v_add_u32_e32 v93, 0x2e000, v92
	buffer_load_dword v92, v93, s[76:79], 0 offen nt
	v_add_u32_e32 v94, 0x2e000, v93
	buffer_load_dword v93, v94, s[76:79], 0 offen nt
	v_add_u32_e32 v95, 0x2e000, v94
	buffer_load_dword v94, v95, s[76:79], 0 offen nt
	v_add_u32_e32 v96, 0x2e000, v95
	buffer_load_dword v95, v96, s[76:79], 0 offen nt
	v_add_u32_e32 v97, 0x2e000, v96
	buffer_load_dword v96, v97, s[76:79], 0 offen nt
	v_add_u32_e32 v98, 0x2e000, v97
	buffer_load_dword v97, v98, s[76:79], 0 offen nt
	v_add_u32_e32 v99, 0x2e000, v98
	buffer_load_dword v98, v99, s[76:79], 0 offen nt
	v_add_u32_e32 v100, 0x2e000, v99
	buffer_load_dword v99, v100, s[76:79], 0 offen nt
	v_add_u32_e32 v101, 0x2e000, v100
	buffer_load_dword v100, v101, s[76:79], 0 offen nt
	v_add_u32_e32 v102, 0x2e000, v101
	buffer_load_dword v101, v102, s[76:79], 0 offen nt
	v_add_u32_e32 v103, 0x2e000, v102
	buffer_load_dword v102, v103, s[76:79], 0 offen nt
	v_add_u32_e32 v104, 0x2e000, v103
	buffer_load_dword v103, v104, s[76:79], 0 offen nt
	v_add_u32_e32 v105, 0x2e000, v104
	buffer_load_dword v104, v105, s[76:79], 0 offen nt
	v_add_u32_e32 v106, 0x2e000, v105
	buffer_load_dword v105, v106, s[76:79], 0 offen nt
	v_add_u32_e32 v107, 0x2e000, v106
	buffer_load_dword v106, v107, s[76:79], 0 offen nt
	v_add_u32_e32 v108, 0x2e000, v107
	buffer_load_dword v107, v108, s[76:79], 0 offen nt
	v_add_u32_e32 v109, 0x2e000, v108
	buffer_load_dword v108, v109, s[76:79], 0 offen nt
	v_add_u32_e32 v110, 0x2e000, v109
	buffer_load_dword v109, v110, s[76:79], 0 offen nt
	v_add_u32_e32 v111, 0x2e000, v110
	buffer_load_dword v110, v111, s[76:79], 0 offen nt
	v_add_u32_e32 v112, 0x2e000, v111
	buffer_load_dword v111, v112, s[76:79], 0 offen nt
	v_add_u32_e32 v113, 0x2e000, v112
	buffer_load_dword v112, v113, s[76:79], 0 offen nt
	v_add_u32_e32 v114, 0x2e000, v113
	buffer_load_dword v113, v114, s[76:79], 0 offen nt
	v_add_u32_e32 v115, 0x2e000, v114
	buffer_load_dword v114, v115, s[76:79], 0 offen nt
	v_add_u32_e32 v116, 0x2e000, v115
	buffer_load_dword v115, v116, s[76:79], 0 offen nt
	v_add_u32_e32 v117, 0x2e000, v116
	buffer_load_dword v116, v117, s[76:79], 0 offen nt
	v_add_u32_e32 v118, 0x2e000, v117
	buffer_load_dword v117, v118, s[76:79], 0 offen nt
	v_add_u32_e32 v119, 0x2e000, v118
	buffer_load_dword v118, v119, s[76:79], 0 offen nt
	v_add_u32_e32 v120, 0x2e000, v119
	buffer_load_dword v119, v120, s[76:79], 0 offen nt
	v_add_u32_e32 v120, 0x2e000, v120
	s_waitcnt vmcnt(30)
	v_max_f32_e64 v121, |v89|, |v89|
	v_max_f32_e64 v120, |v88|, |v88|
	v_max_f32_e32 v120, v120, v121
	s_waitcnt vmcnt(29)
	v_max_f32_e64 v121, |v90|, |v90|
	s_waitcnt vmcnt(28)
	v_max_f32_e64 v122, |v91|, |v91|
	v_max_f32_e32 v121, v121, v122
	v_max3_f32 v35, v35, v120, v121
	s_waitcnt vmcnt(27)
	v_max_f32_e64 v120, |v92|, |v92|
	s_waitcnt vmcnt(26)
	v_max_f32_e64 v121, |v93|, |v93|
	v_max_f32_e32 v120, v120, v121
	s_waitcnt vmcnt(25)
	v_max_f32_e64 v121, |v94|, |v94|
	s_waitcnt vmcnt(24)
	v_max_f32_e64 v122, |v95|, |v95|
	v_max_f32_e32 v121, v121, v122
	v_max3_f32 v35, v35, v120, v121
	s_waitcnt vmcnt(23)
	v_max_f32_e64 v120, |v96|, |v96|
	s_waitcnt vmcnt(22)
	v_max_f32_e64 v121, |v97|, |v97|
	v_max_f32_e32 v120, v120, v121
	s_waitcnt vmcnt(21)
	v_max_f32_e64 v121, |v98|, |v98|
	s_waitcnt vmcnt(20)
	v_max_f32_e64 v122, |v99|, |v99|
	v_max_f32_e32 v121, v121, v122
	v_max3_f32 v35, v35, v120, v121
	s_waitcnt vmcnt(19)
	v_max_f32_e64 v120, |v100|, |v100|
	s_waitcnt vmcnt(18)
	v_max_f32_e64 v121, |v101|, |v101|
	v_max_f32_e32 v120, v120, v121
	s_waitcnt vmcnt(17)
	v_max_f32_e64 v121, |v102|, |v102|
	s_waitcnt vmcnt(16)
	v_max_f32_e64 v122, |v103|, |v103|
	v_max_f32_e32 v121, v121, v122
	v_max3_f32 v35, v35, v120, v121
	s_waitcnt vmcnt(15)
	v_max_f32_e64 v120, |v104|, |v104|
	s_waitcnt vmcnt(14)
	v_max_f32_e64 v121, |v105|, |v105|
	v_max_f32_e32 v120, v120, v121
	s_waitcnt vmcnt(13)
	v_max_f32_e64 v121, |v106|, |v106|
	s_waitcnt vmcnt(12)
	v_max_f32_e64 v122, |v107|, |v107|
	v_max_f32_e32 v121, v121, v122
	v_max3_f32 v35, v35, v120, v121
	s_waitcnt vmcnt(11)
	v_max_f32_e64 v120, |v108|, |v108|
	s_waitcnt vmcnt(10)
	v_max_f32_e64 v121, |v109|, |v109|
	v_max_f32_e32 v120, v120, v121
	s_waitcnt vmcnt(9)
	v_max_f32_e64 v121, |v110|, |v110|
	s_waitcnt vmcnt(8)
	v_max_f32_e64 v122, |v111|, |v111|
	v_max_f32_e32 v121, v121, v122
	v_max3_f32 v35, v35, v120, v121
	s_waitcnt vmcnt(7)
	v_max_f32_e64 v120, |v112|, |v112|
	s_waitcnt vmcnt(6)
	v_max_f32_e64 v121, |v113|, |v113|
	v_max_f32_e32 v120, v120, v121
	s_waitcnt vmcnt(5)
	v_max_f32_e64 v121, |v114|, |v114|
	s_waitcnt vmcnt(4)
	v_max_f32_e64 v122, |v115|, |v115|
	v_max_f32_e32 v121, v121, v122
	v_max3_f32 v35, v35, v120, v121
	s_waitcnt vmcnt(3)
	v_max_f32_e64 v120, |v116|, |v116|
	s_waitcnt vmcnt(2)
	v_max_f32_e64 v121, |v117|, |v117|
	v_max_f32_e32 v120, v120, v121
	s_waitcnt vmcnt(1)
	v_max_f32_e64 v121, |v118|, |v118|
	s_waitcnt vmcnt(0)
	v_max_f32_e64 v122, |v119|, |v119|
	v_max_f32_e32 v121, v121, v122
	v_max3_f32 v35, v35, v120, v121
	v_add_u32_e32 v120, 0x8a00000, v34
	v_add_u32_e32 v122, 0x8a2e000, v34
	buffer_load_dword v120, v120, s[76:79], 0 offen nt
	buffer_load_dword v121, v122, s[76:79], 0 offen nt
	v_add_u32_e32 v123, 0x2e000, v122
	buffer_load_dword v122, v123, s[76:79], 0 offen nt
	v_add_u32_e32 v124, 0x2e000, v123
	buffer_load_dword v123, v124, s[76:79], 0 offen nt
	v_add_u32_e32 v125, 0x2e000, v124
	buffer_load_dword v124, v125, s[76:79], 0 offen nt
	v_add_u32_e32 v126, 0x2e000, v125
	buffer_load_dword v125, v126, s[76:79], 0 offen nt
	v_add_u32_e32 v127, 0x2e000, v126
	buffer_load_dword v126, v127, s[76:79], 0 offen nt
	v_add_u32_e32 v128, 0x2e000, v127
	buffer_load_dword v127, v128, s[76:79], 0 offen nt
	v_add_u32_e32 v129, 0x2e000, v128
	buffer_load_dword v128, v129, s[76:79], 0 offen nt
	v_add_u32_e32 v130, 0x2e000, v129
	buffer_load_dword v129, v130, s[76:79], 0 offen nt
	v_add_u32_e32 v131, 0x2e000, v130
	buffer_load_dword v130, v131, s[76:79], 0 offen nt
	v_add_u32_e32 v132, 0x2e000, v131
	buffer_load_dword v131, v132, s[76:79], 0 offen nt
	v_add_u32_e32 v133, 0x2e000, v132
	buffer_load_dword v132, v133, s[76:79], 0 offen nt
	v_add_u32_e32 v134, 0x2e000, v133
	buffer_load_dword v133, v134, s[76:79], 0 offen nt
	v_add_u32_e32 v135, 0x2e000, v134
	buffer_load_dword v134, v135, s[76:79], 0 offen nt
	v_add_u32_e32 v136, 0x2e000, v135
	buffer_load_dword v135, v136, s[76:79], 0 offen nt
	v_add_u32_e32 v137, 0x2e000, v136
	buffer_load_dword v136, v137, s[76:79], 0 offen nt
	v_add_u32_e32 v138, 0x2e000, v137
	buffer_load_dword v137, v138, s[76:79], 0 offen nt
	v_add_u32_e32 v139, 0x2e000, v138
	buffer_load_dword v138, v139, s[76:79], 0 offen nt
	v_add_u32_e32 v140, 0x2e000, v139
	buffer_load_dword v139, v140, s[76:79], 0 offen nt
	v_add_u32_e32 v141, 0x2e000, v140
	buffer_load_dword v140, v141, s[76:79], 0 offen nt
	v_add_u32_e32 v142, 0x2e000, v141
	buffer_load_dword v141, v142, s[76:79], 0 offen nt
	v_add_u32_e32 v143, 0x2e000, v142
	buffer_load_dword v142, v143, s[76:79], 0 offen nt
	v_add_u32_e32 v144, 0x2e000, v143
	buffer_load_dword v143, v144, s[76:79], 0 offen nt
	v_add_u32_e32 v145, 0x2e000, v144
	buffer_load_dword v144, v145, s[76:79], 0 offen nt
	v_add_u32_e32 v146, 0x2e000, v145
	buffer_load_dword v145, v146, s[76:79], 0 offen nt
	v_add_u32_e32 v147, 0x2e000, v146
	buffer_load_dword v146, v147, s[76:79], 0 offen nt
	v_add_u32_e32 v148, 0x2e000, v147
	buffer_load_dword v147, v148, s[76:79], 0 offen nt
	v_add_u32_e32 v149, 0x2e000, v148
	buffer_load_dword v148, v149, s[76:79], 0 offen nt
	v_add_u32_e32 v150, 0x2e000, v149
	buffer_load_dword v149, v150, s[76:79], 0 offen nt
	v_add_u32_e32 v151, 0x2e000, v150
	buffer_load_dword v150, v151, s[76:79], 0 offen nt
	v_add_u32_e32 v152, 0x2e000, v151
	buffer_load_dword v151, v152, s[76:79], 0 offen nt
	v_add_u32_e32 v152, 0x2e000, v152
	s_waitcnt vmcnt(30)
	v_max_f32_e64 v153, |v121|, |v121|
	v_max_f32_e64 v152, |v120|, |v120|
	v_max_f32_e32 v152, v152, v153
	s_waitcnt vmcnt(29)
	v_max_f32_e64 v153, |v122|, |v122|
	s_waitcnt vmcnt(28)
	v_max_f32_e64 v154, |v123|, |v123|
	v_max_f32_e32 v153, v153, v154
	v_max3_f32 v35, v35, v152, v153
	s_waitcnt vmcnt(27)
	v_max_f32_e64 v152, |v124|, |v124|
	s_waitcnt vmcnt(26)
	v_max_f32_e64 v153, |v125|, |v125|
	v_max_f32_e32 v152, v152, v153
	s_waitcnt vmcnt(25)
	v_max_f32_e64 v153, |v126|, |v126|
	s_waitcnt vmcnt(24)
	v_max_f32_e64 v154, |v127|, |v127|
	v_max_f32_e32 v153, v153, v154
	v_max3_f32 v35, v35, v152, v153
	s_waitcnt vmcnt(23)
	v_max_f32_e64 v152, |v128|, |v128|
	s_waitcnt vmcnt(22)
	v_max_f32_e64 v153, |v129|, |v129|
	v_max_f32_e32 v152, v152, v153
	s_waitcnt vmcnt(21)
	v_max_f32_e64 v153, |v130|, |v130|
	s_waitcnt vmcnt(20)
	v_max_f32_e64 v154, |v131|, |v131|
	v_max_f32_e32 v153, v153, v154
	v_max3_f32 v35, v35, v152, v153
	s_waitcnt vmcnt(19)
	v_max_f32_e64 v152, |v132|, |v132|
	s_waitcnt vmcnt(18)
	v_max_f32_e64 v153, |v133|, |v133|
	v_max_f32_e32 v152, v152, v153
	s_waitcnt vmcnt(17)
	v_max_f32_e64 v153, |v134|, |v134|
	s_waitcnt vmcnt(16)
	v_max_f32_e64 v154, |v135|, |v135|
	v_max_f32_e32 v153, v153, v154
	v_max3_f32 v35, v35, v152, v153
	s_waitcnt vmcnt(15)
	v_max_f32_e64 v152, |v136|, |v136|
	s_waitcnt vmcnt(14)
	v_max_f32_e64 v153, |v137|, |v137|
	v_max_f32_e32 v152, v152, v153
	s_waitcnt vmcnt(13)
	v_max_f32_e64 v153, |v138|, |v138|
	s_waitcnt vmcnt(12)
	v_max_f32_e64 v154, |v139|, |v139|
	v_max_f32_e32 v153, v153, v154
	v_max3_f32 v35, v35, v152, v153
	s_waitcnt vmcnt(11)
	v_max_f32_e64 v152, |v140|, |v140|
	s_waitcnt vmcnt(10)
	v_max_f32_e64 v153, |v141|, |v141|
	v_max_f32_e32 v152, v152, v153
	s_waitcnt vmcnt(9)
	v_max_f32_e64 v153, |v142|, |v142|
	s_waitcnt vmcnt(8)
	v_max_f32_e64 v154, |v143|, |v143|
	v_max_f32_e32 v153, v153, v154
	v_max3_f32 v35, v35, v152, v153
	s_waitcnt vmcnt(7)
	v_max_f32_e64 v152, |v144|, |v144|
	s_waitcnt vmcnt(6)
	v_max_f32_e64 v153, |v145|, |v145|
	v_max_f32_e32 v152, v152, v153
	s_waitcnt vmcnt(5)
	v_max_f32_e64 v153, |v146|, |v146|
	s_waitcnt vmcnt(4)
	v_max_f32_e64 v154, |v147|, |v147|
	v_max_f32_e32 v153, v153, v154
	v_max3_f32 v35, v35, v152, v153
	s_waitcnt vmcnt(3)
	v_max_f32_e64 v152, |v148|, |v148|
	s_waitcnt vmcnt(2)
	v_max_f32_e64 v153, |v149|, |v149|
	v_max_f32_e32 v152, v152, v153
	s_waitcnt vmcnt(1)
	v_max_f32_e64 v153, |v150|, |v150|
	s_waitcnt vmcnt(0)
	v_max_f32_e64 v154, |v151|, |v151|
	v_max_f32_e32 v153, v153, v154
	v_max3_f32 v35, v35, v152, v153
	v_add_u32_e32 v152, 0xb800000, v34
	buffer_load_dword v154, v152, s[76:79], 0 offen nt
	v_add_u32_e32 v152, 0xb82e000, v34
	buffer_load_dword v155, v152, s[76:79], 0 offen nt
	v_add_u32_e32 v152, 0x2e000, v152
	buffer_load_dword v156, v152, s[76:79], 0 offen nt
	v_add_u32_e32 v152, 0x2e000, v152
	buffer_load_dword v157, v152, s[76:79], 0 offen nt
	v_add_u32_e32 v152, 0x2e000, v152
	buffer_load_dword v158, v152, s[76:79], 0 offen nt
	v_add_u32_e32 v152, 0x2e000, v152
	buffer_load_dword v159, v152, s[76:79], 0 offen nt
	v_add_u32_e32 v152, 0x2e000, v152
	buffer_load_dword v160, v152, s[76:79], 0 offen nt
	v_add_u32_e32 v152, 0x2e000, v152
	buffer_load_dword v161, v152, s[76:79], 0 offen nt
	v_add_u32_e32 v152, 0x2e000, v152
	buffer_load_dword v162, v152, s[76:79], 0 offen nt
	v_add_u32_e32 v152, 0x2e000, v152
	buffer_load_dword v163, v152, s[76:79], 0 offen nt
	v_add_u32_e32 v152, 0x2e000, v152
	buffer_load_dword v164, v152, s[76:79], 0 offen nt
	v_add_u32_e32 v152, 0x2e000, v152
	buffer_load_dword v166, v152, s[76:79], 0 offen nt
	v_add_u32_e32 v152, 0x2e000, v152
	buffer_load_dword v168, v152, s[76:79], 0 offen nt
	v_add_u32_e32 v152, 0x2e000, v152
	buffer_load_dword v169, v152, s[76:79], 0 offen nt
	v_add_u32_e32 v152, 0x2e000, v152
	buffer_load_dword v170, v152, s[76:79], 0 offen nt
	v_add_u32_e32 v152, 0x2e000, v152
	buffer_load_dword v171, v152, s[76:79], 0 offen nt
	v_add_u32_e32 v152, 0x2e000, v152
	buffer_load_dword v172, v152, s[76:79], 0 offen nt
	v_add_u32_e32 v152, 0x2e000, v152
	buffer_load_dword v173, v152, s[76:79], 0 offen nt
	v_add_u32_e32 v152, 0x2e000, v152
	buffer_load_dword v174, v152, s[76:79], 0 offen nt
	v_add_u32_e32 v152, 0x2e000, v152
	buffer_load_dword v175, v152, s[76:79], 0 offen nt
	v_add_u32_e32 v152, 0x2e000, v152
	buffer_load_dword v176, v152, s[76:79], 0 offen nt
	v_add_u32_e32 v152, 0x2e000, v152
	buffer_load_dword v177, v152, s[76:79], 0 offen nt
	v_add_u32_e32 v152, 0x2e000, v152
	buffer_load_dword v178, v152, s[76:79], 0 offen nt
	v_add_u32_e32 v152, 0x2e000, v152
	buffer_load_dword v179, v152, s[76:79], 0 offen nt
	v_add_u32_e32 v152, 0x2e000, v152
	buffer_load_dword v180, v152, s[76:79], 0 offen nt
	v_add_u32_e32 v152, 0x2e000, v152
	buffer_load_dword v181, v152, s[76:79], 0 offen nt
	v_add_u32_e32 v152, 0x2e000, v152
	buffer_load_dword v183, v152, s[76:79], 0 offen nt
	v_add_u32_e32 v152, 0x2e000, v152
	buffer_load_dword v184, v152, s[76:79], 0 offen nt
	v_add_u32_e32 v152, 0x2e000, v152
	buffer_load_dword v185, v152, s[76:79], 0 offen nt
	v_add_u32_e32 v152, 0x2e000, v152
	buffer_load_dword v186, v152, s[76:79], 0 offen nt
	v_add_u32_e32 v152, 0x2e000, v152
	buffer_load_dword v187, v152, s[76:79], 0 offen nt
	v_add_u32_e32 v152, 0x2e000, v152
	buffer_load_dword v188, v152, s[76:79], 0 offen nt
	v_add_u32_e32 v152, 0x2e000, v152
	s_waitcnt vmcnt(30)
	v_max_f32_e64 v153, |v155|, |v155|
	v_max_f32_e64 v152, |v154|, |v154|
	v_max_f32_e32 v152, v152, v153
	s_waitcnt vmcnt(29)
	v_max_f32_e64 v153, |v156|, |v156|
	s_waitcnt vmcnt(28)
	v_max_f32_e64 v165, |v157|, |v157|
	v_max_f32_e32 v153, v153, v165
	v_max3_f32 v35, v35, v152, v153
	s_waitcnt vmcnt(27)
	v_max_f32_e64 v152, |v158|, |v158|
	s_waitcnt vmcnt(26)
	v_max_f32_e64 v153, |v159|, |v159|
	v_max_f32_e32 v152, v152, v153
	s_waitcnt vmcnt(25)
	v_max_f32_e64 v153, |v160|, |v160|
	s_waitcnt vmcnt(24)
	v_max_f32_e64 v165, |v161|, |v161|
	v_max_f32_e32 v153, v153, v165
	v_max3_f32 v35, v35, v152, v153
	s_waitcnt vmcnt(23)
	v_max_f32_e64 v152, |v162|, |v162|
	s_waitcnt vmcnt(22)
	v_max_f32_e64 v153, |v163|, |v163|
	v_max_f32_e32 v152, v152, v153
	s_waitcnt vmcnt(21)
	v_max_f32_e64 v153, |v164|, |v164|
	s_waitcnt vmcnt(20)
	v_max_f32_e64 v165, |v166|, |v166|
	v_max_f32_e32 v153, v153, v165
	v_max3_f32 v35, v35, v152, v153
	s_waitcnt vmcnt(19)
	v_max_f32_e64 v152, |v168|, |v168|
	s_waitcnt vmcnt(18)
	v_max_f32_e64 v153, |v169|, |v169|
	v_max_f32_e32 v152, v152, v153
	s_waitcnt vmcnt(17)
	v_max_f32_e64 v153, |v170|, |v170|
	s_waitcnt vmcnt(16)
	v_max_f32_e64 v165, |v171|, |v171|
	v_max_f32_e32 v153, v153, v165
	v_max3_f32 v35, v35, v152, v153
	s_waitcnt vmcnt(15)
	v_max_f32_e64 v152, |v172|, |v172|
	s_waitcnt vmcnt(14)
	v_max_f32_e64 v153, |v173|, |v173|
	v_max_f32_e32 v152, v152, v153
	s_waitcnt vmcnt(13)
	v_max_f32_e64 v153, |v174|, |v174|
	s_waitcnt vmcnt(12)
	v_max_f32_e64 v165, |v175|, |v175|
	v_max_f32_e32 v153, v153, v165
	v_max3_f32 v35, v35, v152, v153
	s_waitcnt vmcnt(11)
	v_max_f32_e64 v152, |v176|, |v176|
	s_waitcnt vmcnt(10)
	v_max_f32_e64 v153, |v177|, |v177|
	v_max_f32_e32 v152, v152, v153
	s_waitcnt vmcnt(9)
	v_max_f32_e64 v153, |v178|, |v178|
	s_waitcnt vmcnt(8)
	v_max_f32_e64 v165, |v179|, |v179|
	v_max_f32_e32 v153, v153, v165
	v_max3_f32 v35, v35, v152, v153
	s_waitcnt vmcnt(7)
	v_max_f32_e64 v152, |v180|, |v180|
	s_waitcnt vmcnt(6)
	v_max_f32_e64 v153, |v181|, |v181|
	v_max_f32_e32 v152, v152, v153
	s_waitcnt vmcnt(5)
	v_max_f32_e64 v153, |v183|, |v183|
	s_waitcnt vmcnt(4)
	v_max_f32_e64 v165, |v184|, |v184|
	v_max_f32_e32 v153, v153, v165
	v_max3_f32 v35, v35, v152, v153
	s_waitcnt vmcnt(3)
	v_max_f32_e64 v152, |v185|, |v185|
	s_waitcnt vmcnt(2)
	v_max_f32_e64 v153, |v186|, |v186|
	v_max_f32_e32 v152, v152, v153
	s_waitcnt vmcnt(1)
	v_max_f32_e64 v153, |v187|, |v187|
	s_waitcnt vmcnt(0)
	v_max_f32_e64 v165, |v188|, |v188|
	v_max_f32_e32 v153, v153, v165
	v_max3_f32 v35, v35, v152, v153
	v_add_u32_e32 v152, 0xe600000, v34
	buffer_load_dword v191, v152, s[76:79], 0 offen nt
	v_add_u32_e32 v152, 0xe62e000, v34
	buffer_load_dword v192, v152, s[76:79], 0 offen nt
	v_add_u32_e32 v152, 0x2e000, v152
	buffer_load_dword v193, v152, s[76:79], 0 offen nt
	v_add_u32_e32 v152, 0x2e000, v152
	buffer_load_dword v194, v152, s[76:79], 0 offen nt
	v_add_u32_e32 v152, 0x2e000, v152
	buffer_load_dword v195, v152, s[76:79], 0 offen nt
	v_add_u32_e32 v152, 0x2e000, v152
	buffer_load_dword v196, v152, s[76:79], 0 offen nt
	v_add_u32_e32 v152, 0x2e000, v152
	buffer_load_dword v197, v152, s[76:79], 0 offen nt
	v_add_u32_e32 v152, 0x2e000, v152
	buffer_load_dword v198, v152, s[76:79], 0 offen nt
	v_add_u32_e32 v152, 0x2e000, v152
	buffer_load_dword v199, v152, s[76:79], 0 offen nt
	v_add_u32_e32 v152, 0x2e000, v152
	buffer_load_dword v200, v152, s[76:79], 0 offen nt
	v_add_u32_e32 v152, 0x2e000, v152
	buffer_load_dword v201, v152, s[76:79], 0 offen nt
	v_add_u32_e32 v152, 0x2e000, v152
	buffer_load_dword v202, v152, s[76:79], 0 offen nt
	v_add_u32_e32 v152, 0x2e000, v152
	buffer_load_dword v203, v152, s[76:79], 0 offen nt
	v_add_u32_e32 v152, 0x2e000, v152
	buffer_load_dword v204, v152, s[76:79], 0 offen nt
	v_add_u32_e32 v152, 0x2e000, v152
	buffer_load_dword v205, v152, s[76:79], 0 offen nt
	v_add_u32_e32 v152, 0x2e000, v152
	buffer_load_dword v206, v152, s[76:79], 0 offen nt
	v_add_u32_e32 v152, 0x2e000, v152
	buffer_load_dword v207, v152, s[76:79], 0 offen nt
	v_add_u32_e32 v152, 0x2e000, v152
	buffer_load_dword v208, v152, s[76:79], 0 offen nt
	v_add_u32_e32 v152, 0x2e000, v152
	buffer_load_dword v209, v152, s[76:79], 0 offen nt
	v_add_u32_e32 v152, 0x2e000, v152
	buffer_load_dword v210, v152, s[76:79], 0 offen nt
	v_add_u32_e32 v152, 0x2e000, v152
	buffer_load_dword v212, v152, s[76:79], 0 offen nt
	v_add_u32_e32 v152, 0x2e000, v152
	buffer_load_dword v214, v152, s[76:79], 0 offen nt
	v_add_u32_e32 v152, 0x2e000, v152
	buffer_load_dword v215, v152, s[76:79], 0 offen nt
	v_add_u32_e32 v152, 0x2e000, v152
	buffer_load_dword v216, v152, s[76:79], 0 offen nt
	v_add_u32_e32 v152, 0x2e000, v152
	buffer_load_dword v211, v152, s[76:79], 0 offen nt
	v_add_u32_e32 v152, 0x2e000, v152
	buffer_load_dword v213, v152, s[76:79], 0 offen nt
	v_add_u32_e32 v152, 0x2e000, v152
	buffer_load_dword v189, v152, s[76:79], 0 offen nt
	v_add_u32_e32 v152, 0x2e000, v152
	buffer_load_dword v190, v152, s[76:79], 0 offen nt
	v_add_u32_e32 v152, 0x2e000, v152
	buffer_load_dword v165, v152, s[76:79], 0 offen nt
	v_add_u32_e32 v152, 0x2e000, v152
	buffer_load_dword v167, v152, s[76:79], 0 offen nt
	v_add_u32_e32 v153, 0x2e000, v152
	buffer_load_dword v152, v153, s[76:79], 0 offen nt
	v_add_u32_e32 v217, 0x2e000, v153
	buffer_load_dword v153, v217, s[76:79], 0 offen nt
	v_add_u32_e32 v217, 0x2e000, v217
	s_waitcnt vmcnt(30)
	v_max_f32_e64 v218, |v192|, |v192|
	v_max_f32_e64 v217, |v191|, |v191|
	v_max_f32_e32 v217, v217, v218
	s_waitcnt vmcnt(29)
	v_max_f32_e64 v218, |v193|, |v193|
	s_waitcnt vmcnt(28)
	v_max_f32_e64 v219, |v194|, |v194|
	v_max_f32_e32 v218, v218, v219
	v_max3_f32 v35, v35, v217, v218
	s_waitcnt vmcnt(27)
	v_max_f32_e64 v217, |v195|, |v195|
	s_waitcnt vmcnt(26)
	v_max_f32_e64 v218, |v196|, |v196|
	v_max_f32_e32 v217, v217, v218
	s_waitcnt vmcnt(25)
	v_max_f32_e64 v218, |v197|, |v197|
	s_waitcnt vmcnt(24)
	v_max_f32_e64 v219, |v198|, |v198|
	v_max_f32_e32 v218, v218, v219
	v_max3_f32 v35, v35, v217, v218
	s_waitcnt vmcnt(23)
	v_max_f32_e64 v217, |v199|, |v199|
	s_waitcnt vmcnt(22)
	v_max_f32_e64 v218, |v200|, |v200|
	v_max_f32_e32 v217, v217, v218
	s_waitcnt vmcnt(21)
	v_max_f32_e64 v218, |v201|, |v201|
	s_waitcnt vmcnt(20)
	v_max_f32_e64 v219, |v202|, |v202|
	v_max_f32_e32 v218, v218, v219
	v_max3_f32 v35, v35, v217, v218
	s_waitcnt vmcnt(19)
	v_max_f32_e64 v217, |v203|, |v203|
	s_waitcnt vmcnt(18)
	v_max_f32_e64 v218, |v204|, |v204|
	v_max_f32_e32 v217, v217, v218
	s_waitcnt vmcnt(17)
	v_max_f32_e64 v218, |v205|, |v205|
	s_waitcnt vmcnt(16)
	v_max_f32_e64 v219, |v206|, |v206|
	v_max_f32_e32 v218, v218, v219
	v_max3_f32 v35, v35, v217, v218
	s_waitcnt vmcnt(15)
	v_max_f32_e64 v217, |v207|, |v207|
	s_waitcnt vmcnt(14)
	v_max_f32_e64 v218, |v208|, |v208|
	v_max_f32_e32 v217, v217, v218
	s_waitcnt vmcnt(13)
	v_max_f32_e64 v218, |v209|, |v209|
	s_waitcnt vmcnt(12)
	v_max_f32_e64 v219, |v210|, |v210|
	v_max_f32_e32 v218, v218, v219
	v_max3_f32 v35, v35, v217, v218
	s_waitcnt vmcnt(11)
	v_max_f32_e64 v217, |v212|, |v212|
	s_waitcnt vmcnt(10)
	v_max_f32_e64 v218, |v214|, |v214|
	v_max_f32_e32 v217, v217, v218
	s_waitcnt vmcnt(9)
	v_max_f32_e64 v218, |v215|, |v215|
	s_waitcnt vmcnt(8)
	v_max_f32_e64 v219, |v216|, |v216|
	v_max_f32_e32 v218, v218, v219
	v_max3_f32 v35, v35, v217, v218
	s_waitcnt vmcnt(7)
	v_max_f32_e64 v217, |v211|, |v211|
	s_waitcnt vmcnt(6)
	v_max_f32_e64 v218, |v213|, |v213|
	v_max_f32_e32 v217, v217, v218
	s_waitcnt vmcnt(5)
	v_max_f32_e64 v218, |v189|, |v189|
	s_waitcnt vmcnt(4)
	v_max_f32_e64 v219, |v190|, |v190|
	v_max_f32_e32 v218, v218, v219
	v_max3_f32 v35, v35, v217, v218
	s_waitcnt vmcnt(3)
	v_max_f32_e64 v217, |v165|, |v165|
	s_waitcnt vmcnt(2)
	v_max_f32_e64 v218, |v167|, |v167|
	v_max_f32_e32 v217, v217, v218
	s_waitcnt vmcnt(1)
	v_max_f32_e64 v218, |v152|, |v152|
	s_waitcnt vmcnt(0)
	v_max_f32_e64 v219, |v153|, |v153|
	v_max_f32_e32 v218, v218, v219
	v_max3_f32 v35, v35, v217, v218
	v_add_u32_e32 v217, 0x11400000, v34
	v_add_u32_e32 v218, 0x1142e000, v34
	buffer_load_dword v217, v217, s[76:79], 0 offen nt
	buffer_load_dword v219, v218, s[76:79], 0 offen nt
	v_add_u32_e32 v218, 0x2e000, v218
	buffer_load_dword v220, v218, s[76:79], 0 offen nt
	v_add_u32_e32 v218, 0x2e000, v218
	buffer_load_dword v221, v218, s[76:79], 0 offen nt
	v_add_u32_e32 v218, 0x2e000, v218
	buffer_load_dword v222, v218, s[76:79], 0 offen nt
	v_add_u32_e32 v218, 0x2e000, v218
	buffer_load_dword v223, v218, s[76:79], 0 offen nt
	v_add_u32_e32 v218, 0x2e000, v218
	buffer_load_dword v224, v218, s[76:79], 0 offen nt
	v_add_u32_e32 v218, 0x2e000, v218
	buffer_load_dword v225, v218, s[76:79], 0 offen nt
	v_add_u32_e32 v218, 0x2e000, v218
	buffer_load_dword v226, v218, s[76:79], 0 offen nt
	v_add_u32_e32 v218, 0x2e000, v218
	buffer_load_dword v227, v218, s[76:79], 0 offen nt
	v_add_u32_e32 v218, 0x2e000, v218
	buffer_load_dword v228, v218, s[76:79], 0 offen nt
	v_add_u32_e32 v218, 0x2e000, v218
	buffer_load_dword v229, v218, s[76:79], 0 offen nt
	v_add_u32_e32 v218, 0x2e000, v218
	buffer_load_dword v230, v218, s[76:79], 0 offen nt
	v_add_u32_e32 v218, 0x2e000, v218
	buffer_load_dword v231, v218, s[76:79], 0 offen nt
	v_add_u32_e32 v218, 0x2e000, v218
	buffer_load_dword v232, v218, s[76:79], 0 offen nt
	v_add_u32_e32 v218, 0x2e000, v218
	buffer_load_dword v233, v218, s[76:79], 0 offen nt
	v_add_u32_e32 v218, 0x2e000, v218
	buffer_load_dword v234, v218, s[76:79], 0 offen nt
	v_add_u32_e32 v218, 0x2e000, v218
	buffer_load_dword v235, v218, s[76:79], 0 offen nt
	v_add_u32_e32 v218, 0x2e000, v218
	buffer_load_dword v236, v218, s[76:79], 0 offen nt
	v_add_u32_e32 v218, 0x2e000, v218
	buffer_load_dword v237, v218, s[76:79], 0 offen nt
	v_add_u32_e32 v218, 0x2e000, v218
	buffer_load_dword v238, v218, s[76:79], 0 offen nt
	v_add_u32_e32 v218, 0x2e000, v218
	buffer_load_dword v239, v218, s[76:79], 0 offen nt
	v_add_u32_e32 v218, 0x2e000, v218
	buffer_load_dword v240, v218, s[76:79], 0 offen nt
	v_add_u32_e32 v218, 0x2e000, v218
	buffer_load_dword v241, v218, s[76:79], 0 offen nt
	v_add_u32_e32 v218, 0x2e000, v218
	buffer_load_dword v242, v218, s[76:79], 0 offen nt
	v_add_u32_e32 v218, 0x2e000, v218
	buffer_load_dword v243, v218, s[76:79], 0 offen nt
	v_add_u32_e32 v218, 0x2e000, v218
	buffer_load_dword v244, v218, s[76:79], 0 offen nt
	v_add_u32_e32 v218, 0x2e000, v218
	buffer_load_dword v245, v218, s[76:79], 0 offen nt
	v_add_u32_e32 v218, 0x2e000, v218
	buffer_load_dword v246, v218, s[76:79], 0 offen nt
	v_add_u32_e32 v218, 0x2e000, v218
	buffer_load_dword v247, v218, s[76:79], 0 offen nt
	v_add_u32_e32 v218, 0x2e000, v218
	buffer_load_dword v248, v218, s[76:79], 0 offen nt
	v_add_u32_e32 v218, 0x2e000, v218
	buffer_load_dword v249, v218, s[76:79], 0 offen nt
	v_add_u32_e32 v218, 0x2e000, v218
	s_waitcnt vmcnt(30)
	v_max_f32_e64 v250, |v219|, |v219|
	v_max_f32_e64 v218, |v217|, |v217|
	v_max_f32_e32 v218, v218, v250
	v_cvt_pk_bf16_f32 v217, v217, v219
	s_waitcnt vmcnt(29)
	v_max_f32_e64 v219, |v220|, |v220|
	s_waitcnt vmcnt(28)
	v_max_f32_e64 v250, |v221|, |v221|
	v_max_f32_e32 v219, v219, v250
	v_max3_f32 v35, v35, v218, v219
	v_cvt_pk_bf16_f32 v218, v220, v221
	v_add_u32_e32 v219, 0x1000, v43
	ds_write2_b32 v219, v217, v218 offset0:32 offset1:98
	s_waitcnt vmcnt(27)
	v_max_f32_e64 v217, |v222|, |v222|
	s_waitcnt vmcnt(26)
	v_max_f32_e64 v218, |v223|, |v223|
	s_waitcnt vmcnt(25)
	v_max_f32_e64 v220, |v224|, |v224|
	s_waitcnt vmcnt(24)
	v_max_f32_e64 v221, |v225|, |v225|
	v_max_f32_e32 v217, v217, v218
	v_max_f32_e32 v220, v220, v221
	v_cvt_pk_bf16_f32 v218, v222, v223
	v_max3_f32 v35, v35, v217, v220
	v_cvt_pk_bf16_f32 v217, v224, v225
	ds_write2_b32 v219, v218, v217 offset0:164 offset1:230
	s_waitcnt vmcnt(23)
	v_max_f32_e64 v217, |v226|, |v226|
	s_waitcnt vmcnt(22)
	v_max_f32_e64 v218, |v227|, |v227|
	s_waitcnt vmcnt(21)
	v_max_f32_e64 v219, |v228|, |v228|
	s_waitcnt vmcnt(20)
	v_max_f32_e64 v220, |v229|, |v229|
	v_max_f32_e32 v217, v217, v218
	v_max_f32_e32 v219, v219, v220
	v_cvt_pk_bf16_f32 v218, v226, v227
	v_max3_f32 v35, v35, v217, v219
	v_cvt_pk_bf16_f32 v217, v228, v229
	v_add_u32_e32 v219, 0x1400, v43
	ds_write2_b32 v219, v218, v217 offset0:40 offset1:106
	s_waitcnt vmcnt(19)
	v_max_f32_e64 v217, |v230|, |v230|
	s_waitcnt vmcnt(18)
	v_max_f32_e64 v218, |v231|, |v231|
	s_waitcnt vmcnt(17)
	v_max_f32_e64 v220, |v232|, |v232|
	s_waitcnt vmcnt(16)
	v_max_f32_e64 v221, |v233|, |v233|
	v_max_f32_e32 v217, v217, v218
	v_max_f32_e32 v220, v220, v221
	v_cvt_pk_bf16_f32 v218, v230, v231
	v_max3_f32 v35, v35, v217, v220
	v_cvt_pk_bf16_f32 v217, v232, v233
	ds_write2_b32 v219, v218, v217 offset0:172 offset1:238
	s_waitcnt vmcnt(15)
	v_max_f32_e64 v217, |v234|, |v234|
	s_waitcnt vmcnt(14)
	v_max_f32_e64 v218, |v235|, |v235|
	s_waitcnt vmcnt(13)
	v_max_f32_e64 v219, |v236|, |v236|
	s_waitcnt vmcnt(12)
	v_max_f32_e64 v220, |v237|, |v237|
	v_max_f32_e32 v217, v217, v218
	v_max_f32_e32 v219, v219, v220
	v_cvt_pk_bf16_f32 v218, v234, v235
	v_max3_f32 v35, v35, v217, v219
	v_cvt_pk_bf16_f32 v217, v236, v237
	v_add_u32_e32 v219, 0x1800, v43
	ds_write2_b32 v219, v218, v217 offset0:48 offset1:114
	s_waitcnt vmcnt(11)
	v_max_f32_e64 v217, |v238|, |v238|
	s_waitcnt vmcnt(10)
	v_max_f32_e64 v218, |v239|, |v239|
	s_waitcnt vmcnt(9)
	v_max_f32_e64 v220, |v240|, |v240|
	s_waitcnt vmcnt(8)
	v_max_f32_e64 v221, |v241|, |v241|
	v_max_f32_e32 v217, v217, v218
	v_max_f32_e32 v220, v220, v221
	v_cvt_pk_bf16_f32 v218, v238, v239
	v_max3_f32 v35, v35, v217, v220
	v_cvt_pk_bf16_f32 v217, v240, v241
	ds_write2_b32 v219, v218, v217 offset0:180 offset1:246
	s_waitcnt vmcnt(7)
	v_max_f32_e64 v217, |v242|, |v242|
	s_waitcnt vmcnt(6)
	v_max_f32_e64 v218, |v243|, |v243|
	s_waitcnt vmcnt(5)
	v_max_f32_e64 v219, |v244|, |v244|
	s_waitcnt vmcnt(4)
	v_max_f32_e64 v220, |v245|, |v245|
	v_max_f32_e32 v217, v217, v218
	v_max_f32_e32 v219, v219, v220
	v_cvt_pk_bf16_f32 v218, v242, v243
	v_max3_f32 v35, v35, v217, v219
	v_cvt_pk_bf16_f32 v217, v244, v245
	v_add_u32_e32 v219, 0x1c00, v43
	ds_write2_b32 v219, v218, v217 offset0:56 offset1:122
	s_waitcnt vmcnt(3)
	v_max_f32_e64 v217, |v246|, |v246|
	s_waitcnt vmcnt(2)
	v_max_f32_e64 v218, |v247|, |v247|
	s_waitcnt vmcnt(1)
	v_max_f32_e64 v220, |v248|, |v248|
	s_waitcnt vmcnt(0)
	v_max_f32_e64 v221, |v249|, |v249|
	v_max_f32_e32 v217, v217, v218
	v_max_f32_e32 v220, v220, v221
	v_cvt_pk_bf16_f32 v218, v246, v247
	v_max3_f32 v35, v35, v217, v220
	v_cvt_pk_bf16_f32 v217, v248, v249
	ds_write2_b32 v219, v218, v217 offset0:188 offset1:254
	v_add_u32_e32 v217, 0x14200000, v34
	v_add_u32_e32 v34, 0x1422e000, v34
	buffer_load_dword v217, v217, s[76:79], 0 offen nt
	buffer_load_dword v218, v34, s[76:79], 0 offen nt
	v_add_u32_e32 v34, 0x2e000, v34
	buffer_load_dword v219, v34, s[76:79], 0 offen nt
	v_add_u32_e32 v34, 0x2e000, v34
	buffer_load_dword v220, v34, s[76:79], 0 offen nt
	v_add_u32_e32 v34, 0x2e000, v34
	buffer_load_dword v221, v34, s[76:79], 0 offen nt
	v_add_u32_e32 v34, 0x2e000, v34
	buffer_load_dword v222, v34, s[76:79], 0 offen nt
	v_add_u32_e32 v34, 0x2e000, v34
	buffer_load_dword v223, v34, s[76:79], 0 offen nt
	v_add_u32_e32 v34, 0x2e000, v34
	buffer_load_dword v224, v34, s[76:79], 0 offen nt
	v_add_u32_e32 v34, 0x2e000, v34
	buffer_load_dword v225, v34, s[76:79], 0 offen nt
	v_add_u32_e32 v34, 0x2e000, v34
	buffer_load_dword v226, v34, s[76:79], 0 offen nt
	v_add_u32_e32 v34, 0x2e000, v34
	buffer_load_dword v227, v34, s[76:79], 0 offen nt
	v_add_u32_e32 v34, 0x2e000, v34
	buffer_load_dword v228, v34, s[76:79], 0 offen nt
	v_add_u32_e32 v34, 0x2e000, v34
	buffer_load_dword v229, v34, s[76:79], 0 offen nt
	v_add_u32_e32 v34, 0x2e000, v34
	buffer_load_dword v230, v34, s[76:79], 0 offen nt
	v_add_u32_e32 v34, 0x2e000, v34
	buffer_load_dword v231, v34, s[76:79], 0 offen nt
	v_add_u32_e32 v34, 0x2e000, v34
	buffer_load_dword v232, v34, s[76:79], 0 offen nt
	v_add_u32_e32 v34, 0x2e000, v34
	buffer_load_dword v233, v34, s[76:79], 0 offen nt
	v_add_u32_e32 v34, 0x2e000, v34
	buffer_load_dword v234, v34, s[76:79], 0 offen nt
	v_add_u32_e32 v34, 0x2e000, v34
	buffer_load_dword v235, v34, s[76:79], 0 offen nt
	v_add_u32_e32 v34, 0x2e000, v34
	buffer_load_dword v236, v34, s[76:79], 0 offen nt
	v_add_u32_e32 v34, 0x2e000, v34
	buffer_load_dword v237, v34, s[76:79], 0 offen nt
	v_add_u32_e32 v34, 0x2e000, v34
	buffer_load_dword v238, v34, s[76:79], 0 offen nt
	v_add_u32_e32 v34, 0x2e000, v34
	buffer_load_dword v239, v34, s[76:79], 0 offen nt
	v_add_u32_e32 v34, 0x2e000, v34
	buffer_load_dword v240, v34, s[76:79], 0 offen nt
	v_add_u32_e32 v34, 0x2e000, v34
	buffer_load_dword v241, v34, s[76:79], 0 offen nt
	v_add_u32_e32 v34, 0x2e000, v34
	buffer_load_dword v242, v34, s[76:79], 0 offen nt
	v_add_u32_e32 v34, 0x2e000, v34
	buffer_load_dword v243, v34, s[76:79], 0 offen nt
	v_add_u32_e32 v34, 0x2e000, v34
	buffer_load_dword v244, v34, s[76:79], 0 offen nt
	v_add_u32_e32 v34, 0x2e000, v34
	buffer_load_dword v245, v34, s[76:79], 0 offen nt
	v_add_u32_e32 v34, 0x2e000, v34
	buffer_load_dword v246, v34, s[76:79], 0 offen nt
	v_add_u32_e32 v34, 0x2e000, v34
	buffer_load_dword v247, v34, s[76:79], 0 offen nt
	v_add_u32_e32 v34, 0x2e000, v34
	buffer_load_dword v248, v34, s[76:79], 0 offen nt
	v_add_u32_e32 v34, 0x2e000, v34
	s_waitcnt vmcnt(30)
	v_max_f32_e64 v249, |v218|, |v218|
	v_max_f32_e64 v34, |v217|, |v217|
	v_max_f32_e32 v34, v34, v249
	v_cvt_pk_bf16_f32 v217, v217, v218
	s_waitcnt vmcnt(29)
	v_max_f32_e64 v218, |v219|, |v219|
	s_waitcnt vmcnt(28)
	v_max_f32_e64 v249, |v220|, |v220|
	v_max_f32_e32 v218, v218, v249
	v_max3_f32 v34, v35, v34, v218
	v_cvt_pk_bf16_f32 v35, v219, v220
	v_add_u32_e32 v218, 0x2000, v43
	ds_write2_b32 v218, v217, v35 offset0:64 offset1:130
	s_waitcnt vmcnt(27)
	v_max_f32_e64 v35, |v221|, |v221|
	s_waitcnt vmcnt(26)
	v_max_f32_e64 v217, |v222|, |v222|
	s_waitcnt vmcnt(25)
	v_max_f32_e64 v218, |v223|, |v223|
	s_waitcnt vmcnt(24)
	v_max_f32_e64 v219, |v224|, |v224|
	v_max_f32_e32 v35, v35, v217
	v_max_f32_e32 v218, v218, v219
	v_cvt_pk_bf16_f32 v217, v221, v222
	v_max3_f32 v34, v34, v35, v218
	v_cvt_pk_bf16_f32 v35, v223, v224
	v_add_u32_e32 v218, 0x2200, v43
	ds_write2_b32 v218, v217, v35 offset0:68 offset1:134
	s_waitcnt vmcnt(23)
	v_max_f32_e64 v35, |v225|, |v225|
	s_waitcnt vmcnt(22)
	v_max_f32_e64 v217, |v226|, |v226|
	s_waitcnt vmcnt(21)
	v_max_f32_e64 v218, |v227|, |v227|
	s_waitcnt vmcnt(20)
	v_max_f32_e64 v219, |v228|, |v228|
	v_max_f32_e32 v35, v35, v217
	v_max_f32_e32 v218, v218, v219
	v_cvt_pk_bf16_f32 v217, v225, v226
	v_max3_f32 v34, v34, v35, v218
	v_cvt_pk_bf16_f32 v35, v227, v228
	v_add_u32_e32 v218, 0x2400, v43
	ds_write2_b32 v218, v217, v35 offset0:72 offset1:138
	s_waitcnt vmcnt(19)
	v_max_f32_e64 v35, |v229|, |v229|
	s_waitcnt vmcnt(18)
	v_max_f32_e64 v217, |v230|, |v230|
	s_waitcnt vmcnt(17)
	v_max_f32_e64 v218, |v231|, |v231|
	s_waitcnt vmcnt(16)
	v_max_f32_e64 v219, |v232|, |v232|
	v_max_f32_e32 v35, v35, v217
	v_max_f32_e32 v218, v218, v219
	v_cvt_pk_bf16_f32 v217, v229, v230
	v_max3_f32 v34, v34, v35, v218
	v_cvt_pk_bf16_f32 v35, v231, v232
	v_add_u32_e32 v218, 0x2600, v43
	ds_write2_b32 v218, v217, v35 offset0:76 offset1:142
	s_waitcnt vmcnt(15)
	v_max_f32_e64 v35, |v233|, |v233|
	s_waitcnt vmcnt(14)
	v_max_f32_e64 v217, |v234|, |v234|
	s_waitcnt vmcnt(13)
	v_max_f32_e64 v218, |v235|, |v235|
	s_waitcnt vmcnt(12)
	v_max_f32_e64 v219, |v236|, |v236|
	v_max_f32_e32 v35, v35, v217
	v_max_f32_e32 v218, v218, v219
	v_cvt_pk_bf16_f32 v217, v233, v234
	v_max3_f32 v34, v34, v35, v218
	v_cvt_pk_bf16_f32 v35, v235, v236
	v_add_u32_e32 v218, 0x2800, v43
	ds_write2_b32 v218, v217, v35 offset0:80 offset1:146
	s_waitcnt vmcnt(11)
	v_max_f32_e64 v35, |v237|, |v237|
	s_waitcnt vmcnt(10)
	v_max_f32_e64 v217, |v238|, |v238|
	s_waitcnt vmcnt(9)
	v_max_f32_e64 v218, |v239|, |v239|
	s_waitcnt vmcnt(8)
	v_max_f32_e64 v219, |v240|, |v240|
	v_max_f32_e32 v35, v35, v217
	v_max_f32_e32 v218, v218, v219
	v_cvt_pk_bf16_f32 v217, v237, v238
	v_max3_f32 v34, v34, v35, v218
	v_cvt_pk_bf16_f32 v35, v239, v240
	v_add_u32_e32 v218, 0x2a00, v43
	ds_write2_b32 v218, v217, v35 offset0:84 offset1:150
	s_waitcnt vmcnt(7)
	v_max_f32_e64 v35, |v241|, |v241|
	s_waitcnt vmcnt(6)
	v_max_f32_e64 v217, |v242|, |v242|
	s_waitcnt vmcnt(5)
	v_max_f32_e64 v218, |v243|, |v243|
	s_waitcnt vmcnt(4)
	v_max_f32_e64 v219, |v244|, |v244|
	v_max_f32_e32 v35, v35, v217
	v_max_f32_e32 v218, v218, v219
	v_cvt_pk_bf16_f32 v217, v241, v242
	v_max3_f32 v34, v34, v35, v218
	v_cvt_pk_bf16_f32 v35, v243, v244
	v_add_u32_e32 v218, 0x2c00, v43
	ds_write2_b32 v218, v217, v35 offset0:88 offset1:154
	s_waitcnt vmcnt(3)
	v_max_f32_e64 v35, |v245|, |v245|
	s_waitcnt vmcnt(2)
	v_max_f32_e64 v217, |v246|, |v246|
	s_waitcnt vmcnt(1)
	v_max_f32_e64 v218, |v247|, |v247|
	s_waitcnt vmcnt(0)
	v_max_f32_e64 v219, |v248|, |v248|
	v_max_f32_e32 v35, v35, v217
	v_max_f32_e32 v218, v218, v219
	v_cvt_pk_bf16_f32 v217, v245, v246
	v_max3_f32 v34, v34, v35, v218
	v_cvt_pk_bf16_f32 v35, v247, v248
	v_add_u32_e32 v218, 0x2e00, v43
	ds_write2_b32 v218, v217, v35 offset0:92 offset1:158
	v_cndmask_b32_e32 v35, v53, v54, vcc
	v_lshlrev_b32_e32 v35, 2, v35
	ds_bpermute_b32 v35, v35, v34
	s_and_saveexec_b64 s[28:29], s[2:3]
	s_cbranch_execz .LBB0_81
	s_add_i32 s12, s4, s34
	s_waitcnt lgkmcnt(0)
	v_max_f32_e32 v35, v35, v35
	v_max_f32_e32 v34, v34, v34
	v_lshl_add_u32 v217, v182, 2, s12
	v_max_f32_e32 v34, v34, v35
	ds_write_b32 v217, v34

.LBB0_93:
	s_cmp_gt_i32 s7, -1
	s_mov_b64 s[2:3], -1
	s_cbranch_scc0 .LBB0_95
	s_lshr_b32 s0, s7, 1
	s_and_b32 s4, s0, 0x3fffffc0
	v_or_b32_e32 v2, s4, v38
	s_and_b32 s0, s11, 0xfe0
	v_lshlrev_b32_e32 v2, 12, v2
	v_or3_b32 v2, v2, s0, v39
	v_lshlrev_b32_e32 v2, 2, v2
	s_mov_b32 s0, s56
	s_mov_b32 s2, s14
	s_mov_b32 s3, s15
	buffer_load_dword v22, v2, s[0:3], 0 offen nt
	v_or_b32_e32 v2, 0x8000, v2
	buffer_load_dword v23, v2, s[0:3], 0 offen nt
	v_add_u32_e32 v2, 0x8000, v2
	buffer_load_dword v24, v2, s[0:3], 0 offen nt
	v_add_u32_e32 v2, 0x8000, v2
	buffer_load_dword v25, v2, s[0:3], 0 offen nt
	v_add_u32_e32 v2, 0x8000, v2
	buffer_load_dword v26, v2, s[0:3], 0 offen nt
	v_add_u32_e32 v2, 0x8000, v2
	buffer_load_dword v27, v2, s[0:3], 0 offen nt
	v_add_u32_e32 v2, 0x8000, v2
	buffer_load_dword v28, v2, s[0:3], 0 offen nt
	v_add_u32_e32 v2, 0x8000, v2
	buffer_load_dword v29, v2, s[0:3], 0 offen nt
	v_add_u32_e32 v2, 0x8000, v2
	buffer_load_dword v36, v2, s[0:3], 0 offen nt
	v_add_u32_e32 v2, 0x8000, v2
	buffer_load_dword v37, v2, s[0:3], 0 offen nt
	v_add_u32_e32 v2, 0x8000, v2
	buffer_load_dword v40, v2, s[0:3], 0 offen nt
	v_add_u32_e32 v2, 0x8000, v2
	buffer_load_dword v41, v2, s[0:3], 0 offen nt
	v_add_u32_e32 v2, 0x8000, v2
	buffer_load_dword v42, v2, s[0:3], 0 offen nt
	v_add_u32_e32 v2, 0x8000, v2
	buffer_load_dword v43, v2, s[0:3], 0 offen nt
	v_add_u32_e32 v2, 0x8000, v2
	buffer_load_dword v44, v2, s[0:3], 0 offen nt
	v_add_u32_e32 v2, 0x8000, v2
	buffer_load_dword v45, v2, s[0:3], 0 offen nt
	v_add_u32_e32 v2, 0x8000, v2
	buffer_load_dword v46, v2, s[0:3], 0 offen nt
	v_add_u32_e32 v2, 0x8000, v2
	buffer_load_dword v47, v2, s[0:3], 0 offen nt
	v_add_u32_e32 v2, 0x8000, v2
	buffer_load_dword v48, v2, s[0:3], 0 offen nt
	v_add_u32_e32 v2, 0x8000, v2
	buffer_load_dword v49, v2, s[0:3], 0 offen nt
	v_add_u32_e32 v2, 0x8000, v2
	buffer_load_dword v50, v2, s[0:3], 0 offen nt
	v_add_u32_e32 v2, 0x8000, v2
	buffer_load_dword v51, v2, s[0:3], 0 offen nt
	v_add_u32_e32 v2, 0x8000, v2
	buffer_load_dword v52, v2, s[0:3], 0 offen nt
	v_add_u32_e32 v2, 0x8000, v2
	buffer_load_dword v53, v2, s[0:3], 0 offen nt
	v_add_u32_e32 v2, 0x8000, v2
	buffer_load_dword v54, v2, s[0:3], 0 offen nt
	v_add_u32_e32 v2, 0x8000, v2
	buffer_load_dword v55, v2, s[0:3], 0 offen nt
	v_add_u32_e32 v2, 0x8000, v2
	buffer_load_dword v56, v2, s[0:3], 0 offen nt
	v_add_u32_e32 v2, 0x8000, v2
	buffer_load_dword v57, v2, s[0:3], 0 offen nt
	v_add_u32_e32 v2, 0x8000, v2
	buffer_load_dword v58, v2, s[0:3], 0 offen nt
	v_add_u32_e32 v2, 0x8000, v2
	buffer_load_dword v59, v2, s[0:3], 0 offen nt
	v_add_u32_e32 v2, 0x8000, v2
	buffer_load_dword v60, v2, s[0:3], 0 offen nt
	v_add_u32_e32 v61, 0x8000, v2
	buffer_load_dword v62, v61, s[0:3], 0 offen nt
	v_add_u32_e32 v2, s11, v1
	v_and_or_b32 v2, v2, s20, v8
	s_lshl_b32 s4, s4, 1
	v_lshlrev_b32_e32 v2, 15, v2
	v_lshl_add_u64 v[30:31], v[4:5], 0, s[4:5]
	v_lshl_add_u64 v[32:33], v[30:31], 0, v[2:3]
	v_add_u32_e32 v2, 0x8000, v61
	v_add_co_u32_e32 v34, vcc, s21, v32
	v_and_or_b32 v2, v13, s23, v11
	s_nop 0
	v_addc_co_u32_e32 v35, vcc, 0, v33, vcc
	s_mov_b64 s[2:3], 0
	s_waitcnt vmcnt(30)
	ds_write2_b32 v14, v22, v23 offset1:66
	s_waitcnt vmcnt(28)
	ds_write2_b32 v14, v24, v25 offset0:132 offset1:198
	s_waitcnt vmcnt(26)
	ds_write2_b32 v15, v26, v27 offset0:8 offset1:74
	s_waitcnt vmcnt(24)
	ds_write2_b32 v15, v28, v29 offset0:140 offset1:206
	s_waitcnt vmcnt(22)
	ds_write2_b32 v16, v36, v37 offset0:16 offset1:82
	s_waitcnt vmcnt(20)
	ds_write2_b32 v16, v40, v41 offset0:148 offset1:214
	s_waitcnt vmcnt(18)
	ds_write2_b32 v17, v42, v43 offset0:24 offset1:90
	s_waitcnt vmcnt(16)
	ds_write2_b32 v17, v44, v45 offset0:156 offset1:222
	s_waitcnt vmcnt(14)
	ds_write2_b32 v18, v46, v47 offset0:32 offset1:98
	s_waitcnt vmcnt(12)
	ds_write2_b32 v18, v48, v49 offset0:164 offset1:230
	s_waitcnt vmcnt(10)
	ds_write2_b32 v19, v50, v51 offset0:40 offset1:106
	s_waitcnt vmcnt(8)
	ds_write2_b32 v19, v52, v53 offset0:172 offset1:238
	s_waitcnt vmcnt(6)
	ds_write2_b32 v20, v54, v55 offset0:48 offset1:114
	s_waitcnt vmcnt(4)
	ds_write2_b32 v20, v56, v57 offset0:180 offset1:246
	s_waitcnt vmcnt(2)
	ds_write2_b32 v21, v58, v59 offset0:56 offset1:122
	s_waitcnt vmcnt(0)
	ds_write2_b32 v21, v60, v62 offset0:188 offset1:254
	s_waitcnt lgkmcnt(0)
	ds_read2_b32 v[26:27], v10 offset0:33 offset1:41
	ds_read2_b32 v[28:29], v10 offset1:8
	ds_read2_b32 v[36:37], v10 offset0:66 offset1:74
	ds_read2_b32 v[40:41], v10 offset0:99 offset1:107
	ds_read2_b32 v[42:43], v10 offset0:132 offset1:140
	ds_read2_b32 v[44:45], v10 offset0:165 offset1:173
	ds_read2_b32 v[46:47], v10 offset0:198 offset1:206
	ds_read2_b32 v[48:49], v10 offset0:231 offset1:239
	ds_read2_b32 v[50:51], v10 offset0:49 offset1:57
	ds_read2_b32 v[52:53], v10 offset0:16 offset1:24
	ds_read2_b32 v[54:55], v10 offset0:82 offset1:90
	ds_read2_b32 v[56:57], v10 offset0:115 offset1:123
	ds_read2_b32 v[58:59], v10 offset0:148 offset1:156
	ds_read2_b32 v[60:61], v10 offset0:181 offset1:189
	ds_read2_b32 v[62:63], v10 offset0:214 offset1:222
	s_waitcnt lgkmcnt(13)
	v_cvt_pk_bf16_f32 v22, v28, v26
	s_waitcnt lgkmcnt(11)
	v_cvt_pk_bf16_f32 v23, v36, v40
	v_cvt_pk_bf16_f32 v26, v29, v27
	v_cvt_pk_bf16_f32 v27, v37, v41
	ds_read2_b32 v[36:37], v10 offset0:247 offset1:255
	s_waitcnt lgkmcnt(10)
	v_cvt_pk_bf16_f32 v28, v43, v45
	s_waitcnt lgkmcnt(8)
	v_cvt_pk_bf16_f32 v29, v47, v49
	v_cvt_pk_bf16_f32 v24, v42, v44
	v_cvt_pk_bf16_f32 v25, v46, v48
	global_store_dwordx4 v[34:35], v[26:29], off
	global_store_dwordx4 v[32:33], v[22:25], off
	s_nop 0
	v_add_co_u32_e32 v26, vcc, s22, v32
	s_waitcnt lgkmcnt(6)
	v_cvt_pk_bf16_f32 v22, v52, v50
	s_waitcnt lgkmcnt(4)
	v_cvt_pk_bf16_f32 v23, v54, v56
	s_waitcnt lgkmcnt(2)
	v_cvt_pk_bf16_f32 v24, v58, v60
	s_waitcnt lgkmcnt(0)
	v_cvt_pk_bf16_f32 v25, v62, v36
	v_addc_co_u32_e32 v27, vcc, 0, v33, vcc
	global_store_dwordx4 v[26:27], v[22:25], off
	v_lshl_add_u64 v[26:27], v[30:31], 0, v[2:3]
	s_nop 0
	v_cvt_pk_bf16_f32 v22, v53, v51
	v_cvt_pk_bf16_f32 v23, v55, v57
	v_cvt_pk_bf16_f32 v24, v59, v61
	v_cvt_pk_bf16_f32 v25, v63, v37
	global_store_dwordx4 v[26:27], v[22:25], off
	s_waitcnt lgkmcnt(0)
.LBB0_95:
	s_andn2_b64 vcc, exec, s[2:3]
	s_cbranch_vccnz .LBB0_92
	s_lshr_b32 s0, s17, 3
	s_and_b32 s2, s18, 0x3fe0
	s_and_b32 s0, s0, 0x1fffffc0
	s_sub_i32 s3, 0x4000, s2
	v_sub_u32_sdwa v2, v38, s0 dst_sel:WORD_1 dst_unused:UNUSED_PAD src0_sel:DWORD src1_sel:DWORD
	v_or_b32_e32 v22, s3, v39
	v_lshl_add_u32 v2, v22, 2, v2
	s_mov_b32 s12, s54
	buffer_load_dword v22, v2, s[12:15], 0 offen nt
	v_add_u32_e32 v2, 0x20000, v2
	buffer_load_dword v23, v2, s[12:15], 0 offen nt
	v_add_u32_e32 v2, 0x20000, v2
	buffer_load_dword v24, v2, s[12:15], 0 offen nt
	v_add_u32_e32 v2, 0x20000, v2
	buffer_load_dword v25, v2, s[12:15], 0 offen nt
	v_add_u32_e32 v2, 0x20000, v2
	buffer_load_dword v26, v2, s[12:15], 0 offen nt
	v_add_u32_e32 v2, 0x20000, v2
	buffer_load_dword v27, v2, s[12:15], 0 offen nt
	v_add_u32_e32 v2, 0x20000, v2
	buffer_load_dword v28, v2, s[12:15], 0 offen nt
	v_add_u32_e32 v2, 0x20000, v2
	buffer_load_dword v29, v2, s[12:15], 0 offen nt
	v_add_u32_e32 v2, 0x20000, v2
	buffer_load_dword v36, v2, s[12:15], 0 offen nt
	v_add_u32_e32 v2, 0x20000, v2
	buffer_load_dword v37, v2, s[12:15], 0 offen nt
	v_add_u32_e32 v2, 0x20000, v2
	buffer_load_dword v40, v2, s[12:15], 0 offen nt
	v_add_u32_e32 v2, 0x20000, v2
	buffer_load_dword v41, v2, s[12:15], 0 offen nt
	v_add_u32_e32 v2, 0x20000, v2
	buffer_load_dword v42, v2, s[12:15], 0 offen nt
	v_add_u32_e32 v2, 0x20000, v2
	buffer_load_dword v43, v2, s[12:15], 0 offen nt
	v_add_u32_e32 v2, 0x20000, v2
	buffer_load_dword v44, v2, s[12:15], 0 offen nt
	v_add_u32_e32 v2, 0x20000, v2
	buffer_load_dword v45, v2, s[12:15], 0 offen nt
	v_add_u32_e32 v2, 0x20000, v2
	buffer_load_dword v46, v2, s[12:15], 0 offen nt
	v_add_u32_e32 v2, 0x20000, v2
	buffer_load_dword v47, v2, s[12:15], 0 offen nt
	v_add_u32_e32 v2, 0x20000, v2
	buffer_load_dword v48, v2, s[12:15], 0 offen nt
	v_add_u32_e32 v2, 0x20000, v2
	buffer_load_dword v49, v2, s[12:15], 0 offen nt
	v_add_u32_e32 v2, 0x20000, v2
	buffer_load_dword v50, v2, s[12:15], 0 offen nt
	v_add_u32_e32 v2, 0x20000, v2
	buffer_load_dword v51, v2, s[12:15], 0 offen nt
	v_add_u32_e32 v2, 0x20000, v2
	buffer_load_dword v52, v2, s[12:15], 0 offen nt
	v_add_u32_e32 v2, 0x20000, v2
	buffer_load_dword v53, v2, s[12:15], 0 offen nt
	v_add_u32_e32 v2, 0x20000, v2
	buffer_load_dword v54, v2, s[12:15], 0 offen nt
	v_add_u32_e32 v2, 0x20000, v2
	buffer_load_dword v55, v2, s[12:15], 0 offen nt
	v_add_u32_e32 v2, 0x20000, v2
	buffer_load_dword v56, v2, s[12:15], 0 offen nt
	v_add_u32_e32 v2, 0x20000, v2
	buffer_load_dword v57, v2, s[12:15], 0 offen nt
	v_add_u32_e32 v2, 0x20000, v2
	buffer_load_dword v58, v2, s[12:15], 0 offen nt
	v_add_u32_e32 v2, 0x20000, v2
	buffer_load_dword v59, v2, s[12:15], 0 offen nt
	v_add_u32_e32 v2, 0x20000, v2
	buffer_load_dword v60, v2, s[12:15], 0 offen nt
	v_add_u32_e32 v61, 0x20000, v2
	buffer_load_dword v62, v61, s[12:15], 0 offen nt
	s_sub_i32 s2, 0, s0
	v_or_b32_e32 v2, s3, v9
	v_or_b32_e32 v30, s3, v12
	s_ashr_i32 s3, s2, 31
	v_lshlrev_b32_e32 v2, 13, v2
	v_lshlrev_b32_e32 v64, 13, v30
	v_lshl_add_u64 v[30:31], s[2:3], 1, v[6:7]
	v_lshl_add_u64 v[32:33], v[30:31], 0, v[2:3]
	v_or_b32_e32 v2, 0x8000, v64
	v_lshl_add_u64 v[34:35], v[30:31], 0, v[2:3]
	v_add_u32_e32 v2, 0x20000, v61
	s_waitcnt vmcnt(30)
	ds_write2_b32 v14, v22, v23 offset1:66
	s_waitcnt vmcnt(28)
	ds_write2_b32 v14, v24, v25 offset0:132 offset1:198
	s_waitcnt vmcnt(26)
	ds_write2_b32 v15, v26, v27 offset0:8 offset1:74
	s_waitcnt vmcnt(24)
	ds_write2_b32 v15, v28, v29 offset0:140 offset1:206
	s_waitcnt vmcnt(22)
	ds_write2_b32 v16, v36, v37 offset0:16 offset1:82
	s_waitcnt vmcnt(20)
	ds_write2_b32 v16, v40, v41 offset0:148 offset1:214
	s_waitcnt vmcnt(18)
	ds_write2_b32 v17, v42, v43 offset0:24 offset1:90
	s_waitcnt vmcnt(16)
	ds_write2_b32 v17, v44, v45 offset0:156 offset1:222
	s_waitcnt vmcnt(14)
	ds_write2_b32 v18, v46, v47 offset0:32 offset1:98
	s_waitcnt vmcnt(12)
	ds_write2_b32 v18, v48, v49 offset0:164 offset1:230
	s_waitcnt vmcnt(10)
	ds_write2_b32 v19, v50, v51 offset0:40 offset1:106
	s_waitcnt vmcnt(8)
	ds_write2_b32 v19, v52, v53 offset0:172 offset1:238
	s_waitcnt vmcnt(6)
	ds_write2_b32 v20, v54, v55 offset0:48 offset1:114
	s_waitcnt vmcnt(4)
	ds_write2_b32 v20, v56, v57 offset0:180 offset1:246
	s_waitcnt vmcnt(2)
	ds_write2_b32 v21, v58, v59 offset0:56 offset1:122
	s_waitcnt vmcnt(0)
	ds_write2_b32 v21, v60, v62 offset0:188 offset1:254
	s_waitcnt lgkmcnt(0)
	ds_read2_b32 v[26:27], v10 offset0:33 offset1:41
	ds_read2_b32 v[28:29], v10 offset1:8
	ds_read2_b32 v[36:37], v10 offset0:66 offset1:74
	ds_read2_b32 v[40:41], v10 offset0:99 offset1:107
	ds_read2_b32 v[42:43], v10 offset0:132 offset1:140
	ds_read2_b32 v[44:45], v10 offset0:165 offset1:173
	ds_read2_b32 v[46:47], v10 offset0:198 offset1:206
	ds_read2_b32 v[48:49], v10 offset0:231 offset1:239
	ds_read2_b32 v[50:51], v10 offset0:16 offset1:24
	ds_read2_b32 v[52:53], v10 offset0:49 offset1:57
	ds_read2_b32 v[54:55], v10 offset0:82 offset1:90
	ds_read2_b32 v[56:57], v10 offset0:115 offset1:123
	ds_read2_b32 v[58:59], v10 offset0:148 offset1:156
	ds_read2_b32 v[60:61], v10 offset0:181 offset1:189
	ds_read2_b32 v[62:63], v10 offset0:214 offset1:222
	s_waitcnt lgkmcnt(13)
	v_cvt_pk_bf16_f32 v22, v28, v26
	s_waitcnt lgkmcnt(11)
	v_cvt_pk_bf16_f32 v23, v36, v40
	v_cvt_pk_bf16_f32 v26, v29, v27
	v_cvt_pk_bf16_f32 v27, v37, v41
	ds_read2_b32 v[36:37], v10 offset0:247 offset1:255
	s_waitcnt lgkmcnt(10)
	v_cvt_pk_bf16_f32 v24, v42, v44
	s_waitcnt lgkmcnt(8)
	v_cvt_pk_bf16_f32 v25, v46, v48
	v_cvt_pk_bf16_f32 v28, v43, v45
	v_cvt_pk_bf16_f32 v29, v47, v49
	global_store_dwordx4 v[32:33], v[22:25], off
	global_store_dwordx4 v[34:35], v[26:29], off
	v_or_b32_e32 v2, 0x18000, v64
	s_waitcnt lgkmcnt(6)
	v_cvt_pk_bf16_f32 v22, v50, v52
	v_add_co_u32_e32 v26, vcc, s28, v32
	s_waitcnt lgkmcnt(4)
	v_cvt_pk_bf16_f32 v23, v54, v56
	s_waitcnt lgkmcnt(2)
	v_cvt_pk_bf16_f32 v24, v58, v60
	s_waitcnt lgkmcnt(0)
	v_cvt_pk_bf16_f32 v25, v62, v36
	v_addc_co_u32_e32 v27, vcc, 0, v33, vcc
	global_store_dwordx4 v[26:27], v[22:25], off
	v_lshl_add_u64 v[26:27], v[30:31], 0, v[2:3]
	s_nop 0
	v_cvt_pk_bf16_f32 v22, v51, v53
	v_cvt_pk_bf16_f32 v23, v55, v57
	v_cvt_pk_bf16_f32 v24, v59, v61
	v_cvt_pk_bf16_f32 v25, v63, v37
	global_store_dwordx4 v[26:27], v[22:25], off
	s_waitcnt lgkmcnt(0)
	s_branch .LBB0_92
